# attn lazy rescale; branch-free gelu erf in E1 epilogue; gemm_tile K-loop LDS read prefetch
# speedup vs baseline: 1.0671x; 1.0351x over previous
; DI void attn_item(const u16* __restrict__ qbuf, const u16* __restrict__ knope, const u16* __restrict__ krope, ...
;     ...
;   __syncthreads();
;   ATT_DMA(0u)
;   for (int kt = 0; kt < ntiles; ++kt) {
;     asm volatile("s_waitcnt vmcnt(0)" ::: "memory");
;     __syncthreads();
;     if (kt + 1 < ntiles) ATT_DMA((unsigned)((kt + 1) & 1) * 40960u)
;     if (active && kt < my_tiles) {
;       const char* cur = smem + (kt & 1) * 40960;
;       f32x16 st[2];
; #pragma unroll
;       for (int mt = 0; mt < 2; ++mt) {
; #pragma unroll
;         for (int j = 0; j < 16; ++j) st[mt][j] = 0.f;
; #pragma unroll
;         for (int ks = 0; ks < 12; ++ks) {
;           const bf16x8 kf = *(const bf16x8*)(cur + koff[ks & 3] + (ks >> 2) * 8192 + mt * 4096);
;           st[mt] = __builtin_amdgcn_mfma_f32_32x32x16_bf16(kf, qf[ks], st[mt], 0, 0, 0);
;         }
;       }
;       if (kt * 64 + 64 > nkeys) {
; #pragma unroll
;         for (int mt = 0; mt < 2; ++mt)
; #pragma unroll
;           for (int j = 0; j < 16; ++j) {
;             const int key = kt * 64 + mt * 32 + (j & 3) + 8 * (j >> 2) + 4 * h2;
;             if (key >= nkeys) st[mt][j] = -INFINITY;
;           }
;       }
;       float mx = fmaxf(st[0][0], st[1][0]);
; #pragma unroll
;       for (int j = 1; j < 16; ++j) mx = fmaxf(mx, fmaxf(st[0][j], st[1][j]));
;       mx = fmaxf(mx, __shfl_xor(mx, 32, 64));
;       const float m_new = fmaxf(m_run, mx);
;       const float alpha = __builtin_amdgcn_exp2f(m_run - m_new);
;       m_run = m_new;
;       float ps = 0.f;
; #pragma unroll
;       for (int mt = 0; mt < 2; ++mt)
; #pragma unroll
;         for (int j = 0; j < 16; ++j) { const float pv = __builtin_amdgcn_exp2f(st[mt][j] - m_new); st[mt][j] = pv; ps += pv; }
;       l_run = l_run * alpha + ps;
;       if (__any(alpha != 1.f)) {
.LBB0_46:
	s_add_i32 s10, s11, 1
	s_bitcmp1_b32 s10, 0
	v_add_u32_e32 v66, v152, v154
	s_cselect_b32 s12, 0xa000, 0
	v_add_u32_e32 v182, 0x1010000, v66
	v_add_u32_e32 v67, v153, v154
	s_waitcnt vmcnt(0)
	s_barrier
	s_add_i32 s13, s12, s7
	v_lshl_add_u64 v[64:65], v[182:183], 1, s[92:93]
	s_mov_b32 s14, m0
	s_mov_b32 m0, s13
	s_nop 0
	global_load_lds_dwordx4 v[64:65], off
	s_mov_b32 m0, s14
	v_add_u32_e32 v182, 0x1012000, v67
	v_lshl_add_u64 v[64:65], v[182:183], 1, s[92:93]
	s_add_i32 s14, s13, 0x400
	s_mov_b32 s15, m0
	s_mov_b32 m0, s14
	s_nop 0
	global_load_lds_dwordx4 v[64:65], off
	s_mov_b32 m0, s15
	v_add_u32_e32 v182, 0x1014000, v66
	v_lshl_add_u64 v[64:65], v[182:183], 1, s[92:93]
	s_add_i32 s14, s13, 0x800
	s_mov_b32 s15, m0
	s_mov_b32 m0, s14
	s_nop 0
	global_load_lds_dwordx4 v[64:65], off
	s_mov_b32 m0, s15
	v_add_u32_e32 v182, 0x1016000, v67
	s_mov_b32 s2, 0x101000
	v_lshl_add_u64 v[64:65], v[182:183], 1, s[92:93]
	s_addk_i32 s13, 0xc00
	s_mov_b32 s14, m0
	s_mov_b32 m0, s13
	s_nop 0
	global_load_lds_dwordx4 v[64:65], off
	s_mov_b32 m0, s14
	v_add3_u32 v182, v152, v155, s2
	s_mov_b32 s2, 0x101200
	s_add_i32 s13, s12, s8
	v_lshl_add_u64 v[64:65], v[182:183], 1, s[30:31]
	s_mov_b32 s14, m0
	s_mov_b32 m0, s13
	s_nop 0
	global_load_lds_dwordx4 v[64:65], off
	s_mov_b32 m0, s14
	v_add3_u32 v182, v153, v155, s2
	v_add_u32_e32 v66, v152, v156
	v_lshl_add_u64 v[64:65], v[182:183], 1, s[30:31]
	s_addk_i32 s13, 0x400
	s_mov_b32 s14, m0
	s_mov_b32 m0, s13
	s_nop 0
	global_load_lds_dwordx4 v[64:65], off
	s_mov_b32 m0, s14
	v_add_u32_e32 v182, 64, v66
	v_add_u32_e32 v67, v153, v156
	s_add_i32 s12, s12, s9
	v_lshl_add_u64 v[64:65], v[182:183], 1, s[40:41]
	s_mov_b32 s13, m0
	s_mov_b32 m0, s12
	s_nop 0
	global_load_lds_dwordx4 v[64:65], off
	s_mov_b32 m0, s13
	v_add_u32_e32 v182, 0x2440, v67
	v_lshl_add_u64 v[64:65], v[182:183], 1, s[40:41]
	s_add_i32 s13, s12, 0x400
	s_mov_b32 s14, m0
	s_mov_b32 m0, s13
	s_nop 0
	global_load_lds_dwordx4 v[64:65], off
	s_mov_b32 m0, s14
	v_add_u32_e32 v182, 0x4840, v66
	v_lshl_add_u64 v[64:65], v[182:183], 1, s[40:41]
	s_add_i32 s13, s12, 0x800
	s_mov_b32 s14, m0
	s_mov_b32 m0, s13
	s_nop 0
	global_load_lds_dwordx4 v[64:65], off
	s_mov_b32 m0, s14
	v_add_u32_e32 v182, 0x6c40, v67
	v_lshl_add_u64 v[64:65], v[182:183], 1, s[40:41]
	s_addk_i32 s12, 0xc00
	s_mov_b32 s13, m0
	s_mov_b32 m0, s12
	s_nop 0
	global_load_lds_dwordx4 v[64:65], off
	s_mov_b32 m0, s13
	s_and_saveexec_b64 s[42:43], s[38:39]
	s_cbranch_execz .LBB0_50
	s_bitcmp1_b32 s11, 0
	s_cselect_b32 s11, 0xa000, 0
	v_or_b32_e32 v157, s11, v150
	v_or_b32_e32 v162, s11, v149
	v_or_b32_e32 v163, s11, v148
	v_or_b32_e32 v164, s11, v145
	ds_read_b128 v[224:227], v157
	ds_read_b128 v[228:231], v162
	ds_read_b128 v[232:235], v163
	ds_read_b128 v[236:239], v164
	ds_read_b128 v[240:243], v157 offset:8192
	ds_read_b128 v[244:247], v162 offset:8192
	ds_read_b128 v[248:251], v163 offset:8192
	ds_read_b128 v[186:189], v164 offset:8192
	s_waitcnt lgkmcnt(7)
	v_mfma_f32_32x32x16_bf16 v[64:79], v[224:227], v[140:143], 0
	ds_read_b128 v[224:227], v157 offset:16384
	s_waitcnt lgkmcnt(7)
	v_mfma_f32_32x32x16_bf16 v[64:79], v[228:231], v[136:139], v[64:79]
	ds_read_b128 v[228:231], v162 offset:16384
	s_waitcnt lgkmcnt(7)
	v_mfma_f32_32x32x16_bf16 v[64:79], v[232:235], v[132:135], v[64:79]
	ds_read_b128 v[232:235], v163 offset:16384
	s_waitcnt lgkmcnt(7)
	v_mfma_f32_32x32x16_bf16 v[64:79], v[236:239], v[128:131], v[64:79]
	ds_read_b128 v[236:239], v164 offset:16384
	s_waitcnt lgkmcnt(7)
	v_mfma_f32_32x32x16_bf16 v[64:79], v[240:243], v[124:127], v[64:79]
	ds_read_b128 v[240:243], v157 offset:4096
	s_waitcnt lgkmcnt(7)
	v_mfma_f32_32x32x16_bf16 v[64:79], v[244:247], v[120:123], v[64:79]
	ds_read_b128 v[244:247], v162 offset:4096
	s_waitcnt lgkmcnt(7)
	v_mfma_f32_32x32x16_bf16 v[64:79], v[248:251], v[116:119], v[64:79]
	ds_read_b128 v[248:251], v163 offset:4096
	s_waitcnt lgkmcnt(7)
	v_mfma_f32_32x32x16_bf16 v[64:79], v[186:189], v[112:115], v[64:79]
	ds_read_b128 v[186:189], v164 offset:4096
	s_waitcnt lgkmcnt(7)
	v_mfma_f32_32x32x16_bf16 v[64:79], v[224:227], v[108:111], v[64:79]
	ds_read_b128 v[224:227], v157 offset:12288
	s_waitcnt lgkmcnt(7)
	v_mfma_f32_32x32x16_bf16 v[64:79], v[228:231], v[104:107], v[64:79]
	ds_read_b128 v[228:231], v162 offset:12288
	s_waitcnt lgkmcnt(7)
	v_mfma_f32_32x32x16_bf16 v[64:79], v[232:235], v[100:103], v[64:79]
	ds_read_b128 v[232:235], v163 offset:12288
	s_waitcnt lgkmcnt(7)
	v_mfma_f32_32x32x16_bf16 v[64:79], v[236:239], v[96:99], v[64:79]
	ds_read_b128 v[236:239], v164 offset:12288
	s_waitcnt lgkmcnt(7)
	v_mfma_f32_32x32x16_bf16 v[80:95], v[240:243], v[140:143], 0
	ds_read_b128 v[240:243], v157 offset:20480
	s_waitcnt lgkmcnt(7)
	v_mfma_f32_32x32x16_bf16 v[80:95], v[244:247], v[136:139], v[80:95]
	ds_read_b128 v[244:247], v162 offset:20480
	s_waitcnt lgkmcnt(7)
	v_mfma_f32_32x32x16_bf16 v[80:95], v[248:251], v[132:135], v[80:95]
	ds_read_b128 v[248:251], v163 offset:20480
	s_waitcnt lgkmcnt(7)
	v_mfma_f32_32x32x16_bf16 v[80:95], v[186:189], v[128:131], v[80:95]
	ds_read_b128 v[186:189], v164 offset:20480
	s_waitcnt lgkmcnt(7)
	v_mfma_f32_32x32x16_bf16 v[80:95], v[224:227], v[124:127], v[80:95]
	ds_read_b128 v[224:227], v157 offset:24576
	s_waitcnt lgkmcnt(7)
	v_mfma_f32_32x32x16_bf16 v[80:95], v[228:231], v[120:123], v[80:95]
	ds_read_b128 v[228:231], v157 offset:28672
	s_waitcnt lgkmcnt(7)
	v_mfma_f32_32x32x16_bf16 v[80:95], v[232:235], v[116:119], v[80:95]
	ds_read_b128 v[232:235], v157 offset:32768
	s_waitcnt lgkmcnt(7)
	v_mfma_f32_32x32x16_bf16 v[80:95], v[236:239], v[112:115], v[80:95]
	ds_read_b128 v[236:239], v157 offset:36864
	s_waitcnt lgkmcnt(7)
	v_mfma_f32_32x32x16_bf16 v[80:95], v[240:243], v[108:111], v[80:95]
	ds_read_b128 v[240:243], v162 offset:24576
	s_waitcnt lgkmcnt(7)
	v_mfma_f32_32x32x16_bf16 v[80:95], v[244:247], v[104:107], v[80:95]
	ds_read_b128 v[244:247], v162 offset:28672
	s_waitcnt lgkmcnt(7)
	v_mfma_f32_32x32x16_bf16 v[80:95], v[248:251], v[100:103], v[80:95]
	ds_read_b128 v[248:251], v162 offset:32768
	s_waitcnt lgkmcnt(7)
	v_mfma_f32_32x32x16_bf16 v[80:95], v[186:189], v[96:99], v[80:95]
	ds_read_b128 v[186:189], v162 offset:36864
	s_nop 1
	v_max3_f32 v158, v64, v65, v66
	v_max3_f32 v159, v67, v68, v69
	v_max3_f32 v158, v158, v70, v71
	v_max3_f32 v159, v159, v72, v73
	v_max3_f32 v158, v158, v74, v75
	v_max3_f32 v159, v159, v76, v77
	v_max3_f32 v158, v158, v78, v79
	v_max_f32_e32 v158, v158, v159
	s_nop 1
	v_max3_f32 v159, v80, v81, v82
	v_max3_f32 v160, v83, v84, v85
	v_max3_f32 v159, v159, v86, v87
	v_max3_f32 v160, v160, v88, v89
	v_max3_f32 v159, v159, v90, v91
	v_max3_f32 v160, v160, v92, v93
	v_max3_f32 v159, v159, v94, v95
	v_max3_f32 v158, v158, v159, v160
	v_mov_b32_e32 v159, v158
	s_nop 1
	v_permlane32_swap_b32_e32 v158, v159
	v_max3_f32 v157, v146, v158, v159
	v_sub_f32_e32 v158, v146, v157
	v_cmp_gt_f32_e32 vcc, 0xc1000000, v158
	s_cbranch_vccnz .Lattn_resc_49
	v_mov_b32_e32 v157, v146
	v_mov_b32_e32 v146, 1.0
	s_branch .LBB0_49
; DI void attn_item(const u16* __restrict__ qbuf, const u16* __restrict__ knope, const u16* __restrict__ krope, ...
;     ...
;       if (__any(alpha != 1.f)) {
; #pragma unroll
;         for (int i = 0; i < 4; ++i)
; #pragma unroll
;           for (int j = 0; j < 16; ++j) oacc[i][j] *= alpha;
;       }
.Lattn_resc_49:
	v_exp_f32_e32 v146, v158
	s_nop 0
	v_pk_mul_f32 v[62:63], v[62:63], v[146:147] op_sel_hi:[1,0]
	v_pk_mul_f32 v[60:61], v[60:61], v[146:147] op_sel_hi:[1,0]
	v_pk_mul_f32 v[58:59], v[58:59], v[146:147] op_sel_hi:[1,0]
	v_pk_mul_f32 v[56:57], v[56:57], v[146:147] op_sel_hi:[1,0]
	v_pk_mul_f32 v[54:55], v[54:55], v[146:147] op_sel_hi:[1,0]
	v_pk_mul_f32 v[52:53], v[52:53], v[146:147] op_sel_hi:[1,0]
	v_pk_mul_f32 v[50:51], v[50:51], v[146:147] op_sel_hi:[1,0]
	v_pk_mul_f32 v[48:49], v[48:49], v[146:147] op_sel_hi:[1,0]
	v_pk_mul_f32 v[46:47], v[46:47], v[146:147] op_sel_hi:[1,0]
	v_pk_mul_f32 v[44:45], v[44:45], v[146:147] op_sel_hi:[1,0]
	v_pk_mul_f32 v[42:43], v[42:43], v[146:147] op_sel_hi:[1,0]
	v_pk_mul_f32 v[40:41], v[40:41], v[146:147] op_sel_hi:[1,0]
	v_pk_mul_f32 v[38:39], v[38:39], v[146:147] op_sel_hi:[1,0]
	v_pk_mul_f32 v[36:37], v[36:37], v[146:147] op_sel_hi:[1,0]
	v_pk_mul_f32 v[34:35], v[34:35], v[146:147] op_sel_hi:[1,0]
	v_pk_mul_f32 v[32:33], v[32:33], v[146:147] op_sel_hi:[1,0]
	v_pk_mul_f32 v[30:31], v[30:31], v[146:147] op_sel_hi:[1,0]
	v_pk_mul_f32 v[28:29], v[28:29], v[146:147] op_sel_hi:[1,0]
	v_pk_mul_f32 v[26:27], v[26:27], v[146:147] op_sel_hi:[1,0]
	v_pk_mul_f32 v[24:25], v[24:25], v[146:147] op_sel_hi:[1,0]
	v_pk_mul_f32 v[22:23], v[22:23], v[146:147] op_sel_hi:[1,0]
	v_pk_mul_f32 v[20:21], v[20:21], v[146:147] op_sel_hi:[1,0]
	v_pk_mul_f32 v[18:19], v[18:19], v[146:147] op_sel_hi:[1,0]
	v_pk_mul_f32 v[16:17], v[16:17], v[146:147] op_sel_hi:[1,0]
	v_pk_mul_f32 v[14:15], v[14:15], v[146:147] op_sel_hi:[1,0]
	v_pk_mul_f32 v[12:13], v[12:13], v[146:147] op_sel_hi:[1,0]
	v_pk_mul_f32 v[10:11], v[10:11], v[146:147] op_sel_hi:[1,0]
	v_pk_mul_f32 v[8:9], v[8:9], v[146:147] op_sel_hi:[1,0]
	v_pk_mul_f32 v[6:7], v[6:7], v[146:147] op_sel_hi:[1,0]
	v_pk_mul_f32 v[4:5], v[4:5], v[146:147] op_sel_hi:[1,0]
	v_pk_mul_f32 v[2:3], v[2:3], v[146:147] op_sel_hi:[1,0]
	v_pk_mul_f32 v[0:1], v[0:1], v[146:147] op_sel_hi:[1,0]
; DI unsigned pk2(float a, float b) { f32x2_t f = {a, b}; return __builtin_bit_cast(unsigned, __builtin_convertvector(f, bf16x2_t)); }
; DI void attn_item(const u16* __restrict__ qbuf, const u16* __restrict__ knope, const u16* __restrict__ krope, ...
;     ...
;       float ps = 0.f;
; #pragma unroll
;       for (int mt = 0; mt < 2; ++mt)
; #pragma unroll
;         for (int j = 0; j < 16; ++j) { const float pv = __builtin_amdgcn_exp2f(st[mt][j] - m_new); st[mt][j] = pv; ps += pv; }
;       l_run = l_run * alpha + ps;
;       if (__any(alpha != 1.f)) {
; #pragma unroll
;         for (int i = 0; i < 4; ++i)
; #pragma unroll
;           for (int j = 0; j < 16; ++j) oacc[i][j] *= alpha;
;       }
; #pragma unroll
;       for (int mt = 0; mt < 2; ++mt)
; #pragma unroll
;         for (int s = 0; s < 2; ++s) {
;           union { bf16x8 v; unsigned u[4]; } pf;
; #pragma unroll
;           for (int k = 0; k < 4; ++k) pf.u[k] = pk2(st[mt][8 * s + 2 * k], st[mt][8 * s + 2 * k + 1]);
; #pragma unroll
;           for (int vt4 = 0; vt4 < 4; ++vt4) {
;             const bf16x8 vf = *(const bf16x8*)(cur + 24576 + koff[mt * 2 + s] + vt4 * 4096);
;             oacc[vt4] = __builtin_amdgcn_mfma_f32_32x32x16_bf16(vf, pf.v, oacc[vt4], 0, 0, 0);
;           }
;         }
.LBB0_49:
	v_sub_f32_e32 v64, v64, v157
	v_sub_f32_e32 v65, v65, v157
	v_sub_f32_e32 v66, v66, v157
	v_sub_f32_e32 v67, v67, v157
	v_sub_f32_e32 v68, v68, v157
	v_sub_f32_e32 v69, v69, v157
	v_sub_f32_e32 v70, v70, v157
	v_sub_f32_e32 v71, v71, v157
	v_exp_f32_e32 v64, v64
	v_exp_f32_e32 v65, v65
	v_exp_f32_e32 v66, v66
	v_exp_f32_e32 v67, v67
	v_exp_f32_e32 v68, v68
	v_exp_f32_e32 v69, v69
	v_exp_f32_e32 v70, v70
	v_exp_f32_e32 v71, v71
	v_add_f32_e32 v158, v64, v65
	v_add_f32_e32 v159, v66, v67
	v_add_f32_e32 v158, v158, v68
	v_add_f32_e32 v159, v159, v69
	v_add_f32_e32 v158, v158, v70
	v_add_f32_e32 v159, v159, v71
	v_cvt_pk_bf16_f32 v64, v64, v65
	v_cvt_pk_bf16_f32 v65, v66, v67
	v_cvt_pk_bf16_f32 v66, v68, v69
	v_cvt_pk_bf16_f32 v67, v70, v71
	v_add_f32_e32 v160, v158, v159
	v_nop
	s_waitcnt lgkmcnt(7)
	v_mfma_f32_32x32x16_bf16 v[48:63], v[224:227], v[64:67], v[48:63]
	ds_read_b128 v[224:227], v163 offset:24576
	v_sub_f32_e32 v72, v72, v157
	v_sub_f32_e32 v73, v73, v157
	v_sub_f32_e32 v74, v74, v157
	v_sub_f32_e32 v75, v75, v157
	v_sub_f32_e32 v76, v76, v157
	v_sub_f32_e32 v77, v77, v157
	v_sub_f32_e32 v78, v78, v157
	s_waitcnt lgkmcnt(7)
	v_mfma_f32_32x32x16_bf16 v[32:47], v[228:231], v[64:67], v[32:47]
	ds_read_b128 v[228:231], v163 offset:28672
	v_sub_f32_e32 v79, v79, v157
	v_exp_f32_e32 v72, v72
	v_exp_f32_e32 v73, v73
	v_exp_f32_e32 v74, v74
	v_exp_f32_e32 v75, v75
	v_exp_f32_e32 v76, v76
	v_exp_f32_e32 v77, v77
	s_waitcnt lgkmcnt(7)
	v_mfma_f32_32x32x16_bf16 v[16:31], v[232:235], v[64:67], v[16:31]
	ds_read_b128 v[232:235], v163 offset:32768
	v_exp_f32_e32 v78, v78
	v_exp_f32_e32 v79, v79
	v_add_f32_e32 v158, v72, v73
	v_add_f32_e32 v159, v74, v75
	v_add_f32_e32 v158, v158, v76
	v_add_f32_e32 v159, v159, v77
	v_add_f32_e32 v158, v158, v78
	s_waitcnt lgkmcnt(7)
	v_mfma_f32_32x32x16_bf16 v[0:15], v[236:239], v[64:67], v[0:15]
	ds_read_b128 v[236:239], v163 offset:36864
	v_add_f32_e32 v159, v159, v79
	v_cvt_pk_bf16_f32 v72, v72, v73
	v_cvt_pk_bf16_f32 v73, v74, v75
	v_cvt_pk_bf16_f32 v74, v76, v77
	v_cvt_pk_bf16_f32 v75, v78, v79
	v_add_f32_e32 v160, v160, v158
	v_add_f32_e32 v160, v160, v159
	s_waitcnt lgkmcnt(7)
	v_mfma_f32_32x32x16_bf16 v[48:63], v[240:243], v[72:75], v[48:63]
	ds_read_b128 v[240:243], v164 offset:24576
	v_sub_f32_e32 v80, v80, v157
	v_sub_f32_e32 v81, v81, v157
	v_sub_f32_e32 v82, v82, v157
	v_sub_f32_e32 v83, v83, v157
	v_sub_f32_e32 v84, v84, v157
	v_sub_f32_e32 v85, v85, v157
	v_sub_f32_e32 v86, v86, v157
	s_waitcnt lgkmcnt(7)
	v_mfma_f32_32x32x16_bf16 v[32:47], v[244:247], v[72:75], v[32:47]
	ds_read_b128 v[244:247], v164 offset:28672
	v_sub_f32_e32 v87, v87, v157
	v_exp_f32_e32 v80, v80
	v_exp_f32_e32 v81, v81
	v_exp_f32_e32 v82, v82
	v_exp_f32_e32 v83, v83
	v_exp_f32_e32 v84, v84
	v_exp_f32_e32 v85, v85
	s_waitcnt lgkmcnt(7)
	v_mfma_f32_32x32x16_bf16 v[16:31], v[248:251], v[72:75], v[16:31]
	ds_read_b128 v[248:251], v164 offset:32768
	v_exp_f32_e32 v86, v86
	v_exp_f32_e32 v87, v87
	v_add_f32_e32 v158, v80, v81
	v_add_f32_e32 v159, v82, v83
	v_add_f32_e32 v158, v158, v84
	v_add_f32_e32 v159, v159, v85
	v_add_f32_e32 v158, v158, v86
	s_waitcnt lgkmcnt(7)
	v_mfma_f32_32x32x16_bf16 v[0:15], v[186:189], v[72:75], v[0:15]
	ds_read_b128 v[186:189], v164 offset:36864
	v_add_f32_e32 v159, v159, v87
	v_cvt_pk_bf16_f32 v80, v80, v81
	v_cvt_pk_bf16_f32 v81, v82, v83
	v_cvt_pk_bf16_f32 v82, v84, v85
	v_cvt_pk_bf16_f32 v83, v86, v87
	v_add_f32_e32 v160, v160, v158
	v_add_f32_e32 v160, v160, v159
	s_waitcnt lgkmcnt(7)
	v_mfma_f32_32x32x16_bf16 v[48:63], v[224:227], v[80:83], v[48:63]
	v_sub_f32_e32 v88, v88, v157
	v_sub_f32_e32 v89, v89, v157
	v_sub_f32_e32 v90, v90, v157
	v_sub_f32_e32 v91, v91, v157
	v_sub_f32_e32 v92, v92, v157
	v_sub_f32_e32 v93, v93, v157
	v_sub_f32_e32 v94, v94, v157
	s_waitcnt lgkmcnt(6)
	v_mfma_f32_32x32x16_bf16 v[32:47], v[228:231], v[80:83], v[32:47]
	v_sub_f32_e32 v95, v95, v157
	v_exp_f32_e32 v88, v88
	v_exp_f32_e32 v89, v89
	v_exp_f32_e32 v90, v90
	v_exp_f32_e32 v91, v91
	v_exp_f32_e32 v92, v92
	v_exp_f32_e32 v93, v93
	s_waitcnt lgkmcnt(5)
	v_mfma_f32_32x32x16_bf16 v[16:31], v[232:235], v[80:83], v[16:31]
	v_exp_f32_e32 v94, v94
	v_exp_f32_e32 v95, v95
	v_add_f32_e32 v158, v88, v89
	v_add_f32_e32 v159, v90, v91
	v_add_f32_e32 v158, v158, v92
	v_add_f32_e32 v159, v159, v93
	v_add_f32_e32 v158, v158, v94
	s_waitcnt lgkmcnt(4)
	v_mfma_f32_32x32x16_bf16 v[0:15], v[236:239], v[80:83], v[0:15]
	v_add_f32_e32 v159, v159, v95
	v_cvt_pk_bf16_f32 v88, v88, v89
	v_cvt_pk_bf16_f32 v89, v90, v91
	v_cvt_pk_bf16_f32 v90, v92, v93
	v_cvt_pk_bf16_f32 v91, v94, v95
	v_add_f32_e32 v160, v160, v158
	v_add_f32_e32 v160, v160, v159
	s_waitcnt lgkmcnt(3)
	v_mfma_f32_32x32x16_bf16 v[48:63], v[240:243], v[88:91], v[48:63]
	v_fmac_f32_e32 v160, v151, v146
	s_waitcnt lgkmcnt(2)
	v_mfma_f32_32x32x16_bf16 v[32:47], v[244:247], v[88:91], v[32:47]
	v_mov_b32_e32 v146, v157
	s_waitcnt lgkmcnt(1)
	v_mfma_f32_32x32x16_bf16 v[16:31], v[248:251], v[88:91], v[16:31]
	v_mov_b32_e32 v151, v160
	s_waitcnt lgkmcnt(0)
	v_mfma_f32_32x32x16_bf16 v[0:15], v[186:189], v[88:91], v[0:15]

; DI void attn_item(const u16* __restrict__ qbuf, const u16* __restrict__ knope, const u16* __restrict__ krope, ...
;     ...
;       float mx = fmaxf(st[0][0], st[1][0]);
; #pragma unroll
;       for (int j = 1; j < 16; ++j) mx = fmaxf(mx, fmaxf(st[0][j], st[1][j]));
;       mx = fmaxf(mx, __shfl_xor(mx, 32, 64));
;       const float m_new = fmaxf(m_run, mx);
;       const float alpha = __builtin_amdgcn_exp2f(m_run - m_new);
;       m_run = m_new;
;       float ps = 0.f;
; #pragma unroll
;       for (int mt = 0; mt < 2; ++mt)
; #pragma unroll
;         for (int j = 0; j < 16; ++j) { const float pv = __builtin_amdgcn_exp2f(st[mt][j] - m_new); st[mt][j] = pv; ps += pv; }
;       l_run = l_run * alpha + ps;
;       if (__any(alpha != 1.f)) {
; #pragma unroll
;         for (int i = 0; i < 4; ++i)
; #pragma unroll
;           for (int j = 0; j < 16; ++j) oacc[i][j] *= alpha;
;       }
.LBB0_70:
	v_max3_f32 v166, v64, v65, v66
	v_max3_f32 v167, v67, v68, v69
	v_max3_f32 v166, v166, v70, v71
	v_max3_f32 v167, v167, v72, v73
	v_max3_f32 v166, v166, v74, v75
	v_max3_f32 v167, v167, v76, v77
	v_max3_f32 v166, v166, v78, v79
	v_max_f32_e32 v166, v166, v167
	s_nop 1
	v_max3_f32 v167, v80, v81, v82
	v_max3_f32 v168, v83, v84, v85
	v_max3_f32 v167, v167, v86, v87
	v_max3_f32 v168, v168, v88, v89
	v_max3_f32 v167, v167, v90, v91
	v_max3_f32 v168, v168, v92, v93
	v_max3_f32 v167, v167, v94, v95
	v_max3_f32 v166, v166, v167, v168
	v_mov_b32_e32 v167, v166
	s_nop 1
	v_permlane32_swap_b32_e32 v166, v167
	v_max3_f32 v165, v146, v166, v167
	v_sub_f32_e32 v166, v146, v165
	v_cmp_gt_f32_e32 vcc, 0xc1000000, v166
	s_cbranch_vccnz .Lattn_resc_72
	v_mov_b32_e32 v165, v146
	v_mov_b32_e32 v146, 1.0
	s_branch .LBB0_72
.Lattn_resc_72:
	v_exp_f32_e32 v146, v166
	s_nop 0
	v_pk_mul_f32 v[62:63], v[62:63], v[146:147] op_sel_hi:[1,0]
	v_pk_mul_f32 v[60:61], v[60:61], v[146:147] op_sel_hi:[1,0]
	v_pk_mul_f32 v[58:59], v[58:59], v[146:147] op_sel_hi:[1,0]
	v_pk_mul_f32 v[56:57], v[56:57], v[146:147] op_sel_hi:[1,0]
	v_pk_mul_f32 v[54:55], v[54:55], v[146:147] op_sel_hi:[1,0]
	v_pk_mul_f32 v[52:53], v[52:53], v[146:147] op_sel_hi:[1,0]
	v_pk_mul_f32 v[50:51], v[50:51], v[146:147] op_sel_hi:[1,0]
	v_pk_mul_f32 v[48:49], v[48:49], v[146:147] op_sel_hi:[1,0]
	v_pk_mul_f32 v[46:47], v[46:47], v[146:147] op_sel_hi:[1,0]
	v_pk_mul_f32 v[44:45], v[44:45], v[146:147] op_sel_hi:[1,0]
	v_pk_mul_f32 v[42:43], v[42:43], v[146:147] op_sel_hi:[1,0]
	v_pk_mul_f32 v[40:41], v[40:41], v[146:147] op_sel_hi:[1,0]
	v_pk_mul_f32 v[38:39], v[38:39], v[146:147] op_sel_hi:[1,0]
	v_pk_mul_f32 v[36:37], v[36:37], v[146:147] op_sel_hi:[1,0]
	v_pk_mul_f32 v[34:35], v[34:35], v[146:147] op_sel_hi:[1,0]
	v_pk_mul_f32 v[32:33], v[32:33], v[146:147] op_sel_hi:[1,0]
	v_pk_mul_f32 v[30:31], v[30:31], v[146:147] op_sel_hi:[1,0]
	v_pk_mul_f32 v[28:29], v[28:29], v[146:147] op_sel_hi:[1,0]
	v_pk_mul_f32 v[26:27], v[26:27], v[146:147] op_sel_hi:[1,0]
	v_pk_mul_f32 v[24:25], v[24:25], v[146:147] op_sel_hi:[1,0]
	v_pk_mul_f32 v[22:23], v[22:23], v[146:147] op_sel_hi:[1,0]
	v_pk_mul_f32 v[20:21], v[20:21], v[146:147] op_sel_hi:[1,0]
	v_pk_mul_f32 v[18:19], v[18:19], v[146:147] op_sel_hi:[1,0]
	v_pk_mul_f32 v[16:17], v[16:17], v[146:147] op_sel_hi:[1,0]
	v_pk_mul_f32 v[14:15], v[14:15], v[146:147] op_sel_hi:[1,0]
	v_pk_mul_f32 v[12:13], v[12:13], v[146:147] op_sel_hi:[1,0]
	v_pk_mul_f32 v[10:11], v[10:11], v[146:147] op_sel_hi:[1,0]
	v_pk_mul_f32 v[8:9], v[8:9], v[146:147] op_sel_hi:[1,0]
	v_pk_mul_f32 v[6:7], v[6:7], v[146:147] op_sel_hi:[1,0]
	v_pk_mul_f32 v[4:5], v[4:5], v[146:147] op_sel_hi:[1,0]
	v_pk_mul_f32 v[2:3], v[2:3], v[146:147] op_sel_hi:[1,0]
	v_pk_mul_f32 v[0:1], v[0:1], v[146:147] op_sel_hi:[1,0]

; template <int MT, class Epi>
; DI void gemm_tile(const u16* __restrict__ X, long ldx, const u16* __restrict__ W, long ldw, int K, char* smem,
;                   int m0, int n0, const Epi& epi, bool pre = false, const u16* Xn = nullptr, const u16* Wn = nullptr) {
;     ...
;   do {
;     asm volatile("s_waitcnt vmcnt(0)" ::: "memory");
;     __syncthreads();
;     if (kt + 1 < nk) GT_DMA((unsigned)((kt + 1) & 1) * 32768u)
;     else if (Xn != nullptr) { xe = Xn + oxe; xo = Xn + oxo; we = Wn + owe; wo = Wn + owo; GT_DMA(0u) }
;     const char* cur = smem + (kt & 1) * 32768;
; #pragma unroll
;     for (int ks = 0; ks < 2; ++ks) {
;       bf16x8 xf[MT], wf[4];
;       const int ch = ((ks * 4 + g) ^ rsw) << 4;
; #pragma unroll
;       for (int i = 0; i < MT; ++i) xf[i] = *(const bf16x8*)(cur + (wm * 16 * MT + i * 16 + lr) * 128 + ch);
; #pragma unroll
;       for (int i = 0; i < 4; ++i) wf[i] = *(const bf16x8*)(cur + 16384 + (wn * 64 + i * 16 + lr) * 128 + ch);
; #pragma unroll
;       for (int nt = 0; nt < 4; ++nt)
; #pragma unroll
;         for (int mt = 0; mt < MT; ++mt)
;           acc[nt][mt] = __builtin_amdgcn_mfma_f32_16x16x32_bf16(wf[nt], xf[mt], acc[nt][mt], 0, 0, 0);
;     }
;   } while (++kt < nk);
.LBB0_144:
	s_add_i32 s7, s8, 0x8000
	v_lshl_add_u64 v[124:125], v[76:77], 0, s[40:41]
	s_and_b32 s9, s7, 0x8000
	v_lshl_add_u64 v[122:123], v[74:75], 0, s[40:41]
	v_lshl_add_u64 v[126:127], v[124:125], 0, s[74:75]
	s_waitcnt vmcnt(0)
	s_barrier
	s_and_b32 s8, s8, 0x8000
	v_or_b32_e32 v162, s8, v85
	v_add3_u32 v163, v162, v81, v82
	v_add3_u32 v164, v162, v84, v82
	v_or_b32_e32 v165, s8, v83
	v_add3_u32 v166, v165, v81, v82
	v_add3_u32 v167, v165, v84, v82
	ds_read_b128 v[86:89], v163
	ds_read_b128 v[90:93], v163 offset:2048
	ds_read_b128 v[94:97], v163 offset:4096
	ds_read_b128 v[98:101], v163 offset:6144
	ds_read_b128 v[102:105], v164 offset:16384
	ds_read_b128 v[106:109], v164 offset:18432
	ds_read_b128 v[110:113], v164 offset:20480
	ds_read_b128 v[114:117], v164 offset:22528
	ds_read_b128 v[130:133], v166
	ds_read_b128 v[134:137], v166 offset:2048
	ds_read_b128 v[138:141], v166 offset:4096
	ds_read_b128 v[142:145], v166 offset:6144
	ds_read_b128 v[146:149], v167 offset:16384
	ds_read_b128 v[150:153], v167 offset:18432
	ds_read_b128 v[154:157], v167 offset:20480
	ds_read_b128 v[158:161], v167 offset:22528
	s_add_i32 s10, s9, s5
	s_mov_b32 s11, m0
	s_mov_b32 m0, s10
	s_nop 0
	global_load_lds_dwordx4 v[126:127], off
	s_mov_b32 m0, s11
	v_lshl_add_u64 v[126:127], v[122:123], 0, s[94:95]
	s_add_i32 s11, s10, 0x400
	s_mov_b32 s12, m0
	s_mov_b32 m0, s11
	s_nop 0
	global_load_lds_dwordx4 v[126:127], off
	s_mov_b32 m0, s12
	v_lshl_add_u64 v[124:125], v[124:125], 0, s[76:77]
	s_add_i32 s11, s10, 0x800
	s_mov_b32 s12, m0
	s_mov_b32 m0, s11
	s_nop 0
	global_load_lds_dwordx4 v[124:125], off
	s_mov_b32 m0, s12
	v_lshl_add_u64 v[120:121], v[72:73], 0, s[40:41]
	v_lshl_add_u64 v[122:123], v[122:123], 0, s[54:55]
	s_addk_i32 s10, 0xc00
	s_mov_b32 s11, m0
	s_mov_b32 m0, s10
	s_nop 0
	global_load_lds_dwordx4 v[122:123], off
	s_mov_b32 m0, s11
	v_lshl_add_u64 v[118:119], v[70:71], 0, s[40:41]
	v_lshl_add_u64 v[128:129], v[120:121], 0, s[28:29]
	s_add_i32 s9, s9, s6
	s_mov_b32 s10, m0
	s_mov_b32 m0, s9
	s_nop 0
	global_load_lds_dwordx4 v[128:129], off
	s_mov_b32 m0, s10
	v_lshl_add_u64 v[122:123], v[118:119], 0, s[94:95]
	s_add_i32 s10, s9, 0x400
	s_mov_b32 s11, m0
	s_mov_b32 m0, s10
	s_nop 0
	global_load_lds_dwordx4 v[122:123], off
	s_mov_b32 m0, s11
	v_lshl_add_u64 v[120:121], v[120:121], 0, s[78:79]
	s_add_i32 s10, s9, 0x800
	s_mov_b32 s11, m0
	s_mov_b32 m0, s10
	s_nop 0
	global_load_lds_dwordx4 v[120:121], off
	s_mov_b32 m0, s11
	v_lshl_add_u64 v[118:119], v[118:119], 0, s[54:55]
	s_addk_i32 s9, 0xc00
	s_mov_b32 s10, m0
	s_mov_b32 m0, s9
	s_nop 0
	global_load_lds_dwordx4 v[118:119], off
	s_mov_b32 m0, s10
	s_mov_b32 s8, s7
	s_add_u32 s40, s40, 0x80
	s_addc_u32 s41, s41, 0
	s_cmpk_lg_i32 s40, 0x780
	s_waitcnt lgkmcnt(11)
	v_mfma_f32_16x16x32_bf16 v[62:65], v[102:105], v[86:89], v[62:65]
	v_mfma_f32_16x16x32_bf16 v[58:61], v[102:105], v[90:93], v[58:61]
	v_mfma_f32_16x16x32_bf16 v[54:57], v[102:105], v[94:97], v[54:57]
	v_mfma_f32_16x16x32_bf16 v[50:53], v[102:105], v[98:101], v[50:53]
	s_waitcnt lgkmcnt(10)
	v_mfma_f32_16x16x32_bf16 v[34:37], v[106:109], v[98:101], v[34:37]
	s_waitcnt lgkmcnt(9)
	v_mfma_f32_16x16x32_bf16 v[18:21], v[110:113], v[98:101], v[18:21]
	s_waitcnt lgkmcnt(8)
	v_mfma_f32_16x16x32_bf16 v[14:17], v[114:117], v[86:89], v[14:17]
	v_mfma_f32_16x16x32_bf16 v[10:13], v[114:117], v[90:93], v[10:13]
	v_mfma_f32_16x16x32_bf16 v[6:9], v[114:117], v[94:97], v[6:9]
	v_mfma_f32_16x16x32_bf16 v[2:5], v[114:117], v[98:101], v[2:5]
	v_mfma_f32_16x16x32_bf16 v[46:49], v[106:109], v[86:89], v[46:49]
	v_mfma_f32_16x16x32_bf16 v[42:45], v[106:109], v[90:93], v[42:45]
	v_mfma_f32_16x16x32_bf16 v[38:41], v[106:109], v[94:97], v[38:41]
	v_mfma_f32_16x16x32_bf16 v[30:33], v[110:113], v[86:89], v[30:33]
	v_mfma_f32_16x16x32_bf16 v[26:29], v[110:113], v[90:93], v[26:29]
	v_mfma_f32_16x16x32_bf16 v[22:25], v[110:113], v[94:97], v[22:25]
	s_waitcnt lgkmcnt(3)
	v_mfma_f32_16x16x32_bf16 v[62:65], v[146:149], v[130:133], v[62:65]
	v_mfma_f32_16x16x32_bf16 v[58:61], v[146:149], v[134:137], v[58:61]
	v_mfma_f32_16x16x32_bf16 v[54:57], v[146:149], v[138:141], v[54:57]
	v_mfma_f32_16x16x32_bf16 v[50:53], v[146:149], v[142:145], v[50:53]
	s_waitcnt lgkmcnt(2)
	v_mfma_f32_16x16x32_bf16 v[46:49], v[150:153], v[130:133], v[46:49]
	v_mfma_f32_16x16x32_bf16 v[42:45], v[150:153], v[134:137], v[42:45]
	v_mfma_f32_16x16x32_bf16 v[38:41], v[150:153], v[138:141], v[38:41]
	v_mfma_f32_16x16x32_bf16 v[34:37], v[150:153], v[142:145], v[34:37]
	s_waitcnt lgkmcnt(1)
	v_mfma_f32_16x16x32_bf16 v[30:33], v[154:157], v[130:133], v[30:33]
	v_mfma_f32_16x16x32_bf16 v[26:29], v[154:157], v[134:137], v[26:29]
	v_mfma_f32_16x16x32_bf16 v[22:25], v[154:157], v[138:141], v[22:25]
	v_mfma_f32_16x16x32_bf16 v[18:21], v[154:157], v[142:145], v[18:21]
	s_waitcnt lgkmcnt(0)
	v_mfma_f32_16x16x32_bf16 v[14:17], v[158:161], v[130:133], v[14:17]
	v_mfma_f32_16x16x32_bf16 v[10:13], v[158:161], v[134:137], v[10:13]
	v_mfma_f32_16x16x32_bf16 v[6:9], v[158:161], v[138:141], v[6:9]
	v_mfma_f32_16x16x32_bf16 v[2:5], v[158:161], v[142:145], v[2:5]
	s_cbranch_scc1 .LBB0_144
; DI int get_bid() { int b = blockIdx.x; asm volatile("" : "+s"(b)); return b; }
; template <int MT, class Epi>
; DI void gemm_tile(const u16* __restrict__ X, long ldx, const u16* __restrict__ W, long ldw, int K, char* smem,
;                   int m0, int n0, const Epi& epi, bool pre = false, const u16* Xn = nullptr, const u16* Wn = nullptr) {
;     ...
;   if (!pre) {
;     __syncthreads();
;     GT_DMA(0u)
;   } else {
;     xe += 64; xo += 64; we += 64; wo += 64;
;   }
;   const int nk = K >> 6;
;   int kt = 0;
;   do {
;     asm volatile("s_waitcnt vmcnt(0)" ::: "memory");
;     __syncthreads();
;     if (kt + 1 < nk) GT_DMA((unsigned)((kt + 1) & 1) * 32768u)
;     else if (Xn != nullptr) { xe = Xn + oxe; xo = Xn + oxo; we = Wn + owe; wo = Wn + owo; GT_DMA(0u) }
; DI void phase_odd(const Params& p, int o, int sub, char* smem) {
;     ...
;     for (int t = get_bid(); t < 132 * 14; t += gridDim.x) {
;       const int tm = t / 14, tn = t % 14;
;       const int t2 = t + gridDim.x, tm2 = t2 / 14, tn2 = t2 % 14;
;       const bool nx = t2 < 132 * 14;
;       gemm_tile<4>(hbuf + (size_t)tm * 128 * 1024, 1024, W + WO_IN + (size_t)tn * 128 * 1024, 1024, 1024, smem, tm * 128, tn * 128, epi, pre,
;                    nx ? hbuf + (size_t)tm2 * 128 * 1024 : nullptr, W + WO_IN + (size_t)tn2 * 128 * 1024);
;       pre = nx;
;     }
	v_readlane_b32 s8, v255, 5
	v_readlane_b32 s14, v255, 11
	s_add_i32 s4, s4, s14
	s_mul_hi_i32 s7, s4, 0x92492493
	s_add_i32 s7, s7, s4
	s_lshr_b32 s8, s7, 31
	s_ashr_i32 s7, s7, 3
	s_add_i32 s46, s7, s8
	s_cmpk_gt_i32 s4, 0x737
	v_readlane_b32 s9, v255, 6
	s_cselect_b64 s[40:41], -1, 0
	s_ashr_i32 s47, s46, 31
	s_lshl_b64 s[8:9], s[46:47], 18
	s_add_u32 s7, s0, s8
	s_addc_u32 s8, s1, s9
	s_cmpk_lt_i32 s4, 0x738
	s_waitcnt vmcnt(0)
	s_cselect_b32 s45, s8, 0
	s_cselect_b32 s44, s7, 0
	v_readlane_b32 s12, v255, 9
	v_readlane_b32 s13, v255, 10
	s_cmp_eq_u64 s[44:45], 0
	v_readlane_b32 s10, v255, 7
	v_readlane_b32 s11, v255, 8
	v_readlane_b32 s15, v255, 12
	s_barrier
	s_cbranch_scc1 .LBB0_147
	s_mul_i32 s7, s46, 14
	s_sub_i32 s8, s4, s7
	s_ashr_i32 s9, s8, 31
	s_lshl_b64 s[8:9], s[8:9], 18
	s_add_u32 s8, s12, s8
	s_addc_u32 s9, s13, s9
	v_lshl_add_u64 v[70:71], s[44:45], 0, v[68:69]
	v_lshl_add_u64 v[72:73], s[8:9], 0, v[66:67]
	v_lshl_add_u64 v[66:67], s[44:45], 0, v[66:67]
	s_mov_b32 s7, m0
	s_mov_b32 m0, s5
	s_nop 0
	global_load_lds_dwordx4 v[70:71], off
	s_mov_b32 m0, s7
	s_mov_b64 s[10:11], 0x4000
	v_lshl_add_u64 v[68:69], s[8:9], 0, v[68:69]
	v_lshl_add_u64 v[74:75], v[66:67], 0, s[10:11]
	s_add_i32 s7, s5, 0x400
	s_mov_b32 s8, m0
	s_mov_b32 m0, s7
	s_nop 0
	global_load_lds_dwordx4 v[74:75], off
	s_mov_b32 m0, s8
	s_mov_b64 s[12:13], 0x8000
	v_lshl_add_u64 v[70:71], v[70:71], 0, s[12:13]
	s_add_i32 s7, s5, 0x800
	s_mov_b32 s8, m0
	s_mov_b32 m0, s7
	s_nop 0
	global_load_lds_dwordx4 v[70:71], off
	s_mov_b32 m0, s8
	s_mov_b64 s[14:15], 0xc000
	v_lshl_add_u64 v[66:67], v[66:67], 0, s[14:15]
	s_add_i32 s7, s5, 0xc00
	s_mov_b32 s8, m0
	s_mov_b32 m0, s7
	s_nop 0
	global_load_lds_dwordx4 v[66:67], off
	s_mov_b32 m0, s8
	s_mov_b32 s7, m0
	s_mov_b32 m0, s6
	s_nop 0
	global_load_lds_dwordx4 v[68:69], off
	s_mov_b32 m0, s7
	v_lshl_add_u64 v[66:67], v[72:73], 0, s[10:11]
	s_add_i32 s6, s5, 0x4400
	s_mov_b32 s7, m0
	s_mov_b32 m0, s6
	s_nop 0
	global_load_lds_dwordx4 v[66:67], off
	s_mov_b32 m0, s7
	v_lshl_add_u64 v[66:67], v[68:69], 0, s[12:13]
	s_add_i32 s6, s5, 0x4800
	s_mov_b32 s7, m0
	s_mov_b32 m0, s6
	s_nop 0
	global_load_lds_dwordx4 v[66:67], off
	s_mov_b32 m0, s7
	v_lshl_add_u64 v[66:67], v[72:73], 0, s[14:15]
	s_addk_i32 s5, 0x4c00
	s_mov_b32 s6, m0
	s_mov_b32 m0, s5
	s_nop 0
	global_load_lds_dwordx4 v[66:67], off
	s_mov_b32 m0, s6

; template <int MT, class Epi>
; DI void gemm_tile(const u16* __restrict__ X, long ldx, const u16* __restrict__ W, long ldw, int K, char* smem,
;                   int m0, int n0, const Epi& epi, bool pre = false, const u16* Xn = nullptr, const u16* Wn = nullptr) {
;     ...
;   do {
;     asm volatile("s_waitcnt vmcnt(0)" ::: "memory");
;     __syncthreads();
;     if (kt + 1 < nk) GT_DMA((unsigned)((kt + 1) & 1) * 32768u)
;     else if (Xn != nullptr) { xe = Xn + oxe; xo = Xn + oxo; we = Wn + owe; wo = Wn + owo; GT_DMA(0u) }
;     const char* cur = smem + (kt & 1) * 32768;
; #pragma unroll
;     for (int ks = 0; ks < 2; ++ks) {
;       bf16x8 xf[MT], wf[4];
;       const int ch = ((ks * 4 + g) ^ rsw) << 4;
; #pragma unroll
;       for (int i = 0; i < MT; ++i) xf[i] = *(const bf16x8*)(cur + (wm * 16 * MT + i * 16 + lr) * 128 + ch);
; #pragma unroll
;       for (int i = 0; i < 4; ++i) wf[i] = *(const bf16x8*)(cur + 16384 + (wn * 64 + i * 16 + lr) * 128 + ch);
; #pragma unroll
;       for (int nt = 0; nt < 4; ++nt)
; #pragma unroll
;         for (int mt = 0; mt < MT; ++mt)
;           acc[nt][mt] = __builtin_amdgcn_mfma_f32_16x16x32_bf16(wf[nt], xf[mt], acc[nt][mt], 0, 0, 0);
;     }
;   } while (++kt < nk);
.LBB0_422:
	s_add_i32 s7, s8, 0x8000
	v_lshl_add_u64 v[124:125], v[76:77], 0, s[40:41]
	s_and_b32 s9, s7, 0x8000
	v_lshl_add_u64 v[122:123], v[74:75], 0, s[40:41]
	v_lshl_add_u64 v[126:127], v[124:125], 0, s[74:75]
	s_waitcnt vmcnt(0)
	s_barrier
	s_and_b32 s8, s8, 0x8000
	v_or_b32_e32 v162, s8, v85
	v_add3_u32 v163, v162, v81, v82
	v_add3_u32 v164, v162, v84, v82
	v_or_b32_e32 v165, s8, v83
	v_add3_u32 v166, v165, v81, v82
	v_add3_u32 v167, v165, v84, v82
	ds_read_b128 v[86:89], v163
	ds_read_b128 v[90:93], v163 offset:2048
	ds_read_b128 v[94:97], v163 offset:4096
	ds_read_b128 v[98:101], v163 offset:6144
	ds_read_b128 v[102:105], v164 offset:16384
	ds_read_b128 v[106:109], v164 offset:18432
	ds_read_b128 v[110:113], v164 offset:20480
	ds_read_b128 v[114:117], v164 offset:22528
	ds_read_b128 v[130:133], v166
	ds_read_b128 v[134:137], v166 offset:2048
	ds_read_b128 v[138:141], v166 offset:4096
	ds_read_b128 v[142:145], v166 offset:6144
	ds_read_b128 v[146:149], v167 offset:16384
	ds_read_b128 v[150:153], v167 offset:18432
	ds_read_b128 v[154:157], v167 offset:20480
	ds_read_b128 v[158:161], v167 offset:22528
	s_add_i32 s10, s9, s5
	s_mov_b32 s11, m0
	s_mov_b32 m0, s10
	s_nop 0
	global_load_lds_dwordx4 v[126:127], off
	s_mov_b32 m0, s11
	v_lshl_add_u64 v[126:127], v[122:123], 0, s[94:95]
	s_add_i32 s11, s10, 0x400
	s_mov_b32 s12, m0
	s_mov_b32 m0, s11
	s_nop 0
	global_load_lds_dwordx4 v[126:127], off
	s_mov_b32 m0, s12
	v_lshl_add_u64 v[124:125], v[124:125], 0, s[76:77]
	s_add_i32 s11, s10, 0x800
	s_mov_b32 s12, m0
	s_mov_b32 m0, s11
	s_nop 0
	global_load_lds_dwordx4 v[124:125], off
	s_mov_b32 m0, s12
	v_lshl_add_u64 v[120:121], v[72:73], 0, s[40:41]
	v_lshl_add_u64 v[122:123], v[122:123], 0, s[54:55]
	s_addk_i32 s10, 0xc00
	s_mov_b32 s11, m0
	s_mov_b32 m0, s10
	s_nop 0
	global_load_lds_dwordx4 v[122:123], off
	s_mov_b32 m0, s11
	v_lshl_add_u64 v[118:119], v[70:71], 0, s[40:41]
	v_lshl_add_u64 v[128:129], v[120:121], 0, s[28:29]
	s_add_i32 s9, s9, s6
	s_mov_b32 s10, m0
	s_mov_b32 m0, s9
	s_nop 0
	global_load_lds_dwordx4 v[128:129], off
	s_mov_b32 m0, s10
	v_lshl_add_u64 v[122:123], v[118:119], 0, s[94:95]
	s_add_i32 s10, s9, 0x400
	s_mov_b32 s11, m0
	s_mov_b32 m0, s10
	s_nop 0
	global_load_lds_dwordx4 v[122:123], off
	s_mov_b32 m0, s11
	v_lshl_add_u64 v[120:121], v[120:121], 0, s[78:79]
	s_add_i32 s10, s9, 0x800
	s_mov_b32 s11, m0
	s_mov_b32 m0, s10
	s_nop 0
	global_load_lds_dwordx4 v[120:121], off
	s_mov_b32 m0, s11
	v_lshl_add_u64 v[118:119], v[118:119], 0, s[54:55]
	s_addk_i32 s9, 0xc00
	s_mov_b32 s10, m0
	s_mov_b32 m0, s9
	s_nop 0
	global_load_lds_dwordx4 v[118:119], off
	s_mov_b32 m0, s10
	s_mov_b32 s8, s7
	s_add_u32 s40, s40, 0x80
	s_addc_u32 s41, s41, 0
	s_cmpk_lg_i32 s40, 0x780
	s_waitcnt lgkmcnt(11)
	v_mfma_f32_16x16x32_bf16 v[62:65], v[102:105], v[86:89], v[62:65]
	v_mfma_f32_16x16x32_bf16 v[58:61], v[102:105], v[90:93], v[58:61]
	v_mfma_f32_16x16x32_bf16 v[54:57], v[102:105], v[94:97], v[54:57]
	v_mfma_f32_16x16x32_bf16 v[50:53], v[102:105], v[98:101], v[50:53]
	s_waitcnt lgkmcnt(10)
	v_mfma_f32_16x16x32_bf16 v[34:37], v[106:109], v[98:101], v[34:37]
	s_waitcnt lgkmcnt(9)
	v_mfma_f32_16x16x32_bf16 v[18:21], v[110:113], v[98:101], v[18:21]
	s_waitcnt lgkmcnt(8)
	v_mfma_f32_16x16x32_bf16 v[14:17], v[114:117], v[86:89], v[14:17]
	v_mfma_f32_16x16x32_bf16 v[10:13], v[114:117], v[90:93], v[10:13]
	v_mfma_f32_16x16x32_bf16 v[6:9], v[114:117], v[94:97], v[6:9]
	v_mfma_f32_16x16x32_bf16 v[2:5], v[114:117], v[98:101], v[2:5]
	v_mfma_f32_16x16x32_bf16 v[46:49], v[106:109], v[86:89], v[46:49]
	v_mfma_f32_16x16x32_bf16 v[42:45], v[106:109], v[90:93], v[42:45]
	v_mfma_f32_16x16x32_bf16 v[38:41], v[106:109], v[94:97], v[38:41]
	v_mfma_f32_16x16x32_bf16 v[30:33], v[110:113], v[86:89], v[30:33]
	v_mfma_f32_16x16x32_bf16 v[26:29], v[110:113], v[90:93], v[26:29]
	v_mfma_f32_16x16x32_bf16 v[22:25], v[110:113], v[94:97], v[22:25]
	s_waitcnt lgkmcnt(3)
	v_mfma_f32_16x16x32_bf16 v[62:65], v[146:149], v[130:133], v[62:65]
	v_mfma_f32_16x16x32_bf16 v[58:61], v[146:149], v[134:137], v[58:61]
	v_mfma_f32_16x16x32_bf16 v[54:57], v[146:149], v[138:141], v[54:57]
	v_mfma_f32_16x16x32_bf16 v[50:53], v[146:149], v[142:145], v[50:53]
	s_waitcnt lgkmcnt(2)
	v_mfma_f32_16x16x32_bf16 v[46:49], v[150:153], v[130:133], v[46:49]
	v_mfma_f32_16x16x32_bf16 v[42:45], v[150:153], v[134:137], v[42:45]
	v_mfma_f32_16x16x32_bf16 v[38:41], v[150:153], v[138:141], v[38:41]
	v_mfma_f32_16x16x32_bf16 v[34:37], v[150:153], v[142:145], v[34:37]
	s_waitcnt lgkmcnt(1)
	v_mfma_f32_16x16x32_bf16 v[30:33], v[154:157], v[130:133], v[30:33]
	v_mfma_f32_16x16x32_bf16 v[26:29], v[154:157], v[134:137], v[26:29]
	v_mfma_f32_16x16x32_bf16 v[22:25], v[154:157], v[138:141], v[22:25]
	v_mfma_f32_16x16x32_bf16 v[18:21], v[154:157], v[142:145], v[18:21]
	s_waitcnt lgkmcnt(0)
	v_mfma_f32_16x16x32_bf16 v[14:17], v[158:161], v[130:133], v[14:17]
	v_mfma_f32_16x16x32_bf16 v[10:13], v[158:161], v[134:137], v[10:13]
	v_mfma_f32_16x16x32_bf16 v[6:9], v[158:161], v[138:141], v[6:9]
	v_mfma_f32_16x16x32_bf16 v[2:5], v[158:161], v[142:145], v[2:5]
	s_cbranch_scc1 .LBB0_422
; DI int get_bid() { int b = blockIdx.x; asm volatile("" : "+s"(b)); return b; }
; template <int MT, class Epi>
; DI void gemm_tile(const u16* __restrict__ X, long ldx, const u16* __restrict__ W, long ldw, int K, char* smem,
;                   int m0, int n0, const Epi& epi, bool pre = false, const u16* Xn = nullptr, const u16* Wn = nullptr) {
;     ...
;   if (!pre) {
;     __syncthreads();
;     GT_DMA(0u)
;   } else {
;     xe += 64; xo += 64; we += 64; wo += 64;
;   }
;   const int nk = K >> 6;
;   int kt = 0;
;   do {
;     asm volatile("s_waitcnt vmcnt(0)" ::: "memory");
;     __syncthreads();
;     if (kt + 1 < nk) GT_DMA((unsigned)((kt + 1) & 1) * 32768u)
;     else if (Xn != nullptr) { xe = Xn + oxe; xo = Xn + oxo; we = Wn + owe; wo = Wn + owo; GT_DMA(0u) }
; DI void phase_even(const Params& p, int e, int sub, char* smem) {
;     ...
;     for (int t = get_bid(); t < 132 * 40; t += gridDim.x) {
;       const int tm = t / 40, tn = t % 40;
;       const int t2 = t + gridDim.x, tm2 = t2 / 40, tn2 = t2 % 40;
;       const bool nx = t2 < 132 * 40;
;       gemm_tile<4>(hbuf + (size_t)tm * 128 * 1024, 1024, W + WE_IN + (size_t)tn * 128 * 1024, 1024, 1024, smem, tm * 128, tn * 128, epi, pre,
;                    nx ? hbuf + (size_t)tm2 * 128 * 1024 : nullptr, W + WE_IN + (size_t)tn2 * 128 * 1024);
;       pre = nx;
;     }
	v_readlane_b32 s8, v255, 5
	v_readlane_b32 s14, v255, 11
	s_add_i32 s4, s4, s14
	s_mul_hi_i32 s7, s4, 0x66666667
	s_lshr_b32 s8, s7, 31
	s_ashr_i32 s7, s7, 4
	s_add_i32 s46, s7, s8
	s_cmpk_gt_i32 s4, 0x149f
	v_readlane_b32 s9, v255, 6
	s_cselect_b64 s[44:45], -1, 0
	s_ashr_i32 s47, s46, 31
	s_lshl_b64 s[8:9], s[46:47], 18
	s_add_u32 s7, s0, s8
	s_addc_u32 s8, s1, s9
	s_cmpk_lt_i32 s4, 0x14a0
	s_waitcnt vmcnt(0)
	s_cselect_b32 s41, s8, 0
	s_cselect_b32 s40, s7, 0
	v_readlane_b32 s12, v255, 9
	v_readlane_b32 s13, v255, 10
	s_cmp_eq_u64 s[40:41], 0
	v_readlane_b32 s10, v255, 7
	v_readlane_b32 s11, v255, 8
	v_readlane_b32 s15, v255, 12
	s_barrier
	s_cbranch_scc1 .LBB0_425
	s_mul_i32 s7, s46, 40
	s_sub_i32 s8, s4, s7
	s_ashr_i32 s9, s8, 31
	s_lshl_b64 s[8:9], s[8:9], 18
	s_add_u32 s8, s12, s8
	s_addc_u32 s9, s13, s9
	v_lshl_add_u64 v[70:71], s[40:41], 0, v[68:69]
	v_lshl_add_u64 v[72:73], s[8:9], 0, v[66:67]
	v_lshl_add_u64 v[66:67], s[40:41], 0, v[66:67]
	s_mov_b32 s7, m0
	s_mov_b32 m0, s5
	s_nop 0
	global_load_lds_dwordx4 v[70:71], off
	s_mov_b32 m0, s7
	s_mov_b64 s[10:11], 0x4000
	v_lshl_add_u64 v[68:69], s[8:9], 0, v[68:69]
	v_lshl_add_u64 v[74:75], v[66:67], 0, s[10:11]
	s_add_i32 s7, s5, 0x400
	s_mov_b32 s8, m0
	s_mov_b32 m0, s7
	s_nop 0
	global_load_lds_dwordx4 v[74:75], off
	s_mov_b32 m0, s8
	s_mov_b64 s[12:13], 0x8000
	v_lshl_add_u64 v[70:71], v[70:71], 0, s[12:13]
	s_add_i32 s7, s5, 0x800
	s_mov_b32 s8, m0
	s_mov_b32 m0, s7
	s_nop 0
	global_load_lds_dwordx4 v[70:71], off
	s_mov_b32 m0, s8
	s_mov_b64 s[14:15], 0xc000
	v_lshl_add_u64 v[66:67], v[66:67], 0, s[14:15]
	s_add_i32 s7, s5, 0xc00
	s_mov_b32 s8, m0
	s_mov_b32 m0, s7
	s_nop 0
	global_load_lds_dwordx4 v[66:67], off
	s_mov_b32 m0, s8
	s_mov_b32 s7, m0
	s_mov_b32 m0, s6
	s_nop 0
	global_load_lds_dwordx4 v[68:69], off
	s_mov_b32 m0, s7
	v_lshl_add_u64 v[66:67], v[72:73], 0, s[10:11]
	s_add_i32 s6, s5, 0x4400
	s_mov_b32 s7, m0
	s_mov_b32 m0, s6
	s_nop 0
	global_load_lds_dwordx4 v[66:67], off
	s_mov_b32 m0, s7
	v_lshl_add_u64 v[66:67], v[68:69], 0, s[12:13]
	s_add_i32 s6, s5, 0x4800
	s_mov_b32 s7, m0
	s_mov_b32 m0, s6
	s_nop 0
	global_load_lds_dwordx4 v[66:67], off
	s_mov_b32 m0, s7
	v_lshl_add_u64 v[66:67], v[72:73], 0, s[14:15]
	s_addk_i32 s5, 0x4c00
	s_mov_b32 s6, m0
	s_mov_b32 m0, s5
	s_nop 0
	global_load_lds_dwordx4 v[66:67], off
	s_mov_b32 m0, s6

; DI void st_bf4(u16* p, float a, float b, float c, float d) { *(uint2*)p = make_uint2(pk2(a, b), pk2(c, d)); }
; DI float gelu_f(float x) { return 0.5f * x * (1.f + erff(x * 0.70710678118654752f)); }
;   template <int NT, int MT> DI void run(f32x4 (&acc)[NT][MT], int mb, int nb) const {
;     ...
;         } else if (n < 3072) {
;           st_bf4(uvbuf + (size_t)m * 2048 + (n - 1024), gelu_f(v[0]), gelu_f(v[1]), gelu_f(v[2]), gelu_f(v[3]));
.LBB0_428:
	s_andn2_saveexec_b64 s[48:49], s[48:49]
	s_cbranch_execz .LBB0_446
	v_mul_f32_e32 v70, 0x3f3504f3, v62
	v_and_b32_e32 v72, 0x7fffffff, v70
	v_fmamk_f32 v73, v72, 0x378e98ab, v222
	v_fmaak_f32 v73, v72, v73, 0x3b7cd369
	v_fmaak_f32 v73, v72, v73, 0xbcc618b2
	v_fmaak_f32 v73, v72, v73, 0x3dda74e4
	v_fmaak_f32 v73, v72, v73, 0x3f228afd
	v_fmaak_f32 v73, v72, v73, 0x3e03c728
	v_fma_f32 v73, v72, v73, v72
	v_mul_f32_e32 v73, 0xbfb8aa3b, v73
	v_exp_f32_e32 v73, v73
	v_mul_f32_e32 v74, v70, v70
	v_sub_f32_e32 v73, 1.0, v73
	v_fmamk_f32 v71, v74, 0xba1345e1, v200
	v_fmaak_f32 v71, v74, v71, 0xbcdac9b8
	v_fmaak_f32 v71, v74, v71, 0x3de703be
	v_fmaak_f32 v71, v74, v71, 0xbec09330
	v_fmaak_f32 v71, v74, v71, 0x3e0375d0
	v_fma_f32 v71, v72, v71, v72
	v_cmp_ngt_f32_e32 vcc, 1.0, v72
	s_nop 1
	v_cndmask_b32_e32 v71, v71, v73, vcc
	v_mul_f32_e32 v72, 0x3f3504f3, v63
	v_and_b32_e32 v74, 0x7fffffff, v72
	v_fmamk_f32 v75, v74, 0x378e98ab, v222
	v_fmaak_f32 v75, v74, v75, 0x3b7cd369
	v_fmaak_f32 v75, v74, v75, 0xbcc618b2
	v_fmaak_f32 v75, v74, v75, 0x3dda74e4
	v_fmaak_f32 v75, v74, v75, 0x3f228afd
	v_fmaak_f32 v75, v74, v75, 0x3e03c728
	v_fma_f32 v75, v74, v75, v74
	v_mul_f32_e32 v75, 0xbfb8aa3b, v75
	v_exp_f32_e32 v75, v75
	v_mul_f32_e32 v76, v72, v72
	v_sub_f32_e32 v75, 1.0, v75
	v_fmamk_f32 v73, v76, 0xba1345e1, v200
	v_fmaak_f32 v73, v76, v73, 0xbcdac9b8
	v_fmaak_f32 v73, v76, v73, 0x3de703be
	v_fmaak_f32 v73, v76, v73, 0xbec09330
	v_fmaak_f32 v73, v76, v73, 0x3e0375d0
	v_fma_f32 v73, v74, v73, v74
	v_cmp_ngt_f32_e32 vcc, 1.0, v74
	s_nop 1
	v_cndmask_b32_e32 v73, v73, v75, vcc
	v_mul_f32_e32 v74, 0x3f3504f3, v64
	v_and_b32_e32 v76, 0x7fffffff, v74
	v_fmamk_f32 v77, v76, 0x378e98ab, v222
	v_fmaak_f32 v77, v76, v77, 0x3b7cd369
	v_fmaak_f32 v77, v76, v77, 0xbcc618b2
	v_fmaak_f32 v77, v76, v77, 0x3dda74e4
	v_fmaak_f32 v77, v76, v77, 0x3f228afd
	v_fmaak_f32 v77, v76, v77, 0x3e03c728
	v_fma_f32 v77, v76, v77, v76
	v_mul_f32_e32 v77, 0xbfb8aa3b, v77
	v_exp_f32_e32 v77, v77
	v_mul_f32_e32 v78, v74, v74
	v_sub_f32_e32 v77, 1.0, v77
	v_fmamk_f32 v75, v78, 0xba1345e1, v200
	v_fmaak_f32 v75, v78, v75, 0xbcdac9b8
	v_fmaak_f32 v75, v78, v75, 0x3de703be
	v_fmaak_f32 v75, v78, v75, 0xbec09330
	v_fmaak_f32 v75, v78, v75, 0x3e0375d0
	v_fma_f32 v75, v76, v75, v76
	v_cmp_ngt_f32_e32 vcc, 1.0, v76
	s_nop 1
	v_cndmask_b32_e32 v75, v75, v77, vcc
	v_mul_f32_e32 v76, 0x3f3504f3, v65
	v_and_b32_e32 v78, 0x7fffffff, v76
	v_fmamk_f32 v79, v78, 0x378e98ab, v222
	v_fmaak_f32 v79, v78, v79, 0x3b7cd369
	v_fmaak_f32 v79, v78, v79, 0xbcc618b2
	v_fmaak_f32 v79, v78, v79, 0x3dda74e4
	v_fmaak_f32 v79, v78, v79, 0x3f228afd
	v_fmaak_f32 v79, v78, v79, 0x3e03c728
	v_fma_f32 v79, v78, v79, v78
	v_mul_f32_e32 v79, 0xbfb8aa3b, v79
	v_exp_f32_e32 v79, v79
	v_mul_f32_e32 v80, v76, v76
	v_sub_f32_e32 v79, 1.0, v79
	v_fmamk_f32 v77, v80, 0xba1345e1, v200
	v_fmaak_f32 v77, v80, v77, 0xbcdac9b8
	v_fmaak_f32 v77, v80, v77, 0x3de703be
	v_fmaak_f32 v77, v80, v77, 0xbec09330
	v_fmaak_f32 v77, v80, v77, 0x3e0375d0
	v_fma_f32 v77, v78, v77, v78
	v_cmp_ngt_f32_e32 vcc, 1.0, v78
	s_nop 1
	v_cndmask_b32_e32 v77, v77, v79, vcc
	v_bfi_b32 v74, s37, v75, v74
	v_mul_f32_e32 v64, 0.5, v64
	v_add_f32_e32 v74, 1.0, v74
	v_mul_f32_e32 v74, v64, v74
	v_bfi_b32 v64, s37, v73, v72
	v_mul_f32_e32 v63, 0.5, v63
	v_add_f32_e32 v64, 1.0, v64
	v_mul_f32_e32 v64, v63, v64
	v_bfi_b32 v63, s37, v71, v70
	v_readlane_b32 s6, v252, 33
	v_mul_f32_e32 v62, 0.5, v62
	v_add_f32_e32 v63, 1.0, v63
	v_readlane_b32 s7, v252, 34
	v_mul_f32_e32 v70, v62, v63
	v_mul_f32_e32 v65, 0.5, v65
	v_lshl_add_u64 v[62:63], s[6:7], 0, v[68:69]
	v_bfi_b32 v68, s37, v77, v76
	v_add_f32_e32 v68, 1.0, v68
	v_mul_f32_e32 v65, v65, v68
	v_lshl_add_u64 v[62:63], v[182:183], 1, v[62:63]
	v_cvt_pk_bf16_f32 v64, v70, v64
	v_cvt_pk_bf16_f32 v65, v74, v65
	global_store_dwordx2 v[62:63], v[64:65], off offset:-2048

; DI void st_bf4(u16* p, float a, float b, float c, float d) { *(uint2*)p = make_uint2(pk2(a, b), pk2(c, d)); }
; DI float gelu_f(float x) { return 0.5f * x * (1.f + erff(x * 0.70710678118654752f)); }
;   template <int NT, int MT> DI void run(f32x4 (&acc)[NT][MT], int mb, int nb) const {
;     ...
;         } else if (n < 3072) {
;           st_bf4(uvbuf + (size_t)m * 2048 + (n - 1024), gelu_f(v[0]), gelu_f(v[1]), gelu_f(v[2]), gelu_f(v[3]));
.LBB0_452:
	s_andn2_saveexec_b64 s[48:49], s[48:49]
	s_cbranch_execz .LBB0_470
	v_mul_f32_e32 v70, 0x3f3504f3, v58
	v_and_b32_e32 v72, 0x7fffffff, v70
	v_fmamk_f32 v73, v72, 0x378e98ab, v222
	v_fmaak_f32 v73, v72, v73, 0x3b7cd369
	v_fmaak_f32 v73, v72, v73, 0xbcc618b2
	v_fmaak_f32 v73, v72, v73, 0x3dda74e4
	v_fmaak_f32 v73, v72, v73, 0x3f228afd
	v_fmaak_f32 v73, v72, v73, 0x3e03c728
	v_fma_f32 v73, v72, v73, v72
	v_mul_f32_e32 v73, 0xbfb8aa3b, v73
	v_exp_f32_e32 v73, v73
	v_mul_f32_e32 v74, v70, v70
	v_sub_f32_e32 v73, 1.0, v73
	v_fmamk_f32 v71, v74, 0xba1345e1, v200
	v_fmaak_f32 v71, v74, v71, 0xbcdac9b8
	v_fmaak_f32 v71, v74, v71, 0x3de703be
	v_fmaak_f32 v71, v74, v71, 0xbec09330
	v_fmaak_f32 v71, v74, v71, 0x3e0375d0
	v_fma_f32 v71, v72, v71, v72
	v_cmp_ngt_f32_e32 vcc, 1.0, v72
	s_nop 1
	v_cndmask_b32_e32 v71, v71, v73, vcc
	v_mul_f32_e32 v72, 0x3f3504f3, v59
	v_and_b32_e32 v74, 0x7fffffff, v72
	v_fmamk_f32 v75, v74, 0x378e98ab, v222
	v_fmaak_f32 v75, v74, v75, 0x3b7cd369
	v_fmaak_f32 v75, v74, v75, 0xbcc618b2
	v_fmaak_f32 v75, v74, v75, 0x3dda74e4
	v_fmaak_f32 v75, v74, v75, 0x3f228afd
	v_fmaak_f32 v75, v74, v75, 0x3e03c728
	v_fma_f32 v75, v74, v75, v74
	v_mul_f32_e32 v75, 0xbfb8aa3b, v75
	v_exp_f32_e32 v75, v75
	v_mul_f32_e32 v76, v72, v72
	v_sub_f32_e32 v75, 1.0, v75
	v_fmamk_f32 v73, v76, 0xba1345e1, v200
	v_fmaak_f32 v73, v76, v73, 0xbcdac9b8
	v_fmaak_f32 v73, v76, v73, 0x3de703be
	v_fmaak_f32 v73, v76, v73, 0xbec09330
	v_fmaak_f32 v73, v76, v73, 0x3e0375d0
	v_fma_f32 v73, v74, v73, v74
	v_cmp_ngt_f32_e32 vcc, 1.0, v74
	s_nop 1
	v_cndmask_b32_e32 v73, v73, v75, vcc
	v_mul_f32_e32 v74, 0x3f3504f3, v60
	v_and_b32_e32 v76, 0x7fffffff, v74
	v_fmamk_f32 v77, v76, 0x378e98ab, v222
	v_fmaak_f32 v77, v76, v77, 0x3b7cd369
	v_fmaak_f32 v77, v76, v77, 0xbcc618b2
	v_fmaak_f32 v77, v76, v77, 0x3dda74e4
	v_fmaak_f32 v77, v76, v77, 0x3f228afd
	v_fmaak_f32 v77, v76, v77, 0x3e03c728
	v_fma_f32 v77, v76, v77, v76
	v_mul_f32_e32 v77, 0xbfb8aa3b, v77
	v_exp_f32_e32 v77, v77
	v_mul_f32_e32 v78, v74, v74
	v_sub_f32_e32 v77, 1.0, v77
	v_fmamk_f32 v75, v78, 0xba1345e1, v200
	v_fmaak_f32 v75, v78, v75, 0xbcdac9b8
	v_fmaak_f32 v75, v78, v75, 0x3de703be
	v_fmaak_f32 v75, v78, v75, 0xbec09330
	v_fmaak_f32 v75, v78, v75, 0x3e0375d0
	v_fma_f32 v75, v76, v75, v76
	v_cmp_ngt_f32_e32 vcc, 1.0, v76
	s_nop 1
	v_cndmask_b32_e32 v75, v75, v77, vcc
	v_mul_f32_e32 v76, 0x3f3504f3, v61
	v_and_b32_e32 v78, 0x7fffffff, v76
	v_fmamk_f32 v79, v78, 0x378e98ab, v222
	v_fmaak_f32 v79, v78, v79, 0x3b7cd369
	v_fmaak_f32 v79, v78, v79, 0xbcc618b2
	v_fmaak_f32 v79, v78, v79, 0x3dda74e4
	v_fmaak_f32 v79, v78, v79, 0x3f228afd
	v_fmaak_f32 v79, v78, v79, 0x3e03c728
	v_fma_f32 v79, v78, v79, v78
	v_mul_f32_e32 v79, 0xbfb8aa3b, v79
	v_exp_f32_e32 v79, v79
	v_mul_f32_e32 v80, v76, v76
	v_sub_f32_e32 v79, 1.0, v79
	v_fmamk_f32 v77, v80, 0xba1345e1, v200
	v_fmaak_f32 v77, v80, v77, 0xbcdac9b8
	v_fmaak_f32 v77, v80, v77, 0x3de703be
	v_fmaak_f32 v77, v80, v77, 0xbec09330
	v_fmaak_f32 v77, v80, v77, 0x3e0375d0
	v_fma_f32 v77, v78, v77, v78
	v_cmp_ngt_f32_e32 vcc, 1.0, v78
	s_nop 1
	v_cndmask_b32_e32 v77, v77, v79, vcc
	v_bfi_b32 v74, s37, v75, v74
	v_mul_f32_e32 v60, 0.5, v60
	v_add_f32_e32 v74, 1.0, v74
	v_mul_f32_e32 v74, v60, v74
	v_bfi_b32 v60, s37, v73, v72
	v_mul_f32_e32 v59, 0.5, v59
	v_add_f32_e32 v60, 1.0, v60
	v_mul_f32_e32 v60, v59, v60
	v_bfi_b32 v59, s37, v71, v70
	v_readlane_b32 s6, v252, 33
	v_mul_f32_e32 v58, 0.5, v58
	v_add_f32_e32 v59, 1.0, v59
	v_readlane_b32 s7, v252, 34
	v_mul_f32_e32 v70, v58, v59
	v_mul_f32_e32 v61, 0.5, v61
	v_lshl_add_u64 v[58:59], s[6:7], 0, v[64:65]
	v_bfi_b32 v64, s37, v77, v76
	v_add_f32_e32 v64, 1.0, v64
	v_mul_f32_e32 v61, v61, v64
	v_lshl_add_u64 v[58:59], v[182:183], 1, v[58:59]
	v_cvt_pk_bf16_f32 v60, v70, v60
	v_cvt_pk_bf16_f32 v61, v74, v61
	global_store_dwordx2 v[58:59], v[60:61], off offset:-2048

; DI void st_bf4(u16* p, float a, float b, float c, float d) { *(uint2*)p = make_uint2(pk2(a, b), pk2(c, d)); }
; DI float gelu_f(float x) { return 0.5f * x * (1.f + erff(x * 0.70710678118654752f)); }
;   template <int NT, int MT> DI void run(f32x4 (&acc)[NT][MT], int mb, int nb) const {
;     ...
;         } else if (n < 3072) {
;           st_bf4(uvbuf + (size_t)m * 2048 + (n - 1024), gelu_f(v[0]), gelu_f(v[1]), gelu_f(v[2]), gelu_f(v[3]));
.LBB0_482:
	s_andn2_saveexec_b64 s[48:49], s[48:49]
	s_cbranch_execz .LBB0_500
	v_mul_f32_e32 v64, 0x3f3504f3, v54
	v_and_b32_e32 v70, 0x7fffffff, v64
	v_fmamk_f32 v71, v70, 0x378e98ab, v222
	v_fmaak_f32 v71, v70, v71, 0x3b7cd369
	v_fmaak_f32 v71, v70, v71, 0xbcc618b2
	v_fmaak_f32 v71, v70, v71, 0x3dda74e4
	v_fmaak_f32 v71, v70, v71, 0x3f228afd
	v_fmaak_f32 v71, v70, v71, 0x3e03c728
	v_fma_f32 v71, v70, v71, v70
	v_mul_f32_e32 v71, 0xbfb8aa3b, v71
	v_exp_f32_e32 v71, v71
	v_mul_f32_e32 v72, v64, v64
	v_sub_f32_e32 v71, 1.0, v71
	v_fmamk_f32 v65, v72, 0xba1345e1, v200
	v_fmaak_f32 v65, v72, v65, 0xbcdac9b8
	v_fmaak_f32 v65, v72, v65, 0x3de703be
	v_fmaak_f32 v65, v72, v65, 0xbec09330
	v_fmaak_f32 v65, v72, v65, 0x3e0375d0
	v_fma_f32 v65, v70, v65, v70
	v_cmp_ngt_f32_e32 vcc, 1.0, v70
	s_nop 1
	v_cndmask_b32_e32 v65, v65, v71, vcc
	v_mul_f32_e32 v70, 0x3f3504f3, v55
	v_and_b32_e32 v72, 0x7fffffff, v70
	v_fmamk_f32 v73, v72, 0x378e98ab, v222
	v_fmaak_f32 v73, v72, v73, 0x3b7cd369
	v_fmaak_f32 v73, v72, v73, 0xbcc618b2
	v_fmaak_f32 v73, v72, v73, 0x3dda74e4
	v_fmaak_f32 v73, v72, v73, 0x3f228afd
	v_fmaak_f32 v73, v72, v73, 0x3e03c728
	v_fma_f32 v73, v72, v73, v72
	v_mul_f32_e32 v73, 0xbfb8aa3b, v73
	v_exp_f32_e32 v73, v73
	v_mul_f32_e32 v74, v70, v70
	v_sub_f32_e32 v73, 1.0, v73
	v_fmamk_f32 v71, v74, 0xba1345e1, v200
	v_fmaak_f32 v71, v74, v71, 0xbcdac9b8
	v_fmaak_f32 v71, v74, v71, 0x3de703be
	v_fmaak_f32 v71, v74, v71, 0xbec09330
	v_fmaak_f32 v71, v74, v71, 0x3e0375d0
	v_fma_f32 v71, v72, v71, v72
	v_cmp_ngt_f32_e32 vcc, 1.0, v72
	s_nop 1
	v_cndmask_b32_e32 v71, v71, v73, vcc
	v_mul_f32_e32 v72, 0x3f3504f3, v56
	v_and_b32_e32 v74, 0x7fffffff, v72
	v_fmamk_f32 v75, v74, 0x378e98ab, v222
	v_fmaak_f32 v75, v74, v75, 0x3b7cd369
	v_fmaak_f32 v75, v74, v75, 0xbcc618b2
	v_fmaak_f32 v75, v74, v75, 0x3dda74e4
	v_fmaak_f32 v75, v74, v75, 0x3f228afd
	v_fmaak_f32 v75, v74, v75, 0x3e03c728
	v_fma_f32 v75, v74, v75, v74
	v_mul_f32_e32 v75, 0xbfb8aa3b, v75
	v_exp_f32_e32 v75, v75
	v_mul_f32_e32 v76, v72, v72
	v_sub_f32_e32 v75, 1.0, v75
	v_fmamk_f32 v73, v76, 0xba1345e1, v200
	v_fmaak_f32 v73, v76, v73, 0xbcdac9b8
	v_fmaak_f32 v73, v76, v73, 0x3de703be
	v_fmaak_f32 v73, v76, v73, 0xbec09330
	v_fmaak_f32 v73, v76, v73, 0x3e0375d0
	v_fma_f32 v73, v74, v73, v74
	v_cmp_ngt_f32_e32 vcc, 1.0, v74
	s_nop 1
	v_cndmask_b32_e32 v73, v73, v75, vcc
	v_mul_f32_e32 v74, 0x3f3504f3, v57
	v_and_b32_e32 v76, 0x7fffffff, v74
	v_fmamk_f32 v77, v76, 0x378e98ab, v222
	v_fmaak_f32 v77, v76, v77, 0x3b7cd369
	v_fmaak_f32 v77, v76, v77, 0xbcc618b2
	v_fmaak_f32 v77, v76, v77, 0x3dda74e4
	v_fmaak_f32 v77, v76, v77, 0x3f228afd
	v_fmaak_f32 v77, v76, v77, 0x3e03c728
	v_fma_f32 v77, v76, v77, v76
	v_mul_f32_e32 v77, 0xbfb8aa3b, v77
	v_exp_f32_e32 v77, v77
	v_mul_f32_e32 v78, v74, v74
	v_sub_f32_e32 v77, 1.0, v77
	v_fmamk_f32 v75, v78, 0xba1345e1, v200
	v_fmaak_f32 v75, v78, v75, 0xbcdac9b8
	v_fmaak_f32 v75, v78, v75, 0x3de703be
	v_fmaak_f32 v75, v78, v75, 0xbec09330
	v_fmaak_f32 v75, v78, v75, 0x3e0375d0
	v_fma_f32 v75, v76, v75, v76
	v_cmp_ngt_f32_e32 vcc, 1.0, v76
	s_nop 1
	v_cndmask_b32_e32 v75, v75, v77, vcc
	v_bfi_b32 v72, s37, v73, v72
	v_mul_f32_e32 v56, 0.5, v56
	v_add_f32_e32 v72, 1.0, v72
	v_mul_f32_e32 v72, v56, v72
	v_bfi_b32 v56, s37, v71, v70
	v_mul_f32_e32 v55, 0.5, v55
	v_add_f32_e32 v56, 1.0, v56
	v_mul_f32_e32 v56, v55, v56
	v_bfi_b32 v55, s37, v65, v64
	v_readlane_b32 s6, v252, 33
	v_mul_f32_e32 v54, 0.5, v54
	v_add_f32_e32 v55, 1.0, v55
	v_readlane_b32 s7, v252, 34
	v_mul_f32_e32 v64, v54, v55
	v_mul_f32_e32 v57, 0.5, v57
	v_lshl_add_u64 v[54:55], s[6:7], 0, v[60:61]
	v_bfi_b32 v60, s37, v75, v74
	v_add_f32_e32 v60, 1.0, v60
	v_mul_f32_e32 v57, v57, v60
	v_lshl_add_u64 v[54:55], v[182:183], 1, v[54:55]
	v_cvt_pk_bf16_f32 v56, v64, v56
	v_cvt_pk_bf16_f32 v57, v72, v57
	global_store_dwordx2 v[54:55], v[56:57], off offset:-2048

; DI void st_bf4(u16* p, float a, float b, float c, float d) { *(uint2*)p = make_uint2(pk2(a, b), pk2(c, d)); }
; DI float gelu_f(float x) { return 0.5f * x * (1.f + erff(x * 0.70710678118654752f)); }
;   template <int NT, int MT> DI void run(f32x4 (&acc)[NT][MT], int mb, int nb) const {
;     ...
;         } else if (n < 3072) {
;           st_bf4(uvbuf + (size_t)m * 2048 + (n - 1024), gelu_f(v[0]), gelu_f(v[1]), gelu_f(v[2]), gelu_f(v[3]));
.LBB0_506:
	s_andn2_saveexec_b64 s[46:47], s[46:47]
	s_cbranch_execz .LBB0_524
	v_mul_f32_e32 v60, 0x3f3504f3, v50
	v_and_b32_e32 v64, 0x7fffffff, v60
	v_fmamk_f32 v65, v64, 0x378e98ab, v222
	v_fmaak_f32 v65, v64, v65, 0x3b7cd369
	v_fmaak_f32 v65, v64, v65, 0xbcc618b2
	v_fmaak_f32 v65, v64, v65, 0x3dda74e4
	v_fmaak_f32 v65, v64, v65, 0x3f228afd
	v_fmaak_f32 v65, v64, v65, 0x3e03c728
	v_fma_f32 v65, v64, v65, v64
	v_mul_f32_e32 v65, 0xbfb8aa3b, v65
	v_exp_f32_e32 v65, v65
	v_mul_f32_e32 v70, v60, v60
	v_sub_f32_e32 v65, 1.0, v65
	v_fmamk_f32 v61, v70, 0xba1345e1, v200
	v_fmaak_f32 v61, v70, v61, 0xbcdac9b8
	v_fmaak_f32 v61, v70, v61, 0x3de703be
	v_fmaak_f32 v61, v70, v61, 0xbec09330
	v_fmaak_f32 v61, v70, v61, 0x3e0375d0
	v_fma_f32 v61, v64, v61, v64
	v_cmp_ngt_f32_e32 vcc, 1.0, v64
	s_nop 1
	v_cndmask_b32_e32 v61, v61, v65, vcc
	v_mul_f32_e32 v64, 0x3f3504f3, v51
	v_and_b32_e32 v70, 0x7fffffff, v64
	v_fmamk_f32 v71, v70, 0x378e98ab, v222
	v_fmaak_f32 v71, v70, v71, 0x3b7cd369
	v_fmaak_f32 v71, v70, v71, 0xbcc618b2
	v_fmaak_f32 v71, v70, v71, 0x3dda74e4
	v_fmaak_f32 v71, v70, v71, 0x3f228afd
	v_fmaak_f32 v71, v70, v71, 0x3e03c728
	v_fma_f32 v71, v70, v71, v70
	v_mul_f32_e32 v71, 0xbfb8aa3b, v71
	v_exp_f32_e32 v71, v71
	v_mul_f32_e32 v72, v64, v64
	v_sub_f32_e32 v71, 1.0, v71
	v_fmamk_f32 v65, v72, 0xba1345e1, v200
	v_fmaak_f32 v65, v72, v65, 0xbcdac9b8
	v_fmaak_f32 v65, v72, v65, 0x3de703be
	v_fmaak_f32 v65, v72, v65, 0xbec09330
	v_fmaak_f32 v65, v72, v65, 0x3e0375d0
	v_fma_f32 v65, v70, v65, v70
	v_cmp_ngt_f32_e32 vcc, 1.0, v70
	s_nop 1
	v_cndmask_b32_e32 v65, v65, v71, vcc
	v_mul_f32_e32 v70, 0x3f3504f3, v52
	v_and_b32_e32 v72, 0x7fffffff, v70
	v_fmamk_f32 v73, v72, 0x378e98ab, v222
	v_fmaak_f32 v73, v72, v73, 0x3b7cd369
	v_fmaak_f32 v73, v72, v73, 0xbcc618b2
	v_fmaak_f32 v73, v72, v73, 0x3dda74e4
	v_fmaak_f32 v73, v72, v73, 0x3f228afd
	v_fmaak_f32 v73, v72, v73, 0x3e03c728
	v_fma_f32 v73, v72, v73, v72
	v_mul_f32_e32 v73, 0xbfb8aa3b, v73
	v_exp_f32_e32 v73, v73
	v_mul_f32_e32 v74, v70, v70
	v_sub_f32_e32 v73, 1.0, v73
	v_fmamk_f32 v71, v74, 0xba1345e1, v200
	v_fmaak_f32 v71, v74, v71, 0xbcdac9b8
	v_fmaak_f32 v71, v74, v71, 0x3de703be
	v_fmaak_f32 v71, v74, v71, 0xbec09330
	v_fmaak_f32 v71, v74, v71, 0x3e0375d0
	v_fma_f32 v71, v72, v71, v72
	v_cmp_ngt_f32_e32 vcc, 1.0, v72
	s_nop 1
	v_cndmask_b32_e32 v71, v71, v73, vcc
	v_mul_f32_e32 v72, 0x3f3504f3, v53
	v_and_b32_e32 v74, 0x7fffffff, v72
	v_fmamk_f32 v75, v74, 0x378e98ab, v222
	v_fmaak_f32 v75, v74, v75, 0x3b7cd369
	v_fmaak_f32 v75, v74, v75, 0xbcc618b2
	v_fmaak_f32 v75, v74, v75, 0x3dda74e4
	v_fmaak_f32 v75, v74, v75, 0x3f228afd
	v_fmaak_f32 v75, v74, v75, 0x3e03c728
	v_fma_f32 v75, v74, v75, v74
	v_mul_f32_e32 v75, 0xbfb8aa3b, v75
	v_exp_f32_e32 v75, v75
	v_mul_f32_e32 v76, v72, v72
	v_sub_f32_e32 v75, 1.0, v75
	v_fmamk_f32 v73, v76, 0xba1345e1, v200
	v_fmaak_f32 v73, v76, v73, 0xbcdac9b8
	v_fmaak_f32 v73, v76, v73, 0x3de703be
	v_fmaak_f32 v73, v76, v73, 0xbec09330
	v_fmaak_f32 v73, v76, v73, 0x3e0375d0
	v_fma_f32 v73, v74, v73, v74
	v_cmp_ngt_f32_e32 vcc, 1.0, v74
	s_nop 1
	v_cndmask_b32_e32 v73, v73, v75, vcc
	v_bfi_b32 v70, s37, v71, v70
	v_mul_f32_e32 v52, 0.5, v52
	v_add_f32_e32 v70, 1.0, v70
	v_mul_f32_e32 v70, v52, v70
	v_bfi_b32 v52, s37, v65, v64
	v_mul_f32_e32 v51, 0.5, v51
	v_add_f32_e32 v52, 1.0, v52
	v_mul_f32_e32 v52, v51, v52
	v_bfi_b32 v51, s37, v61, v60
	v_readlane_b32 s6, v252, 33
	v_mul_f32_e32 v50, 0.5, v50
	v_add_f32_e32 v51, 1.0, v51
	v_readlane_b32 s7, v252, 34
	v_mul_f32_e32 v60, v50, v51
	v_mul_f32_e32 v53, 0.5, v53
	v_lshl_add_u64 v[50:51], s[6:7], 0, v[56:57]
	v_bfi_b32 v56, s37, v73, v72
	v_add_f32_e32 v56, 1.0, v56
	v_mul_f32_e32 v53, v53, v56
	v_lshl_add_u64 v[50:51], v[182:183], 1, v[50:51]
	v_cvt_pk_bf16_f32 v52, v60, v52
	v_cvt_pk_bf16_f32 v53, v70, v53
	global_store_dwordx2 v[50:51], v[52:53], off offset:-2048

; DI void st_bf4(u16* p, float a, float b, float c, float d) { *(uint2*)p = make_uint2(pk2(a, b), pk2(c, d)); }
; DI float gelu_f(float x) { return 0.5f * x * (1.f + erff(x * 0.70710678118654752f)); }
;   template <int NT, int MT> DI void run(f32x4 (&acc)[NT][MT], int mb, int nb) const {
;     ...
;         } else if (n < 3072) {
;           st_bf4(uvbuf + (size_t)m * 2048 + (n - 1024), gelu_f(v[0]), gelu_f(v[1]), gelu_f(v[2]), gelu_f(v[3]));
.LBB0_536:
	s_andn2_saveexec_b64 s[48:49], s[48:49]
	s_cbranch_execz .LBB0_554
	v_mul_f32_e32 v52, 0x3f3504f3, v46
	v_and_b32_e32 v56, 0x7fffffff, v52
	v_fmamk_f32 v57, v56, 0x378e98ab, v222
	v_fmaak_f32 v57, v56, v57, 0x3b7cd369
	v_fmaak_f32 v57, v56, v57, 0xbcc618b2
	v_fmaak_f32 v57, v56, v57, 0x3dda74e4
	v_fmaak_f32 v57, v56, v57, 0x3f228afd
	v_fmaak_f32 v57, v56, v57, 0x3e03c728
	v_fma_f32 v57, v56, v57, v56
	v_mul_f32_e32 v57, 0xbfb8aa3b, v57
	v_exp_f32_e32 v57, v57
	v_mul_f32_e32 v60, v52, v52
	v_sub_f32_e32 v57, 1.0, v57
	v_fmamk_f32 v53, v60, 0xba1345e1, v200
	v_fmaak_f32 v53, v60, v53, 0xbcdac9b8
	v_fmaak_f32 v53, v60, v53, 0x3de703be
	v_fmaak_f32 v53, v60, v53, 0xbec09330
	v_fmaak_f32 v53, v60, v53, 0x3e0375d0
	v_fma_f32 v53, v56, v53, v56
	v_cmp_ngt_f32_e32 vcc, 1.0, v56
	s_nop 1
	v_cndmask_b32_e32 v53, v53, v57, vcc
	v_mul_f32_e32 v56, 0x3f3504f3, v47
	v_and_b32_e32 v60, 0x7fffffff, v56
	v_fmamk_f32 v61, v60, 0x378e98ab, v222
	v_fmaak_f32 v61, v60, v61, 0x3b7cd369
	v_fmaak_f32 v61, v60, v61, 0xbcc618b2
	v_fmaak_f32 v61, v60, v61, 0x3dda74e4
	v_fmaak_f32 v61, v60, v61, 0x3f228afd
	v_fmaak_f32 v61, v60, v61, 0x3e03c728
	v_fma_f32 v61, v60, v61, v60
	v_mul_f32_e32 v61, 0xbfb8aa3b, v61
	v_exp_f32_e32 v61, v61
	v_mul_f32_e32 v64, v56, v56
	v_sub_f32_e32 v61, 1.0, v61
	v_fmamk_f32 v57, v64, 0xba1345e1, v200
	v_fmaak_f32 v57, v64, v57, 0xbcdac9b8
	v_fmaak_f32 v57, v64, v57, 0x3de703be
	v_fmaak_f32 v57, v64, v57, 0xbec09330
	v_fmaak_f32 v57, v64, v57, 0x3e0375d0
	v_fma_f32 v57, v60, v57, v60
	v_cmp_ngt_f32_e32 vcc, 1.0, v60
	s_nop 1
	v_cndmask_b32_e32 v57, v57, v61, vcc
	v_mul_f32_e32 v60, 0x3f3504f3, v48
	v_and_b32_e32 v64, 0x7fffffff, v60
	v_fmamk_f32 v65, v64, 0x378e98ab, v222
	v_fmaak_f32 v65, v64, v65, 0x3b7cd369
	v_fmaak_f32 v65, v64, v65, 0xbcc618b2
	v_fmaak_f32 v65, v64, v65, 0x3dda74e4
	v_fmaak_f32 v65, v64, v65, 0x3f228afd
	v_fmaak_f32 v65, v64, v65, 0x3e03c728
	v_fma_f32 v65, v64, v65, v64
	v_mul_f32_e32 v65, 0xbfb8aa3b, v65
	v_exp_f32_e32 v65, v65
	v_mul_f32_e32 v70, v60, v60
	v_sub_f32_e32 v65, 1.0, v65
	v_fmamk_f32 v61, v70, 0xba1345e1, v200
	v_fmaak_f32 v61, v70, v61, 0xbcdac9b8
	v_fmaak_f32 v61, v70, v61, 0x3de703be
	v_fmaak_f32 v61, v70, v61, 0xbec09330
	v_fmaak_f32 v61, v70, v61, 0x3e0375d0
	v_fma_f32 v61, v64, v61, v64
	v_cmp_ngt_f32_e32 vcc, 1.0, v64
	s_nop 1
	v_cndmask_b32_e32 v61, v61, v65, vcc
	v_mul_f32_e32 v64, 0x3f3504f3, v49
	v_and_b32_e32 v70, 0x7fffffff, v64
	v_fmamk_f32 v71, v70, 0x378e98ab, v222
	v_fmaak_f32 v71, v70, v71, 0x3b7cd369
	v_fmaak_f32 v71, v70, v71, 0xbcc618b2
	v_fmaak_f32 v71, v70, v71, 0x3dda74e4
	v_fmaak_f32 v71, v70, v71, 0x3f228afd
	v_fmaak_f32 v71, v70, v71, 0x3e03c728
	v_fma_f32 v71, v70, v71, v70
	v_mul_f32_e32 v71, 0xbfb8aa3b, v71
	v_exp_f32_e32 v71, v71
	v_mul_f32_e32 v72, v64, v64
	v_sub_f32_e32 v71, 1.0, v71
	v_fmamk_f32 v65, v72, 0xba1345e1, v200
	v_fmaak_f32 v65, v72, v65, 0xbcdac9b8
	v_fmaak_f32 v65, v72, v65, 0x3de703be
	v_fmaak_f32 v65, v72, v65, 0xbec09330
	v_fmaak_f32 v65, v72, v65, 0x3e0375d0
	v_fma_f32 v65, v70, v65, v70
	v_cmp_ngt_f32_e32 vcc, 1.0, v70
	s_nop 1
	v_cndmask_b32_e32 v65, v65, v71, vcc
	v_bfi_b32 v60, s37, v61, v60
	v_mul_f32_e32 v48, 0.5, v48
	v_add_f32_e32 v60, 1.0, v60
	v_mul_f32_e32 v60, v48, v60
	v_bfi_b32 v48, s37, v57, v56
	v_mul_f32_e32 v47, 0.5, v47
	v_add_f32_e32 v48, 1.0, v48
	v_mul_f32_e32 v48, v47, v48
	v_bfi_b32 v47, s37, v53, v52
	v_readlane_b32 s6, v252, 33
	v_mul_f32_e32 v46, 0.5, v46
	v_add_f32_e32 v47, 1.0, v47
	v_readlane_b32 s7, v252, 34
	v_mul_f32_e32 v52, v46, v47
	v_mul_f32_e32 v49, 0.5, v49
	v_lshl_add_u64 v[46:47], s[6:7], 0, v[50:51]
	v_bfi_b32 v50, s37, v65, v64
	v_add_f32_e32 v50, 1.0, v50
	v_mul_f32_e32 v49, v49, v50
	v_lshl_add_u64 v[46:47], v[182:183], 1, v[46:47]
	v_cvt_pk_bf16_f32 v48, v52, v48
	v_cvt_pk_bf16_f32 v49, v60, v49
	global_store_dwordx2 v[46:47], v[48:49], off offset:-2016

; DI void st_bf4(u16* p, float a, float b, float c, float d) { *(uint2*)p = make_uint2(pk2(a, b), pk2(c, d)); }
; DI float gelu_f(float x) { return 0.5f * x * (1.f + erff(x * 0.70710678118654752f)); }
;   template <int NT, int MT> DI void run(f32x4 (&acc)[NT][MT], int mb, int nb) const {
;     ...
;         } else if (n < 3072) {
;           st_bf4(uvbuf + (size_t)m * 2048 + (n - 1024), gelu_f(v[0]), gelu_f(v[1]), gelu_f(v[2]), gelu_f(v[3]));
.LBB0_560:
	s_andn2_saveexec_b64 s[48:49], s[48:49]
	s_cbranch_execz .LBB0_578
	v_mul_f32_e32 v48, 0x3f3504f3, v42
	v_and_b32_e32 v50, 0x7fffffff, v48
	v_fmamk_f32 v51, v50, 0x378e98ab, v222
	v_fmaak_f32 v51, v50, v51, 0x3b7cd369
	v_fmaak_f32 v51, v50, v51, 0xbcc618b2
	v_fmaak_f32 v51, v50, v51, 0x3dda74e4
	v_fmaak_f32 v51, v50, v51, 0x3f228afd
	v_fmaak_f32 v51, v50, v51, 0x3e03c728
	v_fma_f32 v51, v50, v51, v50
	v_mul_f32_e32 v51, 0xbfb8aa3b, v51
	v_exp_f32_e32 v51, v51
	v_mul_f32_e32 v52, v48, v48
	v_sub_f32_e32 v51, 1.0, v51
	v_fmamk_f32 v49, v52, 0xba1345e1, v200
	v_fmaak_f32 v49, v52, v49, 0xbcdac9b8
	v_fmaak_f32 v49, v52, v49, 0x3de703be
	v_fmaak_f32 v49, v52, v49, 0xbec09330
	v_fmaak_f32 v49, v52, v49, 0x3e0375d0
	v_fma_f32 v49, v50, v49, v50
	v_cmp_ngt_f32_e32 vcc, 1.0, v50
	s_nop 1
	v_cndmask_b32_e32 v49, v49, v51, vcc
	v_mul_f32_e32 v50, 0x3f3504f3, v43
	v_and_b32_e32 v52, 0x7fffffff, v50
	v_fmamk_f32 v53, v52, 0x378e98ab, v222
	v_fmaak_f32 v53, v52, v53, 0x3b7cd369
	v_fmaak_f32 v53, v52, v53, 0xbcc618b2
	v_fmaak_f32 v53, v52, v53, 0x3dda74e4
	v_fmaak_f32 v53, v52, v53, 0x3f228afd
	v_fmaak_f32 v53, v52, v53, 0x3e03c728
	v_fma_f32 v53, v52, v53, v52
	v_mul_f32_e32 v53, 0xbfb8aa3b, v53
	v_exp_f32_e32 v53, v53
	v_mul_f32_e32 v56, v50, v50
	v_sub_f32_e32 v53, 1.0, v53
	v_fmamk_f32 v51, v56, 0xba1345e1, v200
	v_fmaak_f32 v51, v56, v51, 0xbcdac9b8
	v_fmaak_f32 v51, v56, v51, 0x3de703be
	v_fmaak_f32 v51, v56, v51, 0xbec09330
	v_fmaak_f32 v51, v56, v51, 0x3e0375d0
	v_fma_f32 v51, v52, v51, v52
	v_cmp_ngt_f32_e32 vcc, 1.0, v52
	s_nop 1
	v_cndmask_b32_e32 v51, v51, v53, vcc
	v_mul_f32_e32 v52, 0x3f3504f3, v44
	v_and_b32_e32 v56, 0x7fffffff, v52
	v_fmamk_f32 v57, v56, 0x378e98ab, v222
	v_fmaak_f32 v57, v56, v57, 0x3b7cd369
	v_fmaak_f32 v57, v56, v57, 0xbcc618b2
	v_fmaak_f32 v57, v56, v57, 0x3dda74e4
	v_fmaak_f32 v57, v56, v57, 0x3f228afd
	v_fmaak_f32 v57, v56, v57, 0x3e03c728
	v_fma_f32 v57, v56, v57, v56
	v_mul_f32_e32 v57, 0xbfb8aa3b, v57
	v_exp_f32_e32 v57, v57
	v_mul_f32_e32 v60, v52, v52
	v_sub_f32_e32 v57, 1.0, v57
	v_fmamk_f32 v53, v60, 0xba1345e1, v200
	v_fmaak_f32 v53, v60, v53, 0xbcdac9b8
	v_fmaak_f32 v53, v60, v53, 0x3de703be
	v_fmaak_f32 v53, v60, v53, 0xbec09330
	v_fmaak_f32 v53, v60, v53, 0x3e0375d0
	v_fma_f32 v53, v56, v53, v56
	v_cmp_ngt_f32_e32 vcc, 1.0, v56
	s_nop 1
	v_cndmask_b32_e32 v53, v53, v57, vcc
	v_mul_f32_e32 v56, 0x3f3504f3, v45
	v_and_b32_e32 v60, 0x7fffffff, v56
	v_fmamk_f32 v61, v60, 0x378e98ab, v222
	v_fmaak_f32 v61, v60, v61, 0x3b7cd369
	v_fmaak_f32 v61, v60, v61, 0xbcc618b2
	v_fmaak_f32 v61, v60, v61, 0x3dda74e4
	v_fmaak_f32 v61, v60, v61, 0x3f228afd
	v_fmaak_f32 v61, v60, v61, 0x3e03c728
	v_fma_f32 v61, v60, v61, v60
	v_mul_f32_e32 v61, 0xbfb8aa3b, v61
	v_exp_f32_e32 v61, v61
	v_mul_f32_e32 v64, v56, v56
	v_sub_f32_e32 v61, 1.0, v61
	v_fmamk_f32 v57, v64, 0xba1345e1, v200
	v_fmaak_f32 v57, v64, v57, 0xbcdac9b8
	v_fmaak_f32 v57, v64, v57, 0x3de703be
	v_fmaak_f32 v57, v64, v57, 0xbec09330
	v_fmaak_f32 v57, v64, v57, 0x3e0375d0
	v_fma_f32 v57, v60, v57, v60
	v_cmp_ngt_f32_e32 vcc, 1.0, v60
	s_nop 1
	v_cndmask_b32_e32 v57, v57, v61, vcc
	v_bfi_b32 v52, s37, v53, v52
	v_mul_f32_e32 v44, 0.5, v44
	v_add_f32_e32 v52, 1.0, v52
	v_mul_f32_e32 v52, v44, v52
	v_bfi_b32 v44, s37, v51, v50
	v_mul_f32_e32 v43, 0.5, v43
	v_add_f32_e32 v44, 1.0, v44
	v_mul_f32_e32 v44, v43, v44
	v_bfi_b32 v43, s37, v49, v48
	v_readlane_b32 s6, v252, 33
	v_mul_f32_e32 v42, 0.5, v42
	v_add_f32_e32 v43, 1.0, v43
	v_readlane_b32 s7, v252, 34
	v_mul_f32_e32 v48, v42, v43
	v_mul_f32_e32 v45, 0.5, v45
	v_lshl_add_u64 v[42:43], s[6:7], 0, v[46:47]
	v_bfi_b32 v46, s37, v57, v56
	v_add_f32_e32 v46, 1.0, v46
	v_mul_f32_e32 v45, v45, v46
	v_lshl_add_u64 v[42:43], v[182:183], 1, v[42:43]
	v_cvt_pk_bf16_f32 v44, v48, v44
	v_cvt_pk_bf16_f32 v45, v52, v45
	global_store_dwordx2 v[42:43], v[44:45], off offset:-2016

; DI void st_bf4(u16* p, float a, float b, float c, float d) { *(uint2*)p = make_uint2(pk2(a, b), pk2(c, d)); }
; DI float gelu_f(float x) { return 0.5f * x * (1.f + erff(x * 0.70710678118654752f)); }
;   template <int NT, int MT> DI void run(f32x4 (&acc)[NT][MT], int mb, int nb) const {
;     ...
;         } else if (n < 3072) {
;           st_bf4(uvbuf + (size_t)m * 2048 + (n - 1024), gelu_f(v[0]), gelu_f(v[1]), gelu_f(v[2]), gelu_f(v[3]));
.LBB0_590:
	s_andn2_saveexec_b64 s[48:49], s[48:49]
	s_cbranch_execz .LBB0_608
	v_mul_f32_e32 v44, 0x3f3504f3, v38
	v_and_b32_e32 v46, 0x7fffffff, v44
	v_fmamk_f32 v47, v46, 0x378e98ab, v222
	v_fmaak_f32 v47, v46, v47, 0x3b7cd369
	v_fmaak_f32 v47, v46, v47, 0xbcc618b2
	v_fmaak_f32 v47, v46, v47, 0x3dda74e4
	v_fmaak_f32 v47, v46, v47, 0x3f228afd
	v_fmaak_f32 v47, v46, v47, 0x3e03c728
	v_fma_f32 v47, v46, v47, v46
	v_mul_f32_e32 v47, 0xbfb8aa3b, v47
	v_exp_f32_e32 v47, v47
	v_mul_f32_e32 v48, v44, v44
	v_sub_f32_e32 v47, 1.0, v47
	v_fmamk_f32 v45, v48, 0xba1345e1, v200
	v_fmaak_f32 v45, v48, v45, 0xbcdac9b8
	v_fmaak_f32 v45, v48, v45, 0x3de703be
	v_fmaak_f32 v45, v48, v45, 0xbec09330
	v_fmaak_f32 v45, v48, v45, 0x3e0375d0
	v_fma_f32 v45, v46, v45, v46
	v_cmp_ngt_f32_e32 vcc, 1.0, v46
	s_nop 1
	v_cndmask_b32_e32 v45, v45, v47, vcc
	v_mul_f32_e32 v46, 0x3f3504f3, v39
	v_and_b32_e32 v48, 0x7fffffff, v46
	v_fmamk_f32 v49, v48, 0x378e98ab, v222
	v_fmaak_f32 v49, v48, v49, 0x3b7cd369
	v_fmaak_f32 v49, v48, v49, 0xbcc618b2
	v_fmaak_f32 v49, v48, v49, 0x3dda74e4
	v_fmaak_f32 v49, v48, v49, 0x3f228afd
	v_fmaak_f32 v49, v48, v49, 0x3e03c728
	v_fma_f32 v49, v48, v49, v48
	v_mul_f32_e32 v49, 0xbfb8aa3b, v49
	v_exp_f32_e32 v49, v49
	v_mul_f32_e32 v50, v46, v46
	v_sub_f32_e32 v49, 1.0, v49
	v_fmamk_f32 v47, v50, 0xba1345e1, v200
	v_fmaak_f32 v47, v50, v47, 0xbcdac9b8
	v_fmaak_f32 v47, v50, v47, 0x3de703be
	v_fmaak_f32 v47, v50, v47, 0xbec09330
	v_fmaak_f32 v47, v50, v47, 0x3e0375d0
	v_fma_f32 v47, v48, v47, v48
	v_cmp_ngt_f32_e32 vcc, 1.0, v48
	s_nop 1
	v_cndmask_b32_e32 v47, v47, v49, vcc
	v_mul_f32_e32 v48, 0x3f3504f3, v40
	v_and_b32_e32 v50, 0x7fffffff, v48
	v_fmamk_f32 v51, v50, 0x378e98ab, v222
	v_fmaak_f32 v51, v50, v51, 0x3b7cd369
	v_fmaak_f32 v51, v50, v51, 0xbcc618b2
	v_fmaak_f32 v51, v50, v51, 0x3dda74e4
	v_fmaak_f32 v51, v50, v51, 0x3f228afd
	v_fmaak_f32 v51, v50, v51, 0x3e03c728
	v_fma_f32 v51, v50, v51, v50
	v_mul_f32_e32 v51, 0xbfb8aa3b, v51
	v_exp_f32_e32 v51, v51
	v_mul_f32_e32 v52, v48, v48
	v_sub_f32_e32 v51, 1.0, v51
	v_fmamk_f32 v49, v52, 0xba1345e1, v200
	v_fmaak_f32 v49, v52, v49, 0xbcdac9b8
	v_fmaak_f32 v49, v52, v49, 0x3de703be
	v_fmaak_f32 v49, v52, v49, 0xbec09330
	v_fmaak_f32 v49, v52, v49, 0x3e0375d0
	v_fma_f32 v49, v50, v49, v50
	v_cmp_ngt_f32_e32 vcc, 1.0, v50
	s_nop 1
	v_cndmask_b32_e32 v49, v49, v51, vcc
	v_mul_f32_e32 v50, 0x3f3504f3, v41
	v_and_b32_e32 v52, 0x7fffffff, v50
	v_fmamk_f32 v53, v52, 0x378e98ab, v222
	v_fmaak_f32 v53, v52, v53, 0x3b7cd369
	v_fmaak_f32 v53, v52, v53, 0xbcc618b2
	v_fmaak_f32 v53, v52, v53, 0x3dda74e4
	v_fmaak_f32 v53, v52, v53, 0x3f228afd
	v_fmaak_f32 v53, v52, v53, 0x3e03c728
	v_fma_f32 v53, v52, v53, v52
	v_mul_f32_e32 v53, 0xbfb8aa3b, v53
	v_exp_f32_e32 v53, v53
	v_mul_f32_e32 v56, v50, v50
	v_sub_f32_e32 v53, 1.0, v53
	v_fmamk_f32 v51, v56, 0xba1345e1, v200
	v_fmaak_f32 v51, v56, v51, 0xbcdac9b8
	v_fmaak_f32 v51, v56, v51, 0x3de703be
	v_fmaak_f32 v51, v56, v51, 0xbec09330
	v_fmaak_f32 v51, v56, v51, 0x3e0375d0
	v_fma_f32 v51, v52, v51, v52
	v_cmp_ngt_f32_e32 vcc, 1.0, v52
	s_nop 1
	v_cndmask_b32_e32 v51, v51, v53, vcc
	v_bfi_b32 v48, s37, v49, v48
	v_mul_f32_e32 v40, 0.5, v40
	v_add_f32_e32 v48, 1.0, v48
	v_mul_f32_e32 v48, v40, v48
	v_bfi_b32 v40, s37, v47, v46
	v_mul_f32_e32 v39, 0.5, v39
	v_add_f32_e32 v40, 1.0, v40
	v_mul_f32_e32 v40, v39, v40
	v_bfi_b32 v39, s37, v45, v44
	v_readlane_b32 s6, v252, 33
	v_mul_f32_e32 v38, 0.5, v38
	v_add_f32_e32 v39, 1.0, v39
	v_readlane_b32 s7, v252, 34
	v_mul_f32_e32 v44, v38, v39
	v_mul_f32_e32 v41, 0.5, v41
	v_lshl_add_u64 v[38:39], s[6:7], 0, v[42:43]
	v_bfi_b32 v42, s37, v51, v50
	v_add_f32_e32 v42, 1.0, v42
	v_mul_f32_e32 v41, v41, v42
	v_lshl_add_u64 v[38:39], v[182:183], 1, v[38:39]
	v_cvt_pk_bf16_f32 v40, v44, v40
	v_cvt_pk_bf16_f32 v41, v48, v41
	global_store_dwordx2 v[38:39], v[40:41], off offset:-2016

; DI void st_bf4(u16* p, float a, float b, float c, float d) { *(uint2*)p = make_uint2(pk2(a, b), pk2(c, d)); }
; DI float gelu_f(float x) { return 0.5f * x * (1.f + erff(x * 0.70710678118654752f)); }
;   template <int NT, int MT> DI void run(f32x4 (&acc)[NT][MT], int mb, int nb) const {
;     ...
;         } else if (n < 3072) {
;           st_bf4(uvbuf + (size_t)m * 2048 + (n - 1024), gelu_f(v[0]), gelu_f(v[1]), gelu_f(v[2]), gelu_f(v[3]));
.LBB0_614:
	s_andn2_saveexec_b64 s[46:47], s[46:47]
	s_cbranch_execz .LBB0_632
	v_mul_f32_e32 v40, 0x3f3504f3, v34
	v_and_b32_e32 v42, 0x7fffffff, v40
	v_fmamk_f32 v43, v42, 0x378e98ab, v222
	v_fmaak_f32 v43, v42, v43, 0x3b7cd369
	v_fmaak_f32 v43, v42, v43, 0xbcc618b2
	v_fmaak_f32 v43, v42, v43, 0x3dda74e4
	v_fmaak_f32 v43, v42, v43, 0x3f228afd
	v_fmaak_f32 v43, v42, v43, 0x3e03c728
	v_fma_f32 v43, v42, v43, v42
	v_mul_f32_e32 v43, 0xbfb8aa3b, v43
	v_exp_f32_e32 v43, v43
	v_mul_f32_e32 v44, v40, v40
	v_sub_f32_e32 v43, 1.0, v43
	v_fmamk_f32 v41, v44, 0xba1345e1, v200
	v_fmaak_f32 v41, v44, v41, 0xbcdac9b8
	v_fmaak_f32 v41, v44, v41, 0x3de703be
	v_fmaak_f32 v41, v44, v41, 0xbec09330
	v_fmaak_f32 v41, v44, v41, 0x3e0375d0
	v_fma_f32 v41, v42, v41, v42
	v_cmp_ngt_f32_e32 vcc, 1.0, v42
	s_nop 1
	v_cndmask_b32_e32 v41, v41, v43, vcc
	v_mul_f32_e32 v42, 0x3f3504f3, v35
	v_and_b32_e32 v44, 0x7fffffff, v42
	v_fmamk_f32 v45, v44, 0x378e98ab, v222
	v_fmaak_f32 v45, v44, v45, 0x3b7cd369
	v_fmaak_f32 v45, v44, v45, 0xbcc618b2
	v_fmaak_f32 v45, v44, v45, 0x3dda74e4
	v_fmaak_f32 v45, v44, v45, 0x3f228afd
	v_fmaak_f32 v45, v44, v45, 0x3e03c728
	v_fma_f32 v45, v44, v45, v44
	v_mul_f32_e32 v45, 0xbfb8aa3b, v45
	v_exp_f32_e32 v45, v45
	v_mul_f32_e32 v46, v42, v42
	v_sub_f32_e32 v45, 1.0, v45
	v_fmamk_f32 v43, v46, 0xba1345e1, v200
	v_fmaak_f32 v43, v46, v43, 0xbcdac9b8
	v_fmaak_f32 v43, v46, v43, 0x3de703be
	v_fmaak_f32 v43, v46, v43, 0xbec09330
	v_fmaak_f32 v43, v46, v43, 0x3e0375d0
	v_fma_f32 v43, v44, v43, v44
	v_cmp_ngt_f32_e32 vcc, 1.0, v44
	s_nop 1
	v_cndmask_b32_e32 v43, v43, v45, vcc
	v_mul_f32_e32 v44, 0x3f3504f3, v36
	v_and_b32_e32 v46, 0x7fffffff, v44
	v_fmamk_f32 v47, v46, 0x378e98ab, v222
	v_fmaak_f32 v47, v46, v47, 0x3b7cd369
	v_fmaak_f32 v47, v46, v47, 0xbcc618b2
	v_fmaak_f32 v47, v46, v47, 0x3dda74e4
	v_fmaak_f32 v47, v46, v47, 0x3f228afd
	v_fmaak_f32 v47, v46, v47, 0x3e03c728
	v_fma_f32 v47, v46, v47, v46
	v_mul_f32_e32 v47, 0xbfb8aa3b, v47
	v_exp_f32_e32 v47, v47
	v_mul_f32_e32 v48, v44, v44
	v_sub_f32_e32 v47, 1.0, v47
	v_fmamk_f32 v45, v48, 0xba1345e1, v200
	v_fmaak_f32 v45, v48, v45, 0xbcdac9b8
	v_fmaak_f32 v45, v48, v45, 0x3de703be
	v_fmaak_f32 v45, v48, v45, 0xbec09330
	v_fmaak_f32 v45, v48, v45, 0x3e0375d0
	v_fma_f32 v45, v46, v45, v46
	v_cmp_ngt_f32_e32 vcc, 1.0, v46
	s_nop 1
	v_cndmask_b32_e32 v45, v45, v47, vcc
	v_mul_f32_e32 v46, 0x3f3504f3, v37
	v_and_b32_e32 v48, 0x7fffffff, v46
	v_fmamk_f32 v49, v48, 0x378e98ab, v222
	v_fmaak_f32 v49, v48, v49, 0x3b7cd369
	v_fmaak_f32 v49, v48, v49, 0xbcc618b2
	v_fmaak_f32 v49, v48, v49, 0x3dda74e4
	v_fmaak_f32 v49, v48, v49, 0x3f228afd
	v_fmaak_f32 v49, v48, v49, 0x3e03c728
	v_fma_f32 v49, v48, v49, v48
	v_mul_f32_e32 v49, 0xbfb8aa3b, v49
	v_exp_f32_e32 v49, v49
	v_mul_f32_e32 v50, v46, v46
	v_sub_f32_e32 v49, 1.0, v49
	v_fmamk_f32 v47, v50, 0xba1345e1, v200
	v_fmaak_f32 v47, v50, v47, 0xbcdac9b8
	v_fmaak_f32 v47, v50, v47, 0x3de703be
	v_fmaak_f32 v47, v50, v47, 0xbec09330
	v_fmaak_f32 v47, v50, v47, 0x3e0375d0
	v_fma_f32 v47, v48, v47, v48
	v_cmp_ngt_f32_e32 vcc, 1.0, v48
	s_nop 1
	v_cndmask_b32_e32 v47, v47, v49, vcc
	v_bfi_b32 v44, s37, v45, v44
	v_mul_f32_e32 v36, 0.5, v36
	v_add_f32_e32 v44, 1.0, v44
	v_mul_f32_e32 v44, v36, v44
	v_bfi_b32 v36, s37, v43, v42
	v_mul_f32_e32 v35, 0.5, v35
	v_add_f32_e32 v36, 1.0, v36
	v_mul_f32_e32 v36, v35, v36
	v_bfi_b32 v35, s37, v41, v40
	v_readlane_b32 s6, v252, 33
	v_mul_f32_e32 v34, 0.5, v34
	v_add_f32_e32 v35, 1.0, v35
	v_readlane_b32 s7, v252, 34
	v_mul_f32_e32 v40, v34, v35
	v_mul_f32_e32 v37, 0.5, v37
	v_lshl_add_u64 v[34:35], s[6:7], 0, v[38:39]
	v_bfi_b32 v38, s37, v47, v46
	v_add_f32_e32 v38, 1.0, v38
	v_mul_f32_e32 v37, v37, v38
	v_lshl_add_u64 v[34:35], v[182:183], 1, v[34:35]
	v_cvt_pk_bf16_f32 v36, v40, v36
	v_cvt_pk_bf16_f32 v37, v44, v37
	global_store_dwordx2 v[34:35], v[36:37], off offset:-2016

; DI void st_bf4(u16* p, float a, float b, float c, float d) { *(uint2*)p = make_uint2(pk2(a, b), pk2(c, d)); }
; DI float gelu_f(float x) { return 0.5f * x * (1.f + erff(x * 0.70710678118654752f)); }
;   template <int NT, int MT> DI void run(f32x4 (&acc)[NT][MT], int mb, int nb) const {
;     ...
;         } else if (n < 3072) {
;           st_bf4(uvbuf + (size_t)m * 2048 + (n - 1024), gelu_f(v[0]), gelu_f(v[1]), gelu_f(v[2]), gelu_f(v[3]));
.LBB0_644:
	s_andn2_saveexec_b64 s[48:49], s[48:49]
	s_cbranch_execz .LBB0_662
	v_mul_f32_e32 v36, 0x3f3504f3, v30
	v_and_b32_e32 v38, 0x7fffffff, v36
	v_fmamk_f32 v39, v38, 0x378e98ab, v222
	v_fmaak_f32 v39, v38, v39, 0x3b7cd369
	v_fmaak_f32 v39, v38, v39, 0xbcc618b2
	v_fmaak_f32 v39, v38, v39, 0x3dda74e4
	v_fmaak_f32 v39, v38, v39, 0x3f228afd
	v_fmaak_f32 v39, v38, v39, 0x3e03c728
	v_fma_f32 v39, v38, v39, v38
	v_mul_f32_e32 v39, 0xbfb8aa3b, v39
	v_exp_f32_e32 v39, v39
	v_mul_f32_e32 v40, v36, v36
	v_sub_f32_e32 v39, 1.0, v39
	v_fmamk_f32 v37, v40, 0xba1345e1, v200
	v_fmaak_f32 v37, v40, v37, 0xbcdac9b8
	v_fmaak_f32 v37, v40, v37, 0x3de703be
	v_fmaak_f32 v37, v40, v37, 0xbec09330
	v_fmaak_f32 v37, v40, v37, 0x3e0375d0
	v_fma_f32 v37, v38, v37, v38
	v_cmp_ngt_f32_e32 vcc, 1.0, v38
	s_nop 1
	v_cndmask_b32_e32 v37, v37, v39, vcc
	v_mul_f32_e32 v38, 0x3f3504f3, v31
	v_and_b32_e32 v40, 0x7fffffff, v38
	v_fmamk_f32 v41, v40, 0x378e98ab, v222
	v_fmaak_f32 v41, v40, v41, 0x3b7cd369
	v_fmaak_f32 v41, v40, v41, 0xbcc618b2
	v_fmaak_f32 v41, v40, v41, 0x3dda74e4
	v_fmaak_f32 v41, v40, v41, 0x3f228afd
	v_fmaak_f32 v41, v40, v41, 0x3e03c728
	v_fma_f32 v41, v40, v41, v40
	v_mul_f32_e32 v41, 0xbfb8aa3b, v41
	v_exp_f32_e32 v41, v41
	v_mul_f32_e32 v42, v38, v38
	v_sub_f32_e32 v41, 1.0, v41
	v_fmamk_f32 v39, v42, 0xba1345e1, v200
	v_fmaak_f32 v39, v42, v39, 0xbcdac9b8
	v_fmaak_f32 v39, v42, v39, 0x3de703be
	v_fmaak_f32 v39, v42, v39, 0xbec09330
	v_fmaak_f32 v39, v42, v39, 0x3e0375d0
	v_fma_f32 v39, v40, v39, v40
	v_cmp_ngt_f32_e32 vcc, 1.0, v40
	s_nop 1
	v_cndmask_b32_e32 v39, v39, v41, vcc
	v_mul_f32_e32 v40, 0x3f3504f3, v32
	v_and_b32_e32 v42, 0x7fffffff, v40
	v_fmamk_f32 v43, v42, 0x378e98ab, v222
	v_fmaak_f32 v43, v42, v43, 0x3b7cd369
	v_fmaak_f32 v43, v42, v43, 0xbcc618b2
	v_fmaak_f32 v43, v42, v43, 0x3dda74e4
	v_fmaak_f32 v43, v42, v43, 0x3f228afd
	v_fmaak_f32 v43, v42, v43, 0x3e03c728
	v_fma_f32 v43, v42, v43, v42
	v_mul_f32_e32 v43, 0xbfb8aa3b, v43
	v_exp_f32_e32 v43, v43
	v_mul_f32_e32 v44, v40, v40
	v_sub_f32_e32 v43, 1.0, v43
	v_fmamk_f32 v41, v44, 0xba1345e1, v200
	v_fmaak_f32 v41, v44, v41, 0xbcdac9b8
	v_fmaak_f32 v41, v44, v41, 0x3de703be
	v_fmaak_f32 v41, v44, v41, 0xbec09330
	v_fmaak_f32 v41, v44, v41, 0x3e0375d0
	v_fma_f32 v41, v42, v41, v42
	v_cmp_ngt_f32_e32 vcc, 1.0, v42
	s_nop 1
	v_cndmask_b32_e32 v41, v41, v43, vcc
	v_mul_f32_e32 v42, 0x3f3504f3, v33
	v_and_b32_e32 v44, 0x7fffffff, v42
	v_fmamk_f32 v45, v44, 0x378e98ab, v222
	v_fmaak_f32 v45, v44, v45, 0x3b7cd369
	v_fmaak_f32 v45, v44, v45, 0xbcc618b2
	v_fmaak_f32 v45, v44, v45, 0x3dda74e4
	v_fmaak_f32 v45, v44, v45, 0x3f228afd
	v_fmaak_f32 v45, v44, v45, 0x3e03c728
	v_fma_f32 v45, v44, v45, v44
	v_mul_f32_e32 v45, 0xbfb8aa3b, v45
	v_exp_f32_e32 v45, v45
	v_mul_f32_e32 v46, v42, v42
	v_sub_f32_e32 v45, 1.0, v45
	v_fmamk_f32 v43, v46, 0xba1345e1, v200
	v_fmaak_f32 v43, v46, v43, 0xbcdac9b8
	v_fmaak_f32 v43, v46, v43, 0x3de703be
	v_fmaak_f32 v43, v46, v43, 0xbec09330
	v_fmaak_f32 v43, v46, v43, 0x3e0375d0
	v_fma_f32 v43, v44, v43, v44
	v_cmp_ngt_f32_e32 vcc, 1.0, v44
	s_nop 1
	v_cndmask_b32_e32 v43, v43, v45, vcc
	v_bfi_b32 v40, s37, v41, v40
	v_mul_f32_e32 v32, 0.5, v32
	v_add_f32_e32 v40, 1.0, v40
	v_mul_f32_e32 v40, v32, v40
	v_bfi_b32 v32, s37, v39, v38
	v_mul_f32_e32 v31, 0.5, v31
	v_add_f32_e32 v32, 1.0, v32
	v_mul_f32_e32 v32, v31, v32
	v_bfi_b32 v31, s37, v37, v36
	v_readlane_b32 s6, v252, 33
	v_mul_f32_e32 v30, 0.5, v30
	v_add_f32_e32 v31, 1.0, v31
	v_readlane_b32 s7, v252, 34
	v_mul_f32_e32 v36, v30, v31
	v_mul_f32_e32 v33, 0.5, v33
	v_lshl_add_u64 v[30:31], s[6:7], 0, v[34:35]
	v_bfi_b32 v34, s37, v43, v42
	v_add_f32_e32 v34, 1.0, v34
	v_mul_f32_e32 v33, v33, v34
	v_lshl_add_u64 v[30:31], v[182:183], 1, v[30:31]
	v_cvt_pk_bf16_f32 v32, v36, v32
	v_cvt_pk_bf16_f32 v33, v40, v33
	global_store_dwordx2 v[30:31], v[32:33], off offset:-1984

; DI void st_bf4(u16* p, float a, float b, float c, float d) { *(uint2*)p = make_uint2(pk2(a, b), pk2(c, d)); }
; DI float gelu_f(float x) { return 0.5f * x * (1.f + erff(x * 0.70710678118654752f)); }
;   template <int NT, int MT> DI void run(f32x4 (&acc)[NT][MT], int mb, int nb) const {
;     ...
;         } else if (n < 3072) {
;           st_bf4(uvbuf + (size_t)m * 2048 + (n - 1024), gelu_f(v[0]), gelu_f(v[1]), gelu_f(v[2]), gelu_f(v[3]));
.LBB0_668:
	s_andn2_saveexec_b64 s[48:49], s[48:49]
	s_cbranch_execz .LBB0_686
	v_mul_f32_e32 v32, 0x3f3504f3, v26
	v_and_b32_e32 v34, 0x7fffffff, v32
	v_fmamk_f32 v35, v34, 0x378e98ab, v222
	v_fmaak_f32 v35, v34, v35, 0x3b7cd369
	v_fmaak_f32 v35, v34, v35, 0xbcc618b2
	v_fmaak_f32 v35, v34, v35, 0x3dda74e4
	v_fmaak_f32 v35, v34, v35, 0x3f228afd
	v_fmaak_f32 v35, v34, v35, 0x3e03c728
	v_fma_f32 v35, v34, v35, v34
	v_mul_f32_e32 v35, 0xbfb8aa3b, v35
	v_exp_f32_e32 v35, v35
	v_mul_f32_e32 v36, v32, v32
	v_sub_f32_e32 v35, 1.0, v35
	v_fmamk_f32 v33, v36, 0xba1345e1, v200
	v_fmaak_f32 v33, v36, v33, 0xbcdac9b8
	v_fmaak_f32 v33, v36, v33, 0x3de703be
	v_fmaak_f32 v33, v36, v33, 0xbec09330
	v_fmaak_f32 v33, v36, v33, 0x3e0375d0
	v_fma_f32 v33, v34, v33, v34
	v_cmp_ngt_f32_e32 vcc, 1.0, v34
	s_nop 1
	v_cndmask_b32_e32 v33, v33, v35, vcc
	v_mul_f32_e32 v34, 0x3f3504f3, v27
	v_and_b32_e32 v36, 0x7fffffff, v34
	v_fmamk_f32 v37, v36, 0x378e98ab, v222
	v_fmaak_f32 v37, v36, v37, 0x3b7cd369
	v_fmaak_f32 v37, v36, v37, 0xbcc618b2
	v_fmaak_f32 v37, v36, v37, 0x3dda74e4
	v_fmaak_f32 v37, v36, v37, 0x3f228afd
	v_fmaak_f32 v37, v36, v37, 0x3e03c728
	v_fma_f32 v37, v36, v37, v36
	v_mul_f32_e32 v37, 0xbfb8aa3b, v37
	v_exp_f32_e32 v37, v37
	v_mul_f32_e32 v38, v34, v34
	v_sub_f32_e32 v37, 1.0, v37
	v_fmamk_f32 v35, v38, 0xba1345e1, v200
	v_fmaak_f32 v35, v38, v35, 0xbcdac9b8
	v_fmaak_f32 v35, v38, v35, 0x3de703be
	v_fmaak_f32 v35, v38, v35, 0xbec09330
	v_fmaak_f32 v35, v38, v35, 0x3e0375d0
	v_fma_f32 v35, v36, v35, v36
	v_cmp_ngt_f32_e32 vcc, 1.0, v36
	s_nop 1
	v_cndmask_b32_e32 v35, v35, v37, vcc
	v_mul_f32_e32 v36, 0x3f3504f3, v28
	v_and_b32_e32 v38, 0x7fffffff, v36
	v_fmamk_f32 v39, v38, 0x378e98ab, v222
	v_fmaak_f32 v39, v38, v39, 0x3b7cd369
	v_fmaak_f32 v39, v38, v39, 0xbcc618b2
	v_fmaak_f32 v39, v38, v39, 0x3dda74e4
	v_fmaak_f32 v39, v38, v39, 0x3f228afd
	v_fmaak_f32 v39, v38, v39, 0x3e03c728
	v_fma_f32 v39, v38, v39, v38
	v_mul_f32_e32 v39, 0xbfb8aa3b, v39
	v_exp_f32_e32 v39, v39
	v_mul_f32_e32 v40, v36, v36
	v_sub_f32_e32 v39, 1.0, v39
	v_fmamk_f32 v37, v40, 0xba1345e1, v200
	v_fmaak_f32 v37, v40, v37, 0xbcdac9b8
	v_fmaak_f32 v37, v40, v37, 0x3de703be
	v_fmaak_f32 v37, v40, v37, 0xbec09330
	v_fmaak_f32 v37, v40, v37, 0x3e0375d0
	v_fma_f32 v37, v38, v37, v38
	v_cmp_ngt_f32_e32 vcc, 1.0, v38
	s_nop 1
	v_cndmask_b32_e32 v37, v37, v39, vcc
	v_mul_f32_e32 v38, 0x3f3504f3, v29
	v_and_b32_e32 v40, 0x7fffffff, v38
	v_fmamk_f32 v41, v40, 0x378e98ab, v222
	v_fmaak_f32 v41, v40, v41, 0x3b7cd369
	v_fmaak_f32 v41, v40, v41, 0xbcc618b2
	v_fmaak_f32 v41, v40, v41, 0x3dda74e4
	v_fmaak_f32 v41, v40, v41, 0x3f228afd
	v_fmaak_f32 v41, v40, v41, 0x3e03c728
	v_fma_f32 v41, v40, v41, v40
	v_mul_f32_e32 v41, 0xbfb8aa3b, v41
	v_exp_f32_e32 v41, v41
	v_mul_f32_e32 v42, v38, v38
	v_sub_f32_e32 v41, 1.0, v41
	v_fmamk_f32 v39, v42, 0xba1345e1, v200
	v_fmaak_f32 v39, v42, v39, 0xbcdac9b8
	v_fmaak_f32 v39, v42, v39, 0x3de703be
	v_fmaak_f32 v39, v42, v39, 0xbec09330
	v_fmaak_f32 v39, v42, v39, 0x3e0375d0
	v_fma_f32 v39, v40, v39, v40
	v_cmp_ngt_f32_e32 vcc, 1.0, v40
	s_nop 1
	v_cndmask_b32_e32 v39, v39, v41, vcc
	v_bfi_b32 v36, s37, v37, v36
	v_mul_f32_e32 v28, 0.5, v28
	v_add_f32_e32 v36, 1.0, v36
	v_mul_f32_e32 v36, v28, v36
	v_bfi_b32 v28, s37, v35, v34
	v_mul_f32_e32 v27, 0.5, v27
	v_add_f32_e32 v28, 1.0, v28
	v_mul_f32_e32 v28, v27, v28
	v_bfi_b32 v27, s37, v33, v32
	v_readlane_b32 s6, v252, 33
	v_mul_f32_e32 v26, 0.5, v26
	v_add_f32_e32 v27, 1.0, v27
	v_readlane_b32 s7, v252, 34
	v_mul_f32_e32 v32, v26, v27
	v_mul_f32_e32 v29, 0.5, v29
	v_lshl_add_u64 v[26:27], s[6:7], 0, v[30:31]
	v_bfi_b32 v30, s37, v39, v38
	v_add_f32_e32 v30, 1.0, v30
	v_mul_f32_e32 v29, v29, v30
	v_lshl_add_u64 v[26:27], v[182:183], 1, v[26:27]
	v_cvt_pk_bf16_f32 v28, v32, v28
	v_cvt_pk_bf16_f32 v29, v36, v29
	global_store_dwordx2 v[26:27], v[28:29], off offset:-1984

; DI void st_bf4(u16* p, float a, float b, float c, float d) { *(uint2*)p = make_uint2(pk2(a, b), pk2(c, d)); }
; DI float gelu_f(float x) { return 0.5f * x * (1.f + erff(x * 0.70710678118654752f)); }
;   template <int NT, int MT> DI void run(f32x4 (&acc)[NT][MT], int mb, int nb) const {
;     ...
;         } else if (n < 3072) {
;           st_bf4(uvbuf + (size_t)m * 2048 + (n - 1024), gelu_f(v[0]), gelu_f(v[1]), gelu_f(v[2]), gelu_f(v[3]));
.LBB0_698:
	s_andn2_saveexec_b64 s[48:49], s[48:49]
	s_cbranch_execz .LBB0_716
	v_mul_f32_e32 v28, 0x3f3504f3, v22
	v_and_b32_e32 v30, 0x7fffffff, v28
	v_fmamk_f32 v31, v30, 0x378e98ab, v222
	v_fmaak_f32 v31, v30, v31, 0x3b7cd369
	v_fmaak_f32 v31, v30, v31, 0xbcc618b2
	v_fmaak_f32 v31, v30, v31, 0x3dda74e4
	v_fmaak_f32 v31, v30, v31, 0x3f228afd
	v_fmaak_f32 v31, v30, v31, 0x3e03c728
	v_fma_f32 v31, v30, v31, v30
	v_mul_f32_e32 v31, 0xbfb8aa3b, v31
	v_exp_f32_e32 v31, v31
	v_mul_f32_e32 v32, v28, v28
	v_sub_f32_e32 v31, 1.0, v31
	v_fmamk_f32 v29, v32, 0xba1345e1, v200
	v_fmaak_f32 v29, v32, v29, 0xbcdac9b8
	v_fmaak_f32 v29, v32, v29, 0x3de703be
	v_fmaak_f32 v29, v32, v29, 0xbec09330
	v_fmaak_f32 v29, v32, v29, 0x3e0375d0
	v_fma_f32 v29, v30, v29, v30
	v_cmp_ngt_f32_e32 vcc, 1.0, v30
	s_nop 1
	v_cndmask_b32_e32 v29, v29, v31, vcc
	v_mul_f32_e32 v30, 0x3f3504f3, v23
	v_and_b32_e32 v32, 0x7fffffff, v30
	v_fmamk_f32 v33, v32, 0x378e98ab, v222
	v_fmaak_f32 v33, v32, v33, 0x3b7cd369
	v_fmaak_f32 v33, v32, v33, 0xbcc618b2
	v_fmaak_f32 v33, v32, v33, 0x3dda74e4
	v_fmaak_f32 v33, v32, v33, 0x3f228afd
	v_fmaak_f32 v33, v32, v33, 0x3e03c728
	v_fma_f32 v33, v32, v33, v32
	v_mul_f32_e32 v33, 0xbfb8aa3b, v33
	v_exp_f32_e32 v33, v33
	v_mul_f32_e32 v34, v30, v30
	v_sub_f32_e32 v33, 1.0, v33
	v_fmamk_f32 v31, v34, 0xba1345e1, v200
	v_fmaak_f32 v31, v34, v31, 0xbcdac9b8
	v_fmaak_f32 v31, v34, v31, 0x3de703be
	v_fmaak_f32 v31, v34, v31, 0xbec09330
	v_fmaak_f32 v31, v34, v31, 0x3e0375d0
	v_fma_f32 v31, v32, v31, v32
	v_cmp_ngt_f32_e32 vcc, 1.0, v32
	s_nop 1
	v_cndmask_b32_e32 v31, v31, v33, vcc
	v_mul_f32_e32 v32, 0x3f3504f3, v24
	v_and_b32_e32 v34, 0x7fffffff, v32
	v_fmamk_f32 v35, v34, 0x378e98ab, v222
	v_fmaak_f32 v35, v34, v35, 0x3b7cd369
	v_fmaak_f32 v35, v34, v35, 0xbcc618b2
	v_fmaak_f32 v35, v34, v35, 0x3dda74e4
	v_fmaak_f32 v35, v34, v35, 0x3f228afd
	v_fmaak_f32 v35, v34, v35, 0x3e03c728
	v_fma_f32 v35, v34, v35, v34
	v_mul_f32_e32 v35, 0xbfb8aa3b, v35
	v_exp_f32_e32 v35, v35
	v_mul_f32_e32 v36, v32, v32
	v_sub_f32_e32 v35, 1.0, v35
	v_fmamk_f32 v33, v36, 0xba1345e1, v200
	v_fmaak_f32 v33, v36, v33, 0xbcdac9b8
	v_fmaak_f32 v33, v36, v33, 0x3de703be
	v_fmaak_f32 v33, v36, v33, 0xbec09330
	v_fmaak_f32 v33, v36, v33, 0x3e0375d0
	v_fma_f32 v33, v34, v33, v34
	v_cmp_ngt_f32_e32 vcc, 1.0, v34
	s_nop 1
	v_cndmask_b32_e32 v33, v33, v35, vcc
	v_mul_f32_e32 v34, 0x3f3504f3, v25
	v_and_b32_e32 v36, 0x7fffffff, v34
	v_fmamk_f32 v37, v36, 0x378e98ab, v222
	v_fmaak_f32 v37, v36, v37, 0x3b7cd369
	v_fmaak_f32 v37, v36, v37, 0xbcc618b2
	v_fmaak_f32 v37, v36, v37, 0x3dda74e4
	v_fmaak_f32 v37, v36, v37, 0x3f228afd
	v_fmaak_f32 v37, v36, v37, 0x3e03c728
	v_fma_f32 v37, v36, v37, v36
	v_mul_f32_e32 v37, 0xbfb8aa3b, v37
	v_exp_f32_e32 v37, v37
	v_mul_f32_e32 v38, v34, v34
	v_sub_f32_e32 v37, 1.0, v37
	v_fmamk_f32 v35, v38, 0xba1345e1, v200
	v_fmaak_f32 v35, v38, v35, 0xbcdac9b8
	v_fmaak_f32 v35, v38, v35, 0x3de703be
	v_fmaak_f32 v35, v38, v35, 0xbec09330
	v_fmaak_f32 v35, v38, v35, 0x3e0375d0
	v_fma_f32 v35, v36, v35, v36
	v_cmp_ngt_f32_e32 vcc, 1.0, v36
	s_nop 1
	v_cndmask_b32_e32 v35, v35, v37, vcc
	v_bfi_b32 v32, s37, v33, v32
	v_mul_f32_e32 v24, 0.5, v24
	v_add_f32_e32 v32, 1.0, v32
	v_mul_f32_e32 v32, v24, v32
	v_bfi_b32 v24, s37, v31, v30
	v_mul_f32_e32 v23, 0.5, v23
	v_add_f32_e32 v24, 1.0, v24
	v_mul_f32_e32 v24, v23, v24
	v_bfi_b32 v23, s37, v29, v28
	v_readlane_b32 s6, v252, 33
	v_mul_f32_e32 v22, 0.5, v22
	v_add_f32_e32 v23, 1.0, v23
	v_readlane_b32 s7, v252, 34
	v_mul_f32_e32 v28, v22, v23
	v_mul_f32_e32 v25, 0.5, v25
	v_lshl_add_u64 v[22:23], s[6:7], 0, v[26:27]
	v_bfi_b32 v26, s37, v35, v34
	v_add_f32_e32 v26, 1.0, v26
	v_mul_f32_e32 v25, v25, v26
	v_lshl_add_u64 v[22:23], v[182:183], 1, v[22:23]
	v_cvt_pk_bf16_f32 v24, v28, v24
	v_cvt_pk_bf16_f32 v25, v32, v25
	global_store_dwordx2 v[22:23], v[24:25], off offset:-1984

; DI void st_bf4(u16* p, float a, float b, float c, float d) { *(uint2*)p = make_uint2(pk2(a, b), pk2(c, d)); }
; DI float gelu_f(float x) { return 0.5f * x * (1.f + erff(x * 0.70710678118654752f)); }
;   template <int NT, int MT> DI void run(f32x4 (&acc)[NT][MT], int mb, int nb) const {
;     ...
;         } else if (n < 3072) {
;           st_bf4(uvbuf + (size_t)m * 2048 + (n - 1024), gelu_f(v[0]), gelu_f(v[1]), gelu_f(v[2]), gelu_f(v[3]));
.LBB0_722:
	s_andn2_saveexec_b64 s[46:47], s[46:47]
	s_cbranch_execz .LBB0_740
	v_mul_f32_e32 v24, 0x3f3504f3, v18
	v_and_b32_e32 v26, 0x7fffffff, v24
	v_fmamk_f32 v27, v26, 0x378e98ab, v222
	v_fmaak_f32 v27, v26, v27, 0x3b7cd369
	v_fmaak_f32 v27, v26, v27, 0xbcc618b2
	v_fmaak_f32 v27, v26, v27, 0x3dda74e4
	v_fmaak_f32 v27, v26, v27, 0x3f228afd
	v_fmaak_f32 v27, v26, v27, 0x3e03c728
	v_fma_f32 v27, v26, v27, v26
	v_mul_f32_e32 v27, 0xbfb8aa3b, v27
	v_exp_f32_e32 v27, v27
	v_mul_f32_e32 v28, v24, v24
	v_sub_f32_e32 v27, 1.0, v27
	v_fmamk_f32 v25, v28, 0xba1345e1, v200
	v_fmaak_f32 v25, v28, v25, 0xbcdac9b8
	v_fmaak_f32 v25, v28, v25, 0x3de703be
	v_fmaak_f32 v25, v28, v25, 0xbec09330
	v_fmaak_f32 v25, v28, v25, 0x3e0375d0
	v_fma_f32 v25, v26, v25, v26
	v_cmp_ngt_f32_e32 vcc, 1.0, v26
	s_nop 1
	v_cndmask_b32_e32 v25, v25, v27, vcc
	v_mul_f32_e32 v26, 0x3f3504f3, v19
	v_and_b32_e32 v28, 0x7fffffff, v26
	v_fmamk_f32 v29, v28, 0x378e98ab, v222
	v_fmaak_f32 v29, v28, v29, 0x3b7cd369
	v_fmaak_f32 v29, v28, v29, 0xbcc618b2
	v_fmaak_f32 v29, v28, v29, 0x3dda74e4
	v_fmaak_f32 v29, v28, v29, 0x3f228afd
	v_fmaak_f32 v29, v28, v29, 0x3e03c728
	v_fma_f32 v29, v28, v29, v28
	v_mul_f32_e32 v29, 0xbfb8aa3b, v29
	v_exp_f32_e32 v29, v29
	v_mul_f32_e32 v30, v26, v26
	v_sub_f32_e32 v29, 1.0, v29
	v_fmamk_f32 v27, v30, 0xba1345e1, v200
	v_fmaak_f32 v27, v30, v27, 0xbcdac9b8
	v_fmaak_f32 v27, v30, v27, 0x3de703be
	v_fmaak_f32 v27, v30, v27, 0xbec09330
	v_fmaak_f32 v27, v30, v27, 0x3e0375d0
	v_fma_f32 v27, v28, v27, v28
	v_cmp_ngt_f32_e32 vcc, 1.0, v28
	s_nop 1
	v_cndmask_b32_e32 v27, v27, v29, vcc
	v_mul_f32_e32 v28, 0x3f3504f3, v20
	v_and_b32_e32 v30, 0x7fffffff, v28
	v_fmamk_f32 v31, v30, 0x378e98ab, v222
	v_fmaak_f32 v31, v30, v31, 0x3b7cd369
	v_fmaak_f32 v31, v30, v31, 0xbcc618b2
	v_fmaak_f32 v31, v30, v31, 0x3dda74e4
	v_fmaak_f32 v31, v30, v31, 0x3f228afd
	v_fmaak_f32 v31, v30, v31, 0x3e03c728
	v_fma_f32 v31, v30, v31, v30
	v_mul_f32_e32 v31, 0xbfb8aa3b, v31
	v_exp_f32_e32 v31, v31
	v_mul_f32_e32 v32, v28, v28
	v_sub_f32_e32 v31, 1.0, v31
	v_fmamk_f32 v29, v32, 0xba1345e1, v200
	v_fmaak_f32 v29, v32, v29, 0xbcdac9b8
	v_fmaak_f32 v29, v32, v29, 0x3de703be
	v_fmaak_f32 v29, v32, v29, 0xbec09330
	v_fmaak_f32 v29, v32, v29, 0x3e0375d0
	v_fma_f32 v29, v30, v29, v30
	v_cmp_ngt_f32_e32 vcc, 1.0, v30
	s_nop 1
	v_cndmask_b32_e32 v29, v29, v31, vcc
	v_mul_f32_e32 v30, 0x3f3504f3, v21
	v_and_b32_e32 v32, 0x7fffffff, v30
	v_fmamk_f32 v33, v32, 0x378e98ab, v222
	v_fmaak_f32 v33, v32, v33, 0x3b7cd369
	v_fmaak_f32 v33, v32, v33, 0xbcc618b2
	v_fmaak_f32 v33, v32, v33, 0x3dda74e4
	v_fmaak_f32 v33, v32, v33, 0x3f228afd
	v_fmaak_f32 v33, v32, v33, 0x3e03c728
	v_fma_f32 v33, v32, v33, v32
	v_mul_f32_e32 v33, 0xbfb8aa3b, v33
	v_exp_f32_e32 v33, v33
	v_mul_f32_e32 v34, v30, v30
	v_sub_f32_e32 v33, 1.0, v33
	v_fmamk_f32 v31, v34, 0xba1345e1, v200
	v_fmaak_f32 v31, v34, v31, 0xbcdac9b8
	v_fmaak_f32 v31, v34, v31, 0x3de703be
	v_fmaak_f32 v31, v34, v31, 0xbec09330
	v_fmaak_f32 v31, v34, v31, 0x3e0375d0
	v_fma_f32 v31, v32, v31, v32
	v_cmp_ngt_f32_e32 vcc, 1.0, v32
	s_nop 1
	v_cndmask_b32_e32 v31, v31, v33, vcc
	v_bfi_b32 v28, s37, v29, v28
	v_mul_f32_e32 v20, 0.5, v20
	v_add_f32_e32 v28, 1.0, v28
	v_mul_f32_e32 v28, v20, v28
	v_bfi_b32 v20, s37, v27, v26
	v_mul_f32_e32 v19, 0.5, v19
	v_add_f32_e32 v20, 1.0, v20
	v_mul_f32_e32 v20, v19, v20
	v_bfi_b32 v19, s37, v25, v24
	v_readlane_b32 s6, v252, 33
	v_mul_f32_e32 v18, 0.5, v18
	v_add_f32_e32 v19, 1.0, v19
	v_readlane_b32 s7, v252, 34
	v_mul_f32_e32 v24, v18, v19
	v_mul_f32_e32 v21, 0.5, v21
	v_lshl_add_u64 v[18:19], s[6:7], 0, v[22:23]
	v_bfi_b32 v22, s37, v31, v30
	v_add_f32_e32 v22, 1.0, v22
	v_mul_f32_e32 v21, v21, v22
	v_lshl_add_u64 v[18:19], v[182:183], 1, v[18:19]
	v_cvt_pk_bf16_f32 v20, v24, v20
	v_cvt_pk_bf16_f32 v21, v28, v21
	global_store_dwordx2 v[18:19], v[20:21], off offset:-1984

; DI void st_bf4(u16* p, float a, float b, float c, float d) { *(uint2*)p = make_uint2(pk2(a, b), pk2(c, d)); }
; DI float gelu_f(float x) { return 0.5f * x * (1.f + erff(x * 0.70710678118654752f)); }
;   template <int NT, int MT> DI void run(f32x4 (&acc)[NT][MT], int mb, int nb) const {
;     ...
;         } else if (n < 3072) {
;           st_bf4(uvbuf + (size_t)m * 2048 + (n - 1024), gelu_f(v[0]), gelu_f(v[1]), gelu_f(v[2]), gelu_f(v[3]));
.LBB0_752:
	s_andn2_saveexec_b64 s[48:49], s[48:49]
	s_cbranch_execz .LBB0_770
	v_mul_f32_e32 v20, 0x3f3504f3, v14
	v_and_b32_e32 v22, 0x7fffffff, v20
	v_fmamk_f32 v23, v22, 0x378e98ab, v222
	v_fmaak_f32 v23, v22, v23, 0x3b7cd369
	v_fmaak_f32 v23, v22, v23, 0xbcc618b2
	v_fmaak_f32 v23, v22, v23, 0x3dda74e4
	v_fmaak_f32 v23, v22, v23, 0x3f228afd
	v_fmaak_f32 v23, v22, v23, 0x3e03c728
	v_fma_f32 v23, v22, v23, v22
	v_mul_f32_e32 v23, 0xbfb8aa3b, v23
	v_exp_f32_e32 v23, v23
	v_mul_f32_e32 v24, v20, v20
	v_sub_f32_e32 v23, 1.0, v23
	v_fmamk_f32 v21, v24, 0xba1345e1, v200
	v_fmaak_f32 v21, v24, v21, 0xbcdac9b8
	v_fmaak_f32 v21, v24, v21, 0x3de703be
	v_fmaak_f32 v21, v24, v21, 0xbec09330
	v_fmaak_f32 v21, v24, v21, 0x3e0375d0
	v_fma_f32 v21, v22, v21, v22
	v_cmp_ngt_f32_e32 vcc, 1.0, v22
	s_nop 1
	v_cndmask_b32_e32 v21, v21, v23, vcc
	v_mul_f32_e32 v22, 0x3f3504f3, v15
	v_and_b32_e32 v24, 0x7fffffff, v22
	v_fmamk_f32 v25, v24, 0x378e98ab, v222
	v_fmaak_f32 v25, v24, v25, 0x3b7cd369
	v_fmaak_f32 v25, v24, v25, 0xbcc618b2
	v_fmaak_f32 v25, v24, v25, 0x3dda74e4
	v_fmaak_f32 v25, v24, v25, 0x3f228afd
	v_fmaak_f32 v25, v24, v25, 0x3e03c728
	v_fma_f32 v25, v24, v25, v24
	v_mul_f32_e32 v25, 0xbfb8aa3b, v25
	v_exp_f32_e32 v25, v25
	v_mul_f32_e32 v26, v22, v22
	v_sub_f32_e32 v25, 1.0, v25
	v_fmamk_f32 v23, v26, 0xba1345e1, v200
	v_fmaak_f32 v23, v26, v23, 0xbcdac9b8
	v_fmaak_f32 v23, v26, v23, 0x3de703be
	v_fmaak_f32 v23, v26, v23, 0xbec09330
	v_fmaak_f32 v23, v26, v23, 0x3e0375d0
	v_fma_f32 v23, v24, v23, v24
	v_cmp_ngt_f32_e32 vcc, 1.0, v24
	s_nop 1
	v_cndmask_b32_e32 v23, v23, v25, vcc
	v_mul_f32_e32 v24, 0x3f3504f3, v16
	v_and_b32_e32 v26, 0x7fffffff, v24
	v_fmamk_f32 v27, v26, 0x378e98ab, v222
	v_fmaak_f32 v27, v26, v27, 0x3b7cd369
	v_fmaak_f32 v27, v26, v27, 0xbcc618b2
	v_fmaak_f32 v27, v26, v27, 0x3dda74e4
	v_fmaak_f32 v27, v26, v27, 0x3f228afd
	v_fmaak_f32 v27, v26, v27, 0x3e03c728
	v_fma_f32 v27, v26, v27, v26
	v_mul_f32_e32 v27, 0xbfb8aa3b, v27
	v_exp_f32_e32 v27, v27
	v_mul_f32_e32 v28, v24, v24
	v_sub_f32_e32 v27, 1.0, v27
	v_fmamk_f32 v25, v28, 0xba1345e1, v200
	v_fmaak_f32 v25, v28, v25, 0xbcdac9b8
	v_fmaak_f32 v25, v28, v25, 0x3de703be
	v_fmaak_f32 v25, v28, v25, 0xbec09330
	v_fmaak_f32 v25, v28, v25, 0x3e0375d0
	v_fma_f32 v25, v26, v25, v26
	v_cmp_ngt_f32_e32 vcc, 1.0, v26
	s_nop 1
	v_cndmask_b32_e32 v25, v25, v27, vcc
	v_mul_f32_e32 v26, 0x3f3504f3, v17
	v_and_b32_e32 v28, 0x7fffffff, v26
	v_fmamk_f32 v29, v28, 0x378e98ab, v222
	v_fmaak_f32 v29, v28, v29, 0x3b7cd369
	v_fmaak_f32 v29, v28, v29, 0xbcc618b2
	v_fmaak_f32 v29, v28, v29, 0x3dda74e4
	v_fmaak_f32 v29, v28, v29, 0x3f228afd
	v_fmaak_f32 v29, v28, v29, 0x3e03c728
	v_fma_f32 v29, v28, v29, v28
	v_mul_f32_e32 v29, 0xbfb8aa3b, v29
	v_exp_f32_e32 v29, v29
	v_mul_f32_e32 v30, v26, v26
	v_sub_f32_e32 v29, 1.0, v29
	v_fmamk_f32 v27, v30, 0xba1345e1, v200
	v_fmaak_f32 v27, v30, v27, 0xbcdac9b8
	v_fmaak_f32 v27, v30, v27, 0x3de703be
	v_fmaak_f32 v27, v30, v27, 0xbec09330
	v_fmaak_f32 v27, v30, v27, 0x3e0375d0
	v_fma_f32 v27, v28, v27, v28
	v_cmp_ngt_f32_e32 vcc, 1.0, v28
	s_nop 1
	v_cndmask_b32_e32 v27, v27, v29, vcc
	v_bfi_b32 v24, s37, v25, v24
	v_mul_f32_e32 v16, 0.5, v16
	v_add_f32_e32 v24, 1.0, v24
	v_mul_f32_e32 v24, v16, v24
	v_bfi_b32 v16, s37, v23, v22
	v_mul_f32_e32 v15, 0.5, v15
	v_add_f32_e32 v16, 1.0, v16
	v_mul_f32_e32 v16, v15, v16
	v_bfi_b32 v15, s37, v21, v20
	v_readlane_b32 s6, v252, 33
	v_mul_f32_e32 v14, 0.5, v14
	v_add_f32_e32 v15, 1.0, v15
	v_readlane_b32 s7, v252, 34
	v_mul_f32_e32 v20, v14, v15
	v_mul_f32_e32 v17, 0.5, v17
	v_lshl_add_u64 v[14:15], s[6:7], 0, v[18:19]
	v_bfi_b32 v18, s37, v27, v26
	v_add_f32_e32 v18, 1.0, v18
	v_mul_f32_e32 v17, v17, v18
	v_lshl_add_u64 v[14:15], v[182:183], 1, v[14:15]
	v_cvt_pk_bf16_f32 v16, v20, v16
	v_cvt_pk_bf16_f32 v17, v24, v17
	global_store_dwordx2 v[14:15], v[16:17], off offset:-1952

; DI void st_bf4(u16* p, float a, float b, float c, float d) { *(uint2*)p = make_uint2(pk2(a, b), pk2(c, d)); }
; DI float gelu_f(float x) { return 0.5f * x * (1.f + erff(x * 0.70710678118654752f)); }
;   template <int NT, int MT> DI void run(f32x4 (&acc)[NT][MT], int mb, int nb) const {
;     ...
;         } else if (n < 3072) {
;           st_bf4(uvbuf + (size_t)m * 2048 + (n - 1024), gelu_f(v[0]), gelu_f(v[1]), gelu_f(v[2]), gelu_f(v[3]));
.LBB0_776:
	s_andn2_saveexec_b64 s[48:49], s[48:49]
	s_cbranch_execz .LBB0_794
	v_mul_f32_e32 v16, 0x3f3504f3, v10
	v_and_b32_e32 v18, 0x7fffffff, v16
	v_fmamk_f32 v19, v18, 0x378e98ab, v222
	v_fmaak_f32 v19, v18, v19, 0x3b7cd369
	v_fmaak_f32 v19, v18, v19, 0xbcc618b2
	v_fmaak_f32 v19, v18, v19, 0x3dda74e4
	v_fmaak_f32 v19, v18, v19, 0x3f228afd
	v_fmaak_f32 v19, v18, v19, 0x3e03c728
	v_fma_f32 v19, v18, v19, v18
	v_mul_f32_e32 v19, 0xbfb8aa3b, v19
	v_exp_f32_e32 v19, v19
	v_mul_f32_e32 v20, v16, v16
	v_sub_f32_e32 v19, 1.0, v19
	v_fmamk_f32 v17, v20, 0xba1345e1, v200
	v_fmaak_f32 v17, v20, v17, 0xbcdac9b8
	v_fmaak_f32 v17, v20, v17, 0x3de703be
	v_fmaak_f32 v17, v20, v17, 0xbec09330
	v_fmaak_f32 v17, v20, v17, 0x3e0375d0
	v_fma_f32 v17, v18, v17, v18
	v_cmp_ngt_f32_e32 vcc, 1.0, v18
	s_nop 1
	v_cndmask_b32_e32 v17, v17, v19, vcc
	v_mul_f32_e32 v18, 0x3f3504f3, v11
	v_and_b32_e32 v20, 0x7fffffff, v18
	v_fmamk_f32 v21, v20, 0x378e98ab, v222
	v_fmaak_f32 v21, v20, v21, 0x3b7cd369
	v_fmaak_f32 v21, v20, v21, 0xbcc618b2
	v_fmaak_f32 v21, v20, v21, 0x3dda74e4
	v_fmaak_f32 v21, v20, v21, 0x3f228afd
	v_fmaak_f32 v21, v20, v21, 0x3e03c728
	v_fma_f32 v21, v20, v21, v20
	v_mul_f32_e32 v21, 0xbfb8aa3b, v21
	v_exp_f32_e32 v21, v21
	v_mul_f32_e32 v22, v18, v18
	v_sub_f32_e32 v21, 1.0, v21
	v_fmamk_f32 v19, v22, 0xba1345e1, v200
	v_fmaak_f32 v19, v22, v19, 0xbcdac9b8
	v_fmaak_f32 v19, v22, v19, 0x3de703be
	v_fmaak_f32 v19, v22, v19, 0xbec09330
	v_fmaak_f32 v19, v22, v19, 0x3e0375d0
	v_fma_f32 v19, v20, v19, v20
	v_cmp_ngt_f32_e32 vcc, 1.0, v20
	s_nop 1
	v_cndmask_b32_e32 v19, v19, v21, vcc
	v_mul_f32_e32 v20, 0x3f3504f3, v12
	v_and_b32_e32 v22, 0x7fffffff, v20
	v_fmamk_f32 v23, v22, 0x378e98ab, v222
	v_fmaak_f32 v23, v22, v23, 0x3b7cd369
	v_fmaak_f32 v23, v22, v23, 0xbcc618b2
	v_fmaak_f32 v23, v22, v23, 0x3dda74e4
	v_fmaak_f32 v23, v22, v23, 0x3f228afd
	v_fmaak_f32 v23, v22, v23, 0x3e03c728
	v_fma_f32 v23, v22, v23, v22
	v_mul_f32_e32 v23, 0xbfb8aa3b, v23
	v_exp_f32_e32 v23, v23
	v_mul_f32_e32 v24, v20, v20
	v_sub_f32_e32 v23, 1.0, v23
	v_fmamk_f32 v21, v24, 0xba1345e1, v200
	v_fmaak_f32 v21, v24, v21, 0xbcdac9b8
	v_fmaak_f32 v21, v24, v21, 0x3de703be
	v_fmaak_f32 v21, v24, v21, 0xbec09330
	v_fmaak_f32 v21, v24, v21, 0x3e0375d0
	v_fma_f32 v21, v22, v21, v22
	v_cmp_ngt_f32_e32 vcc, 1.0, v22
	s_nop 1
	v_cndmask_b32_e32 v21, v21, v23, vcc
	v_mul_f32_e32 v22, 0x3f3504f3, v13
	v_and_b32_e32 v24, 0x7fffffff, v22
	v_fmamk_f32 v25, v24, 0x378e98ab, v222
	v_fmaak_f32 v25, v24, v25, 0x3b7cd369
	v_fmaak_f32 v25, v24, v25, 0xbcc618b2
	v_fmaak_f32 v25, v24, v25, 0x3dda74e4
	v_fmaak_f32 v25, v24, v25, 0x3f228afd
	v_fmaak_f32 v25, v24, v25, 0x3e03c728
	v_fma_f32 v25, v24, v25, v24
	v_mul_f32_e32 v25, 0xbfb8aa3b, v25
	v_exp_f32_e32 v25, v25
	v_mul_f32_e32 v26, v22, v22
	v_sub_f32_e32 v25, 1.0, v25
	v_fmamk_f32 v23, v26, 0xba1345e1, v200
	v_fmaak_f32 v23, v26, v23, 0xbcdac9b8
	v_fmaak_f32 v23, v26, v23, 0x3de703be
	v_fmaak_f32 v23, v26, v23, 0xbec09330
	v_fmaak_f32 v23, v26, v23, 0x3e0375d0
	v_fma_f32 v23, v24, v23, v24
	v_cmp_ngt_f32_e32 vcc, 1.0, v24
	s_nop 1
	v_cndmask_b32_e32 v23, v23, v25, vcc
	v_bfi_b32 v20, s37, v21, v20
	v_mul_f32_e32 v12, 0.5, v12
	v_add_f32_e32 v20, 1.0, v20
	v_mul_f32_e32 v20, v12, v20
	v_bfi_b32 v12, s37, v19, v18
	v_mul_f32_e32 v11, 0.5, v11
	v_add_f32_e32 v12, 1.0, v12
	v_mul_f32_e32 v12, v11, v12
	v_bfi_b32 v11, s37, v17, v16
	v_readlane_b32 s6, v252, 33
	v_mul_f32_e32 v10, 0.5, v10
	v_add_f32_e32 v11, 1.0, v11
	v_readlane_b32 s7, v252, 34
	v_mul_f32_e32 v16, v10, v11
	v_mul_f32_e32 v13, 0.5, v13
	v_lshl_add_u64 v[10:11], s[6:7], 0, v[14:15]
	v_bfi_b32 v14, s37, v23, v22
	v_add_f32_e32 v14, 1.0, v14
	v_mul_f32_e32 v13, v13, v14
	v_lshl_add_u64 v[10:11], v[182:183], 1, v[10:11]
	v_cvt_pk_bf16_f32 v12, v16, v12
	v_cvt_pk_bf16_f32 v13, v20, v13
	global_store_dwordx2 v[10:11], v[12:13], off offset:-1952

; DI void st_bf4(u16* p, float a, float b, float c, float d) { *(uint2*)p = make_uint2(pk2(a, b), pk2(c, d)); }
; DI float gelu_f(float x) { return 0.5f * x * (1.f + erff(x * 0.70710678118654752f)); }
;   template <int NT, int MT> DI void run(f32x4 (&acc)[NT][MT], int mb, int nb) const {
;     ...
;         } else if (n < 3072) {
;           st_bf4(uvbuf + (size_t)m * 2048 + (n - 1024), gelu_f(v[0]), gelu_f(v[1]), gelu_f(v[2]), gelu_f(v[3]));
.LBB0_806:
	s_andn2_saveexec_b64 s[48:49], s[48:49]
	s_cbranch_execz .LBB0_824
	v_mul_f32_e32 v12, 0x3f3504f3, v6
	v_and_b32_e32 v14, 0x7fffffff, v12
	v_fmamk_f32 v15, v14, 0x378e98ab, v222
	v_fmaak_f32 v15, v14, v15, 0x3b7cd369
	v_fmaak_f32 v15, v14, v15, 0xbcc618b2
	v_fmaak_f32 v15, v14, v15, 0x3dda74e4
	v_fmaak_f32 v15, v14, v15, 0x3f228afd
	v_fmaak_f32 v15, v14, v15, 0x3e03c728
	v_fma_f32 v15, v14, v15, v14
	v_mul_f32_e32 v15, 0xbfb8aa3b, v15
	v_exp_f32_e32 v15, v15
	v_mul_f32_e32 v16, v12, v12
	v_sub_f32_e32 v15, 1.0, v15
	v_fmamk_f32 v13, v16, 0xba1345e1, v200
	v_fmaak_f32 v13, v16, v13, 0xbcdac9b8
	v_fmaak_f32 v13, v16, v13, 0x3de703be
	v_fmaak_f32 v13, v16, v13, 0xbec09330
	v_fmaak_f32 v13, v16, v13, 0x3e0375d0
	v_fma_f32 v13, v14, v13, v14
	v_cmp_ngt_f32_e32 vcc, 1.0, v14
	s_nop 1
	v_cndmask_b32_e32 v13, v13, v15, vcc
	v_mul_f32_e32 v14, 0x3f3504f3, v7
	v_and_b32_e32 v16, 0x7fffffff, v14
	v_fmamk_f32 v17, v16, 0x378e98ab, v222
	v_fmaak_f32 v17, v16, v17, 0x3b7cd369
	v_fmaak_f32 v17, v16, v17, 0xbcc618b2
	v_fmaak_f32 v17, v16, v17, 0x3dda74e4
	v_fmaak_f32 v17, v16, v17, 0x3f228afd
	v_fmaak_f32 v17, v16, v17, 0x3e03c728
	v_fma_f32 v17, v16, v17, v16
	v_mul_f32_e32 v17, 0xbfb8aa3b, v17
	v_exp_f32_e32 v17, v17
	v_mul_f32_e32 v18, v14, v14
	v_sub_f32_e32 v17, 1.0, v17
	v_fmamk_f32 v15, v18, 0xba1345e1, v200
	v_fmaak_f32 v15, v18, v15, 0xbcdac9b8
	v_fmaak_f32 v15, v18, v15, 0x3de703be
	v_fmaak_f32 v15, v18, v15, 0xbec09330
	v_fmaak_f32 v15, v18, v15, 0x3e0375d0
	v_fma_f32 v15, v16, v15, v16
	v_cmp_ngt_f32_e32 vcc, 1.0, v16
	s_nop 1
	v_cndmask_b32_e32 v15, v15, v17, vcc
	v_mul_f32_e32 v16, 0x3f3504f3, v8
	v_and_b32_e32 v18, 0x7fffffff, v16
	v_fmamk_f32 v19, v18, 0x378e98ab, v222
	v_fmaak_f32 v19, v18, v19, 0x3b7cd369
	v_fmaak_f32 v19, v18, v19, 0xbcc618b2
	v_fmaak_f32 v19, v18, v19, 0x3dda74e4
	v_fmaak_f32 v19, v18, v19, 0x3f228afd
	v_fmaak_f32 v19, v18, v19, 0x3e03c728
	v_fma_f32 v19, v18, v19, v18
	v_mul_f32_e32 v19, 0xbfb8aa3b, v19
	v_exp_f32_e32 v19, v19
	v_mul_f32_e32 v20, v16, v16
	v_sub_f32_e32 v19, 1.0, v19
	v_fmamk_f32 v17, v20, 0xba1345e1, v200
	v_fmaak_f32 v17, v20, v17, 0xbcdac9b8
	v_fmaak_f32 v17, v20, v17, 0x3de703be
	v_fmaak_f32 v17, v20, v17, 0xbec09330
	v_fmaak_f32 v17, v20, v17, 0x3e0375d0
	v_fma_f32 v17, v18, v17, v18
	v_cmp_ngt_f32_e32 vcc, 1.0, v18
	s_nop 1
	v_cndmask_b32_e32 v17, v17, v19, vcc
	v_mul_f32_e32 v18, 0x3f3504f3, v9
	v_and_b32_e32 v20, 0x7fffffff, v18
	v_fmamk_f32 v21, v20, 0x378e98ab, v222
	v_fmaak_f32 v21, v20, v21, 0x3b7cd369
	v_fmaak_f32 v21, v20, v21, 0xbcc618b2
	v_fmaak_f32 v21, v20, v21, 0x3dda74e4
	v_fmaak_f32 v21, v20, v21, 0x3f228afd
	v_fmaak_f32 v21, v20, v21, 0x3e03c728
	v_fma_f32 v21, v20, v21, v20
	v_mul_f32_e32 v21, 0xbfb8aa3b, v21
	v_exp_f32_e32 v21, v21
	v_mul_f32_e32 v22, v18, v18
	v_sub_f32_e32 v21, 1.0, v21
	v_fmamk_f32 v19, v22, 0xba1345e1, v200
	v_fmaak_f32 v19, v22, v19, 0xbcdac9b8
	v_fmaak_f32 v19, v22, v19, 0x3de703be
	v_fmaak_f32 v19, v22, v19, 0xbec09330
	v_fmaak_f32 v19, v22, v19, 0x3e0375d0
	v_fma_f32 v19, v20, v19, v20
	v_cmp_ngt_f32_e32 vcc, 1.0, v20
	s_nop 1
	v_cndmask_b32_e32 v19, v19, v21, vcc
	v_bfi_b32 v16, s37, v17, v16
	v_mul_f32_e32 v8, 0.5, v8
	v_add_f32_e32 v16, 1.0, v16
	v_mul_f32_e32 v16, v8, v16
	v_bfi_b32 v8, s37, v15, v14
	v_mul_f32_e32 v7, 0.5, v7
	v_add_f32_e32 v8, 1.0, v8
	v_mul_f32_e32 v8, v7, v8
	v_bfi_b32 v7, s37, v13, v12
	v_readlane_b32 s6, v252, 33
	v_mul_f32_e32 v6, 0.5, v6
	v_add_f32_e32 v7, 1.0, v7
	v_readlane_b32 s7, v252, 34
	v_mul_f32_e32 v12, v6, v7
	v_mul_f32_e32 v9, 0.5, v9
	v_lshl_add_u64 v[6:7], s[6:7], 0, v[10:11]
	v_bfi_b32 v10, s37, v19, v18
	v_add_f32_e32 v10, 1.0, v10
	v_mul_f32_e32 v9, v9, v10
	v_lshl_add_u64 v[6:7], v[182:183], 1, v[6:7]
	v_cvt_pk_bf16_f32 v8, v12, v8
	v_cvt_pk_bf16_f32 v9, v16, v9
	global_store_dwordx2 v[6:7], v[8:9], off offset:-1952

; DI void st_bf4(u16* p, float a, float b, float c, float d) { *(uint2*)p = make_uint2(pk2(a, b), pk2(c, d)); }
; DI float gelu_f(float x) { return 0.5f * x * (1.f + erff(x * 0.70710678118654752f)); }
;   template <int NT, int MT> DI void run(f32x4 (&acc)[NT][MT], int mb, int nb) const {
;     ...
;         } else if (n < 3072) {
;           st_bf4(uvbuf + (size_t)m * 2048 + (n - 1024), gelu_f(v[0]), gelu_f(v[1]), gelu_f(v[2]), gelu_f(v[3]));
.LBB0_830:
	s_andn2_saveexec_b64 s[38:39], s[38:39]
	s_cbranch_execz .LBB0_848
	v_mul_f32_e32 v1, 0x3f3504f3, v2
	v_and_b32_e32 v9, 0x7fffffff, v1
	v_fmamk_f32 v10, v9, 0x378e98ab, v222
	v_fmaak_f32 v10, v9, v10, 0x3b7cd369
	v_fmaak_f32 v10, v9, v10, 0xbcc618b2
	v_fmaak_f32 v10, v9, v10, 0x3dda74e4
	v_fmaak_f32 v10, v9, v10, 0x3f228afd
	v_fmaak_f32 v10, v9, v10, 0x3e03c728
	v_fma_f32 v10, v9, v10, v9
	v_mul_f32_e32 v10, 0xbfb8aa3b, v10
	v_exp_f32_e32 v10, v10
	v_mul_f32_e32 v11, v1, v1
	v_sub_f32_e32 v10, 1.0, v10
	v_fmamk_f32 v8, v11, 0xba1345e1, v200
	v_fmaak_f32 v8, v11, v8, 0xbcdac9b8
	v_fmaak_f32 v8, v11, v8, 0x3de703be
	v_fmaak_f32 v8, v11, v8, 0xbec09330
	v_fmaak_f32 v8, v11, v8, 0x3e0375d0
	v_fma_f32 v8, v9, v8, v9
	v_cmp_ngt_f32_e32 vcc, 1.0, v9
	s_nop 1
	v_cndmask_b32_e32 v8, v8, v10, vcc
	v_mul_f32_e32 v9, 0x3f3504f3, v3
	v_and_b32_e32 v11, 0x7fffffff, v9
	v_fmamk_f32 v12, v11, 0x378e98ab, v222
	v_fmaak_f32 v12, v11, v12, 0x3b7cd369
	v_fmaak_f32 v12, v11, v12, 0xbcc618b2
	v_fmaak_f32 v12, v11, v12, 0x3dda74e4
	v_fmaak_f32 v12, v11, v12, 0x3f228afd
	v_fmaak_f32 v12, v11, v12, 0x3e03c728
	v_fma_f32 v12, v11, v12, v11
	v_mul_f32_e32 v12, 0xbfb8aa3b, v12
	v_exp_f32_e32 v12, v12
	v_mul_f32_e32 v13, v9, v9
	v_sub_f32_e32 v12, 1.0, v12
	v_fmamk_f32 v10, v13, 0xba1345e1, v200
	v_fmaak_f32 v10, v13, v10, 0xbcdac9b8
	v_fmaak_f32 v10, v13, v10, 0x3de703be
	v_fmaak_f32 v10, v13, v10, 0xbec09330
	v_fmaak_f32 v10, v13, v10, 0x3e0375d0
	v_fma_f32 v10, v11, v10, v11
	v_cmp_ngt_f32_e32 vcc, 1.0, v11
	s_nop 1
	v_cndmask_b32_e32 v10, v10, v12, vcc
	v_mul_f32_e32 v11, 0x3f3504f3, v4
	v_and_b32_e32 v13, 0x7fffffff, v11
	v_fmamk_f32 v14, v13, 0x378e98ab, v222
	v_fmaak_f32 v14, v13, v14, 0x3b7cd369
	v_fmaak_f32 v14, v13, v14, 0xbcc618b2
	v_fmaak_f32 v14, v13, v14, 0x3dda74e4
	v_fmaak_f32 v14, v13, v14, 0x3f228afd
	v_fmaak_f32 v14, v13, v14, 0x3e03c728
	v_fma_f32 v14, v13, v14, v13
	v_mul_f32_e32 v14, 0xbfb8aa3b, v14
	v_exp_f32_e32 v14, v14
	v_mul_f32_e32 v15, v11, v11
	v_sub_f32_e32 v14, 1.0, v14
	v_fmamk_f32 v12, v15, 0xba1345e1, v200
	v_fmaak_f32 v12, v15, v12, 0xbcdac9b8
	v_fmaak_f32 v12, v15, v12, 0x3de703be
	v_fmaak_f32 v12, v15, v12, 0xbec09330
	v_fmaak_f32 v12, v15, v12, 0x3e0375d0
	v_fma_f32 v12, v13, v12, v13
	v_cmp_ngt_f32_e32 vcc, 1.0, v13
	s_nop 1
	v_cndmask_b32_e32 v12, v12, v14, vcc
	v_mul_f32_e32 v13, 0x3f3504f3, v5
	v_and_b32_e32 v15, 0x7fffffff, v13
	v_fmamk_f32 v16, v15, 0x378e98ab, v222
	v_fmaak_f32 v16, v15, v16, 0x3b7cd369
	v_fmaak_f32 v16, v15, v16, 0xbcc618b2
	v_fmaak_f32 v16, v15, v16, 0x3dda74e4
	v_fmaak_f32 v16, v15, v16, 0x3f228afd
	v_fmaak_f32 v16, v15, v16, 0x3e03c728
	v_fma_f32 v16, v15, v16, v15
	v_mul_f32_e32 v16, 0xbfb8aa3b, v16
	v_exp_f32_e32 v16, v16
	v_mul_f32_e32 v17, v13, v13
	v_sub_f32_e32 v16, 1.0, v16
	v_fmamk_f32 v14, v17, 0xba1345e1, v200
	v_fmaak_f32 v14, v17, v14, 0xbcdac9b8
	v_fmaak_f32 v14, v17, v14, 0x3de703be
	v_fmaak_f32 v14, v17, v14, 0xbec09330
	v_fmaak_f32 v14, v17, v14, 0x3e0375d0
	v_fma_f32 v14, v15, v14, v15
	v_cmp_ngt_f32_e32 vcc, 1.0, v15
	s_nop 1
	v_cndmask_b32_e32 v14, v14, v16, vcc
	v_bfi_b32 v11, s37, v12, v11
	v_mul_f32_e32 v4, 0.5, v4
	v_add_f32_e32 v11, 1.0, v11
	v_mul_f32_e32 v11, v4, v11
	v_bfi_b32 v4, s37, v10, v9
	v_bfi_b32 v1, s37, v8, v1
	v_readlane_b32 s6, v252, 33
	v_mul_f32_e32 v3, 0.5, v3
	v_add_f32_e32 v4, 1.0, v4
	v_mul_f32_e32 v2, 0.5, v2
	v_add_f32_e32 v1, 1.0, v1
	v_readlane_b32 s7, v252, 34
	v_mul_f32_e32 v4, v3, v4
	v_mul_f32_e32 v1, v2, v1
	v_lshl_add_u64 v[2:3], s[6:7], 0, v[6:7]
	v_bfi_b32 v6, s37, v14, v13
	v_mul_f32_e32 v5, 0.5, v5
	v_add_f32_e32 v6, 1.0, v6
	v_mul_f32_e32 v5, v5, v6
	v_lshl_add_u64 v[2:3], v[182:183], 1, v[2:3]
	v_cvt_pk_bf16_f32 v4, v1, v4
	v_cvt_pk_bf16_f32 v5, v11, v5
	global_store_dwordx2 v[2:3], v[4:5], off offset:-1952

; template <int MT, class Epi>
; DI void gemm_tile(const u16* __restrict__ X, long ldx, const u16* __restrict__ W, long ldw, int K, char* smem,
;                   int m0, int n0, const Epi& epi, bool pre = false, const u16* Xn = nullptr, const u16* Wn = nullptr) {
;     ...
;   do {
;     asm volatile("s_waitcnt vmcnt(0)" ::: "memory");
;     __syncthreads();
;     if (kt + 1 < nk) GT_DMA((unsigned)((kt + 1) & 1) * 32768u)
;     else if (Xn != nullptr) { xe = Xn + oxe; xo = Xn + oxo; we = Wn + owe; wo = Wn + owo; GT_DMA(0u) }
;     const char* cur = smem + (kt & 1) * 32768;
; #pragma unroll
;     for (int ks = 0; ks < 2; ++ks) {
;       bf16x8 xf[MT], wf[4];
;       const int ch = ((ks * 4 + g) ^ rsw) << 4;
; #pragma unroll
;       for (int i = 0; i < MT; ++i) xf[i] = *(const bf16x8*)(cur + (wm * 16 * MT + i * 16 + lr) * 128 + ch);
; #pragma unroll
;       for (int i = 0; i < 4; ++i) wf[i] = *(const bf16x8*)(cur + 16384 + (wn * 64 + i * 16 + lr) * 128 + ch);
; #pragma unroll
;       for (int nt = 0; nt < 4; ++nt)
; #pragma unroll
;         for (int mt = 0; mt < MT; ++mt)
;           acc[nt][mt] = __builtin_amdgcn_mfma_f32_16x16x32_bf16(wf[nt], xf[mt], acc[nt][mt], 0, 0, 0);
;     }
;   } while (++kt < nk);
.LBB0_1026:
	s_add_i32 s7, s8, 0x8000
	v_lshl_add_u64 v[124:125], v[74:75], 0, s[40:41]
	s_and_b32 s9, s7, 0x8000
	v_lshl_add_u64 v[122:123], v[72:73], 0, s[40:41]
	v_lshl_add_u64 v[126:127], v[124:125], 0, s[74:75]
	s_waitcnt vmcnt(0)
	s_waitcnt lgkmcnt(0)
	s_barrier
	s_and_b32 s8, s8, 0x8000
	v_or_b32_e32 v162, s8, v84
	v_add3_u32 v163, v162, v80, v81
	v_add3_u32 v164, v162, v83, v81
	v_or_b32_e32 v165, s8, v82
	v_add3_u32 v166, v165, v80, v81
	v_add3_u32 v167, v165, v83, v81
	ds_read_b128 v[86:89], v163
	ds_read_b128 v[90:93], v163 offset:2048
	ds_read_b128 v[94:97], v163 offset:4096
	ds_read_b128 v[98:101], v163 offset:6144
	ds_read_b128 v[102:105], v164 offset:16384
	ds_read_b128 v[106:109], v164 offset:18432
	ds_read_b128 v[110:113], v164 offset:20480
	ds_read_b128 v[114:117], v164 offset:22528
	ds_read_b128 v[130:133], v166
	ds_read_b128 v[134:137], v166 offset:2048
	ds_read_b128 v[138:141], v166 offset:4096
	ds_read_b128 v[142:145], v166 offset:6144
	ds_read_b128 v[146:149], v167 offset:16384
	ds_read_b128 v[150:153], v167 offset:18432
	ds_read_b128 v[154:157], v167 offset:20480
	ds_read_b128 v[158:161], v167 offset:22528
	s_add_i32 s10, s9, s5
	s_mov_b32 s11, m0
	s_mov_b32 m0, s10
	s_nop 0
	global_load_lds_dwordx4 v[126:127], off
	s_mov_b32 m0, s11
	v_lshl_add_u64 v[126:127], v[122:123], 0, s[94:95]
	s_add_i32 s11, s10, 0x400
	s_mov_b32 s12, m0
	s_mov_b32 m0, s11
	s_nop 0
	global_load_lds_dwordx4 v[126:127], off
	s_mov_b32 m0, s12
	v_lshl_add_u64 v[124:125], v[124:125], 0, s[76:77]
	s_add_i32 s11, s10, 0x800
	s_mov_b32 s12, m0
	s_mov_b32 m0, s11
	s_nop 0
	global_load_lds_dwordx4 v[124:125], off
	s_mov_b32 m0, s12
	v_lshl_add_u64 v[120:121], v[70:71], 0, s[40:41]
	v_lshl_add_u64 v[122:123], v[122:123], 0, s[54:55]
	s_addk_i32 s10, 0xc00
	s_mov_b32 s11, m0
	s_mov_b32 m0, s10
	s_nop 0
	global_load_lds_dwordx4 v[122:123], off
	s_mov_b32 m0, s11
	v_lshl_add_u64 v[118:119], v[68:69], 0, s[40:41]
	v_lshl_add_u64 v[128:129], v[120:121], 0, s[28:29]
	s_add_i32 s9, s9, s6
	s_mov_b32 s10, m0
	s_mov_b32 m0, s9
	s_nop 0
	global_load_lds_dwordx4 v[128:129], off
	s_mov_b32 m0, s10
	v_lshl_add_u64 v[122:123], v[118:119], 0, s[94:95]
	s_add_i32 s10, s9, 0x400
	s_mov_b32 s11, m0
	s_mov_b32 m0, s10
	s_nop 0
	global_load_lds_dwordx4 v[122:123], off
	s_mov_b32 m0, s11
	v_lshl_add_u64 v[120:121], v[120:121], 0, s[78:79]
	s_add_i32 s10, s9, 0x800
	s_mov_b32 s11, m0
	s_mov_b32 m0, s10
	s_nop 0
	global_load_lds_dwordx4 v[120:121], off
	s_mov_b32 m0, s11
	v_lshl_add_u64 v[118:119], v[118:119], 0, s[54:55]
	s_addk_i32 s9, 0xc00
	s_mov_b32 s10, m0
	s_mov_b32 m0, s9
	s_nop 0
	global_load_lds_dwordx4 v[118:119], off
	s_mov_b32 m0, s10
	s_mov_b32 s8, s7
	s_add_u32 s40, s40, 0x80
	s_addc_u32 s41, s41, 0
	s_cmpk_lg_i32 s40, 0x780
	s_waitcnt lgkmcnt(11)
	v_mfma_f32_16x16x32_bf16 v[48:51], v[102:105], v[98:101], v[48:51]
	s_waitcnt lgkmcnt(10)
	v_mfma_f32_16x16x32_bf16 v[32:35], v[106:109], v[98:101], v[32:35]
	s_waitcnt lgkmcnt(9)
	v_mfma_f32_16x16x32_bf16 v[16:19], v[110:113], v[98:101], v[16:19]
	s_waitcnt lgkmcnt(8)
	v_mfma_f32_16x16x32_bf16 v[0:3], v[114:117], v[98:101], v[0:3]
	v_mfma_f32_16x16x32_bf16 v[60:63], v[102:105], v[86:89], v[60:63]
	v_mfma_f32_16x16x32_bf16 v[56:59], v[102:105], v[90:93], v[56:59]
	v_mfma_f32_16x16x32_bf16 v[52:55], v[102:105], v[94:97], v[52:55]
	v_mfma_f32_16x16x32_bf16 v[44:47], v[106:109], v[86:89], v[44:47]
	v_mfma_f32_16x16x32_bf16 v[40:43], v[106:109], v[90:93], v[40:43]
	v_mfma_f32_16x16x32_bf16 v[36:39], v[106:109], v[94:97], v[36:39]
	v_mfma_f32_16x16x32_bf16 v[28:31], v[110:113], v[86:89], v[28:31]
	v_mfma_f32_16x16x32_bf16 v[24:27], v[110:113], v[90:93], v[24:27]
	v_mfma_f32_16x16x32_bf16 v[20:23], v[110:113], v[94:97], v[20:23]
	v_mfma_f32_16x16x32_bf16 v[12:15], v[114:117], v[86:89], v[12:15]
	v_mfma_f32_16x16x32_bf16 v[8:11], v[114:117], v[90:93], v[8:11]
	v_mfma_f32_16x16x32_bf16 v[4:7], v[114:117], v[94:97], v[4:7]
	s_waitcnt lgkmcnt(3)
	v_mfma_f32_16x16x32_bf16 v[60:63], v[146:149], v[130:133], v[60:63]
	v_mfma_f32_16x16x32_bf16 v[56:59], v[146:149], v[134:137], v[56:59]
	v_mfma_f32_16x16x32_bf16 v[52:55], v[146:149], v[138:141], v[52:55]
	v_mfma_f32_16x16x32_bf16 v[48:51], v[146:149], v[142:145], v[48:51]
	s_waitcnt lgkmcnt(2)
	v_mfma_f32_16x16x32_bf16 v[44:47], v[150:153], v[130:133], v[44:47]
	v_mfma_f32_16x16x32_bf16 v[40:43], v[150:153], v[134:137], v[40:43]
	v_mfma_f32_16x16x32_bf16 v[36:39], v[150:153], v[138:141], v[36:39]
	v_mfma_f32_16x16x32_bf16 v[32:35], v[150:153], v[142:145], v[32:35]
	s_waitcnt lgkmcnt(1)
	v_mfma_f32_16x16x32_bf16 v[28:31], v[154:157], v[130:133], v[28:31]
	v_mfma_f32_16x16x32_bf16 v[24:27], v[154:157], v[134:137], v[24:27]
	v_mfma_f32_16x16x32_bf16 v[20:23], v[154:157], v[138:141], v[20:23]
	v_mfma_f32_16x16x32_bf16 v[16:19], v[154:157], v[142:145], v[16:19]
	s_waitcnt lgkmcnt(0)
	v_mfma_f32_16x16x32_bf16 v[12:15], v[158:161], v[130:133], v[12:15]
	v_mfma_f32_16x16x32_bf16 v[8:11], v[158:161], v[134:137], v[8:11]
	v_mfma_f32_16x16x32_bf16 v[4:7], v[158:161], v[138:141], v[4:7]
	v_mfma_f32_16x16x32_bf16 v[0:3], v[158:161], v[142:145], v[0:3]
	s_cbranch_scc1 .LBB0_1026
; DI int get_bid() { int b = blockIdx.x; asm volatile("" : "+s"(b)); return b; }
; template <int MT, class Epi>
; DI void gemm_tile(const u16* __restrict__ X, long ldx, const u16* __restrict__ W, long ldw, int K, char* smem,
;                   int m0, int n0, const Epi& epi, bool pre = false, const u16* Xn = nullptr, const u16* Wn = nullptr) {
;     ...
;   do {
;     asm volatile("s_waitcnt vmcnt(0)" ::: "memory");
;     __syncthreads();
;     if (kt + 1 < nk) GT_DMA((unsigned)((kt + 1) & 1) * 32768u)
;     else if (Xn != nullptr) { xe = Xn + oxe; xo = Xn + oxo; we = Wn + owe; wo = Wn + owo; GT_DMA(0u) }
; DI void phase_odd(const Params& p, int o, int sub, char* smem) {
;     ...
;     for (int t = get_bid(); t < 132 * 14; t += gridDim.x) {
;       const int tm = t / 14, tn = t % 14;
;       const int t2 = t + gridDim.x, tm2 = t2 / 14, tn2 = t2 % 14;
;       const bool nx = t2 < 132 * 14;
;       gemm_tile<4>(hbuf + (size_t)tm * 128 * 1024, 1024, W + WO_IN + (size_t)tn * 128 * 1024, 1024, 1024, smem, tm * 128, tn * 128, epi, pre,
;                    nx ? hbuf + (size_t)tm2 * 128 * 1024 : nullptr, W + WO_IN + (size_t)tn2 * 128 * 1024);
;       pre = nx;
	v_readlane_b32 s8, v255, 5
	v_readlane_b32 s14, v255, 11
	s_add_i32 s4, s4, s14
	s_mul_hi_i32 s7, s4, 0x92492493
	s_add_i32 s7, s7, s4
	s_lshr_b32 s8, s7, 31
	s_ashr_i32 s7, s7, 3
	s_add_i32 s46, s7, s8
	s_cmpk_gt_i32 s4, 0x737
	v_readlane_b32 s9, v255, 6
	s_cselect_b64 s[40:41], -1, 0
	s_ashr_i32 s47, s46, 31
	s_lshl_b64 s[8:9], s[46:47], 18
	s_add_u32 s7, s0, s8
	s_addc_u32 s8, s1, s9
	s_cmpk_lt_i32 s4, 0x738
	s_waitcnt vmcnt(0)
	s_cselect_b32 s45, s8, 0
	s_cselect_b32 s44, s7, 0
	v_readlane_b32 s12, v255, 9
	v_readlane_b32 s13, v255, 10
	s_cmp_eq_u64 s[44:45], 0
	v_readlane_b32 s10, v255, 7
	v_readlane_b32 s11, v255, 8
	v_readlane_b32 s15, v255, 12
	s_barrier
	s_cbranch_scc1 .LBB0_1029
	s_mul_i32 s7, s46, 14
	s_sub_i32 s8, s4, s7
	s_ashr_i32 s9, s8, 31
	s_lshl_b64 s[8:9], s[8:9], 18
	s_add_u32 s8, s12, s8
	s_addc_u32 s9, s13, s9
	v_lshl_add_u64 v[68:69], s[44:45], 0, v[66:67]
	v_lshl_add_u64 v[70:71], s[8:9], 0, v[64:65]
	v_lshl_add_u64 v[64:65], s[44:45], 0, v[64:65]
	s_mov_b32 s7, m0
	s_mov_b32 m0, s5
	s_nop 0
	global_load_lds_dwordx4 v[68:69], off
	s_mov_b32 m0, s7
	s_mov_b64 s[10:11], 0x4000
	v_lshl_add_u64 v[66:67], s[8:9], 0, v[66:67]
	v_lshl_add_u64 v[72:73], v[64:65], 0, s[10:11]
	s_add_i32 s7, s5, 0x400
	s_mov_b32 s8, m0
	s_mov_b32 m0, s7
	s_nop 0
	global_load_lds_dwordx4 v[72:73], off
	s_mov_b32 m0, s8
	s_mov_b64 s[12:13], 0x8000
	v_lshl_add_u64 v[68:69], v[68:69], 0, s[12:13]
	s_add_i32 s7, s5, 0x800
	s_mov_b32 s8, m0
	s_mov_b32 m0, s7
	s_nop 0
	global_load_lds_dwordx4 v[68:69], off
	s_mov_b32 m0, s8
	s_mov_b64 s[14:15], 0xc000
	v_lshl_add_u64 v[64:65], v[64:65], 0, s[14:15]
	s_add_i32 s7, s5, 0xc00
	s_mov_b32 s8, m0
	s_mov_b32 m0, s7
	s_nop 0
	global_load_lds_dwordx4 v[64:65], off
	s_mov_b32 m0, s8
	s_mov_b32 s7, m0
	s_mov_b32 m0, s6
	s_nop 0
	global_load_lds_dwordx4 v[66:67], off
	s_mov_b32 m0, s7
	v_lshl_add_u64 v[64:65], v[70:71], 0, s[10:11]
	s_add_i32 s6, s5, 0x4400
	s_mov_b32 s7, m0
	s_mov_b32 m0, s6
	s_nop 0
	global_load_lds_dwordx4 v[64:65], off
	s_mov_b32 m0, s7
	v_lshl_add_u64 v[64:65], v[66:67], 0, s[12:13]
	s_add_i32 s6, s5, 0x4800
	s_mov_b32 s7, m0
	s_mov_b32 m0, s6
	s_nop 0
	global_load_lds_dwordx4 v[64:65], off
	s_mov_b32 m0, s7
	v_lshl_add_u64 v[64:65], v[70:71], 0, s[14:15]
	s_addk_i32 s5, 0x4c00
	s_mov_b32 s6, m0
	s_mov_b32 m0, s5
	s_nop 0
	global_load_lds_dwordx4 v[64:65], off
	s_mov_b32 m0, s6

; template <int MT, class Epi>
; DI void gemm_tile(const u16* __restrict__ X, long ldx, const u16* __restrict__ W, long ldw, int K, char* smem,
;                   int m0, int n0, const Epi& epi, bool pre = false, const u16* Xn = nullptr, const u16* Wn = nullptr) {
;     ...
;   if (!pre) {
;     __syncthreads();
;     GT_DMA(0u)
;   } else {
;     xe += 64; xo += 64; we += 64; wo += 64;
;   }
;   const int nk = K >> 6;
;   int kt = 0;
;   do {
;     asm volatile("s_waitcnt vmcnt(0)" ::: "memory");
;     __syncthreads();
;     if (kt + 1 < nk) GT_DMA((unsigned)((kt + 1) & 1) * 32768u)
;     else if (Xn != nullptr) { xe = Xn + oxe; xo = Xn + oxo; we = Wn + owe; wo = Wn + owo; GT_DMA(0u) }
;     const char* cur = smem + (kt & 1) * 32768;
; #pragma unroll
;     for (int ks = 0; ks < 2; ++ks) {
;       bf16x8 xf[MT], wf[4];
;       const int ch = ((ks * 4 + g) ^ rsw) << 4;
; #pragma unroll
;       for (int i = 0; i < MT; ++i) xf[i] = *(const bf16x8*)(cur + (wm * 16 * MT + i * 16 + lr) * 128 + ch);
; #pragma unroll
;       for (int i = 0; i < 4; ++i) wf[i] = *(const bf16x8*)(cur + 16384 + (wn * 64 + i * 16 + lr) * 128 + ch);
; #pragma unroll
;       for (int nt = 0; nt < 4; ++nt)
; #pragma unroll
;         for (int mt = 0; mt < MT; ++mt)
;           acc[nt][mt] = __builtin_amdgcn_mfma_f32_16x16x32_bf16(wf[nt], xf[mt], acc[nt][mt], 0, 0, 0);
;     }
;   } while (++kt < nk);
.LBB0_1312:
	s_add_i32 s7, s8, 0x8000
	v_lshl_add_u64 v[124:125], v[74:75], 0, s[40:41]
	s_and_b32 s9, s7, 0x8000
	v_lshl_add_u64 v[122:123], v[72:73], 0, s[40:41]
	v_lshl_add_u64 v[126:127], v[124:125], 0, s[74:75]
	s_waitcnt vmcnt(0)
	s_waitcnt lgkmcnt(0)
	s_barrier
	s_and_b32 s8, s8, 0x8000
	v_or_b32_e32 v162, s8, v84
	v_add3_u32 v163, v162, v80, v81
	v_add3_u32 v164, v162, v83, v81
	v_or_b32_e32 v165, s8, v82
	v_add3_u32 v166, v165, v80, v81
	v_add3_u32 v167, v165, v83, v81
	ds_read_b128 v[86:89], v163
	ds_read_b128 v[90:93], v163 offset:2048
	ds_read_b128 v[94:97], v163 offset:4096
	ds_read_b128 v[98:101], v163 offset:6144
	ds_read_b128 v[102:105], v164 offset:16384
	ds_read_b128 v[106:109], v164 offset:18432
	ds_read_b128 v[110:113], v164 offset:20480
	ds_read_b128 v[114:117], v164 offset:22528
	ds_read_b128 v[130:133], v166
	ds_read_b128 v[134:137], v166 offset:2048
	ds_read_b128 v[138:141], v166 offset:4096
	ds_read_b128 v[142:145], v166 offset:6144
	ds_read_b128 v[146:149], v167 offset:16384
	ds_read_b128 v[150:153], v167 offset:18432
	ds_read_b128 v[154:157], v167 offset:20480
	ds_read_b128 v[158:161], v167 offset:22528
	s_add_i32 s10, s9, s5
	s_mov_b32 s11, m0
	s_mov_b32 m0, s10
	s_nop 0
	global_load_lds_dwordx4 v[126:127], off
	s_mov_b32 m0, s11
	v_lshl_add_u64 v[126:127], v[122:123], 0, s[94:95]
	s_add_i32 s11, s10, 0x400
	s_mov_b32 s12, m0
	s_mov_b32 m0, s11
	s_nop 0
	global_load_lds_dwordx4 v[126:127], off
	s_mov_b32 m0, s12
	v_lshl_add_u64 v[124:125], v[124:125], 0, s[76:77]
	s_add_i32 s11, s10, 0x800
	s_mov_b32 s12, m0
	s_mov_b32 m0, s11
	s_nop 0
	global_load_lds_dwordx4 v[124:125], off
	s_mov_b32 m0, s12
	v_lshl_add_u64 v[120:121], v[70:71], 0, s[40:41]
	v_lshl_add_u64 v[122:123], v[122:123], 0, s[54:55]
	s_addk_i32 s10, 0xc00
	s_mov_b32 s11, m0
	s_mov_b32 m0, s10
	s_nop 0
	global_load_lds_dwordx4 v[122:123], off
	s_mov_b32 m0, s11
	v_lshl_add_u64 v[118:119], v[68:69], 0, s[40:41]
	v_lshl_add_u64 v[128:129], v[120:121], 0, s[28:29]
	s_add_i32 s9, s9, s6
	s_mov_b32 s10, m0
	s_mov_b32 m0, s9
	s_nop 0
	global_load_lds_dwordx4 v[128:129], off
	s_mov_b32 m0, s10
	v_lshl_add_u64 v[122:123], v[118:119], 0, s[94:95]
	s_add_i32 s10, s9, 0x400
	s_mov_b32 s11, m0
	s_mov_b32 m0, s10
	s_nop 0
	global_load_lds_dwordx4 v[122:123], off
	s_mov_b32 m0, s11
	v_lshl_add_u64 v[120:121], v[120:121], 0, s[78:79]
	s_add_i32 s10, s9, 0x800
	s_mov_b32 s11, m0
	s_mov_b32 m0, s10
	s_nop 0
	global_load_lds_dwordx4 v[120:121], off
	s_mov_b32 m0, s11
	v_lshl_add_u64 v[118:119], v[118:119], 0, s[54:55]
	s_addk_i32 s9, 0xc00
	s_mov_b32 s10, m0
	s_mov_b32 m0, s9
	s_nop 0
	global_load_lds_dwordx4 v[118:119], off
	s_mov_b32 m0, s10
	s_mov_b32 s8, s7
	s_add_u32 s40, s40, 0x80
	s_addc_u32 s41, s41, 0
	s_cmpk_lg_i32 s40, 0x780
	s_waitcnt lgkmcnt(11)
	v_mfma_f32_16x16x32_bf16 v[48:51], v[102:105], v[98:101], v[48:51]
	s_waitcnt lgkmcnt(10)
	v_mfma_f32_16x16x32_bf16 v[32:35], v[106:109], v[98:101], v[32:35]
	s_waitcnt lgkmcnt(9)
	v_mfma_f32_16x16x32_bf16 v[16:19], v[110:113], v[98:101], v[16:19]
	s_waitcnt lgkmcnt(8)
	v_mfma_f32_16x16x32_bf16 v[0:3], v[114:117], v[98:101], v[0:3]
	v_mfma_f32_16x16x32_bf16 v[60:63], v[102:105], v[86:89], v[60:63]
	v_mfma_f32_16x16x32_bf16 v[56:59], v[102:105], v[90:93], v[56:59]
	v_mfma_f32_16x16x32_bf16 v[52:55], v[102:105], v[94:97], v[52:55]
	v_mfma_f32_16x16x32_bf16 v[44:47], v[106:109], v[86:89], v[44:47]
	v_mfma_f32_16x16x32_bf16 v[40:43], v[106:109], v[90:93], v[40:43]
	v_mfma_f32_16x16x32_bf16 v[36:39], v[106:109], v[94:97], v[36:39]
	v_mfma_f32_16x16x32_bf16 v[28:31], v[110:113], v[86:89], v[28:31]
	v_mfma_f32_16x16x32_bf16 v[24:27], v[110:113], v[90:93], v[24:27]
	v_mfma_f32_16x16x32_bf16 v[20:23], v[110:113], v[94:97], v[20:23]
	v_mfma_f32_16x16x32_bf16 v[12:15], v[114:117], v[86:89], v[12:15]
	v_mfma_f32_16x16x32_bf16 v[8:11], v[114:117], v[90:93], v[8:11]
	v_mfma_f32_16x16x32_bf16 v[4:7], v[114:117], v[94:97], v[4:7]
	s_waitcnt lgkmcnt(3)
	v_mfma_f32_16x16x32_bf16 v[60:63], v[146:149], v[130:133], v[60:63]
	v_mfma_f32_16x16x32_bf16 v[56:59], v[146:149], v[134:137], v[56:59]
	v_mfma_f32_16x16x32_bf16 v[52:55], v[146:149], v[138:141], v[52:55]
	v_mfma_f32_16x16x32_bf16 v[48:51], v[146:149], v[142:145], v[48:51]
	s_waitcnt lgkmcnt(2)
	v_mfma_f32_16x16x32_bf16 v[44:47], v[150:153], v[130:133], v[44:47]
	v_mfma_f32_16x16x32_bf16 v[40:43], v[150:153], v[134:137], v[40:43]
	v_mfma_f32_16x16x32_bf16 v[36:39], v[150:153], v[138:141], v[36:39]
	v_mfma_f32_16x16x32_bf16 v[32:35], v[150:153], v[142:145], v[32:35]
	s_waitcnt lgkmcnt(1)
	v_mfma_f32_16x16x32_bf16 v[28:31], v[154:157], v[130:133], v[28:31]
	v_mfma_f32_16x16x32_bf16 v[24:27], v[154:157], v[134:137], v[24:27]
	v_mfma_f32_16x16x32_bf16 v[20:23], v[154:157], v[138:141], v[20:23]
	v_mfma_f32_16x16x32_bf16 v[16:19], v[154:157], v[142:145], v[16:19]
	s_waitcnt lgkmcnt(0)
	v_mfma_f32_16x16x32_bf16 v[12:15], v[158:161], v[130:133], v[12:15]
	v_mfma_f32_16x16x32_bf16 v[8:11], v[158:161], v[134:137], v[8:11]
	v_mfma_f32_16x16x32_bf16 v[4:7], v[158:161], v[138:141], v[4:7]
	v_mfma_f32_16x16x32_bf16 v[0:3], v[158:161], v[142:145], v[0:3]
	s_cbranch_scc1 .LBB0_1312
; DI int get_bid() { int b = blockIdx.x; asm volatile("" : "+s"(b)); return b; }
; template <int MT, class Epi>
; DI void gemm_tile(const u16* __restrict__ X, long ldx, const u16* __restrict__ W, long ldw, int K, char* smem,
;                   int m0, int n0, const Epi& epi, bool pre = false, const u16* Xn = nullptr, const u16* Wn = nullptr) {
;     ...
;     if (kt + 1 < nk) GT_DMA((unsigned)((kt + 1) & 1) * 32768u)
;     else if (Xn != nullptr) { xe = Xn + oxe; xo = Xn + oxo; we = Wn + owe; wo = Wn + owo; GT_DMA(0u) }
; DI void phase_even(const Params& p, int e, int sub, char* smem) {
;     ...
;     for (int t = get_bid(); t < 132 * 40; t += gridDim.x) {
;       const int tm = t / 40, tn = t % 40;
;       const int t2 = t + gridDim.x, tm2 = t2 / 40, tn2 = t2 % 40;
;       const bool nx = t2 < 132 * 40;
;       gemm_tile<4>(hbuf + (size_t)tm * 128 * 1024, 1024, W + WE_IN + (size_t)tn * 128 * 1024, 1024, 1024, smem, tm * 128, tn * 128, epi, pre,
;                    nx ? hbuf + (size_t)tm2 * 128 * 1024 : nullptr, W + WE_IN + (size_t)tn2 * 128 * 1024);
;       pre = nx;
;     }
	v_readlane_b32 s8, v255, 5
	v_readlane_b32 s14, v255, 11
	s_add_i32 s4, s4, s14
	s_mul_hi_i32 s7, s4, 0x66666667
	s_lshr_b32 s8, s7, 31
	s_ashr_i32 s7, s7, 4
	s_add_i32 s46, s7, s8
	s_cmpk_gt_i32 s4, 0x149f
	v_readlane_b32 s9, v255, 6
	s_cselect_b64 s[44:45], -1, 0
	s_ashr_i32 s47, s46, 31
	s_lshl_b64 s[8:9], s[46:47], 18
	s_add_u32 s7, s0, s8
	s_addc_u32 s8, s1, s9
	s_cmpk_lt_i32 s4, 0x14a0
	s_waitcnt vmcnt(0)
	s_cselect_b32 s41, s8, 0
	s_cselect_b32 s40, s7, 0
	v_readlane_b32 s12, v255, 9
	v_readlane_b32 s13, v255, 10
	s_cmp_eq_u64 s[40:41], 0
	v_readlane_b32 s10, v255, 7
	v_readlane_b32 s11, v255, 8
	v_readlane_b32 s15, v255, 12
	s_barrier
	s_cbranch_scc1 .LBB0_1315
	s_mul_i32 s7, s46, 40
	s_sub_i32 s8, s4, s7
	s_ashr_i32 s9, s8, 31
	s_lshl_b64 s[8:9], s[8:9], 18
	s_add_u32 s8, s12, s8
	s_addc_u32 s9, s13, s9
	v_lshl_add_u64 v[68:69], s[40:41], 0, v[66:67]
	v_lshl_add_u64 v[70:71], s[8:9], 0, v[64:65]
	v_lshl_add_u64 v[64:65], s[40:41], 0, v[64:65]
	s_mov_b32 s7, m0
	s_mov_b32 m0, s5
	s_nop 0
	global_load_lds_dwordx4 v[68:69], off
	s_mov_b32 m0, s7
	s_mov_b64 s[10:11], 0x4000
	v_lshl_add_u64 v[66:67], s[8:9], 0, v[66:67]
	v_lshl_add_u64 v[72:73], v[64:65], 0, s[10:11]
	s_add_i32 s7, s5, 0x400
	s_mov_b32 s8, m0
	s_mov_b32 m0, s7
	s_nop 0
	global_load_lds_dwordx4 v[72:73], off
	s_mov_b32 m0, s8
	s_mov_b64 s[12:13], 0x8000
	v_lshl_add_u64 v[68:69], v[68:69], 0, s[12:13]
	s_add_i32 s7, s5, 0x800
	s_mov_b32 s8, m0
	s_mov_b32 m0, s7
	s_nop 0
	global_load_lds_dwordx4 v[68:69], off
	s_mov_b32 m0, s8
	s_mov_b64 s[14:15], 0xc000
	v_lshl_add_u64 v[64:65], v[64:65], 0, s[14:15]
	s_add_i32 s7, s5, 0xc00
	s_mov_b32 s8, m0
	s_mov_b32 m0, s7
	s_nop 0
	global_load_lds_dwordx4 v[64:65], off
	s_mov_b32 m0, s8
	s_mov_b32 s7, m0
	s_mov_b32 m0, s6
	s_nop 0
	global_load_lds_dwordx4 v[66:67], off
	s_mov_b32 m0, s7
	v_lshl_add_u64 v[64:65], v[70:71], 0, s[10:11]
	s_add_i32 s6, s5, 0x4400
	s_mov_b32 s7, m0
	s_mov_b32 m0, s6
	s_nop 0
	global_load_lds_dwordx4 v[64:65], off
	s_mov_b32 m0, s7
	v_lshl_add_u64 v[64:65], v[66:67], 0, s[12:13]
	s_add_i32 s6, s5, 0x4800
	s_mov_b32 s7, m0
	s_mov_b32 m0, s6
	s_nop 0
	global_load_lds_dwordx4 v[64:65], off
	s_mov_b32 m0, s7
	v_lshl_add_u64 v[64:65], v[70:71], 0, s[14:15]
	s_addk_i32 s5, 0x4c00
	s_mov_b32 s6, m0
	s_mov_b32 m0, s5
	s_nop 0
	global_load_lds_dwordx4 v[64:65], off
	s_mov_b32 m0, s6

; DI void st_bf4(u16* p, float a, float b, float c, float d) { *(uint2*)p = make_uint2(pk2(a, b), pk2(c, d)); }
; DI float gelu_f(float x) { return 0.5f * x * (1.f + erff(x * 0.70710678118654752f)); }
;   template <int NT, int MT> DI void run(f32x4 (&acc)[NT][MT], int mb, int nb) const {
;     ...
;         } else if (n < 3072) {
;           st_bf4(uvbuf + (size_t)m * 2048 + (n - 1024), gelu_f(v[0]), gelu_f(v[1]), gelu_f(v[2]), gelu_f(v[3]));
.LBB0_1318:
	s_andn2_saveexec_b64 s[48:49], s[48:49]
	s_cbranch_execz .LBB0_1336
	v_mul_f32_e32 v69, 0x3f3504f3, v60
	v_and_b32_e32 v71, 0x7fffffff, v69
	v_fmamk_f32 v72, v71, 0x378e98ab, v222
	v_fmaak_f32 v72, v71, v72, 0x3b7cd369
	v_fmaak_f32 v72, v71, v72, 0xbcc618b2
	v_fmaak_f32 v72, v71, v72, 0x3dda74e4
	v_fmaak_f32 v72, v71, v72, 0x3f228afd
	v_fmaak_f32 v72, v71, v72, 0x3e03c728
	v_fma_f32 v72, v71, v72, v71
	v_mul_f32_e32 v72, 0xbfb8aa3b, v72
	v_exp_f32_e32 v72, v72
	v_mul_f32_e32 v73, v69, v69
	v_sub_f32_e32 v72, 1.0, v72
	v_fmamk_f32 v70, v73, 0xba1345e1, v200
	v_fmaak_f32 v70, v73, v70, 0xbcdac9b8
	v_fmaak_f32 v70, v73, v70, 0x3de703be
	v_fmaak_f32 v70, v73, v70, 0xbec09330
	v_fmaak_f32 v70, v73, v70, 0x3e0375d0
	v_fma_f32 v70, v71, v70, v71
	v_cmp_ngt_f32_e32 vcc, 1.0, v71
	s_nop 1
	v_cndmask_b32_e32 v70, v70, v72, vcc
	v_mul_f32_e32 v71, 0x3f3504f3, v61
	v_and_b32_e32 v73, 0x7fffffff, v71
	v_fmamk_f32 v74, v73, 0x378e98ab, v222
	v_fmaak_f32 v74, v73, v74, 0x3b7cd369
	v_fmaak_f32 v74, v73, v74, 0xbcc618b2
	v_fmaak_f32 v74, v73, v74, 0x3dda74e4
	v_fmaak_f32 v74, v73, v74, 0x3f228afd
	v_fmaak_f32 v74, v73, v74, 0x3e03c728
	v_fma_f32 v74, v73, v74, v73
	v_mul_f32_e32 v74, 0xbfb8aa3b, v74
	v_exp_f32_e32 v74, v74
	v_mul_f32_e32 v75, v71, v71
	v_sub_f32_e32 v74, 1.0, v74
	v_fmamk_f32 v72, v75, 0xba1345e1, v200
	v_fmaak_f32 v72, v75, v72, 0xbcdac9b8
	v_fmaak_f32 v72, v75, v72, 0x3de703be
	v_fmaak_f32 v72, v75, v72, 0xbec09330
	v_fmaak_f32 v72, v75, v72, 0x3e0375d0
	v_fma_f32 v72, v73, v72, v73
	v_cmp_ngt_f32_e32 vcc, 1.0, v73
	s_nop 1
	v_cndmask_b32_e32 v72, v72, v74, vcc
	v_mul_f32_e32 v73, 0x3f3504f3, v62
	v_and_b32_e32 v75, 0x7fffffff, v73
	v_fmamk_f32 v76, v75, 0x378e98ab, v222
	v_fmaak_f32 v76, v75, v76, 0x3b7cd369
	v_fmaak_f32 v76, v75, v76, 0xbcc618b2
	v_fmaak_f32 v76, v75, v76, 0x3dda74e4
	v_fmaak_f32 v76, v75, v76, 0x3f228afd
	v_fmaak_f32 v76, v75, v76, 0x3e03c728
	v_fma_f32 v76, v75, v76, v75
	v_mul_f32_e32 v76, 0xbfb8aa3b, v76
	v_exp_f32_e32 v76, v76
	v_mul_f32_e32 v77, v73, v73
	v_sub_f32_e32 v76, 1.0, v76
	v_fmamk_f32 v74, v77, 0xba1345e1, v200
	v_fmaak_f32 v74, v77, v74, 0xbcdac9b8
	v_fmaak_f32 v74, v77, v74, 0x3de703be
	v_fmaak_f32 v74, v77, v74, 0xbec09330
	v_fmaak_f32 v74, v77, v74, 0x3e0375d0
	v_fma_f32 v74, v75, v74, v75
	v_cmp_ngt_f32_e32 vcc, 1.0, v75
	s_nop 1
	v_cndmask_b32_e32 v74, v74, v76, vcc
	v_mul_f32_e32 v75, 0x3f3504f3, v63
	v_and_b32_e32 v77, 0x7fffffff, v75
	v_fmamk_f32 v78, v77, 0x378e98ab, v222
	v_fmaak_f32 v78, v77, v78, 0x3b7cd369
	v_fmaak_f32 v78, v77, v78, 0xbcc618b2
	v_fmaak_f32 v78, v77, v78, 0x3dda74e4
	v_fmaak_f32 v78, v77, v78, 0x3f228afd
	v_fmaak_f32 v78, v77, v78, 0x3e03c728
	v_fma_f32 v78, v77, v78, v77
	v_mul_f32_e32 v78, 0xbfb8aa3b, v78
	v_exp_f32_e32 v78, v78
	v_mul_f32_e32 v79, v75, v75
	v_sub_f32_e32 v78, 1.0, v78
	v_fmamk_f32 v76, v79, 0xba1345e1, v200
	v_fmaak_f32 v76, v79, v76, 0xbcdac9b8
	v_fmaak_f32 v76, v79, v76, 0x3de703be
	v_fmaak_f32 v76, v79, v76, 0xbec09330
	v_fmaak_f32 v76, v79, v76, 0x3e0375d0
	v_fma_f32 v76, v77, v76, v77
	v_cmp_ngt_f32_e32 vcc, 1.0, v77
	s_nop 1
	v_cndmask_b32_e32 v76, v76, v78, vcc
	v_bfi_b32 v73, s37, v74, v73
	v_mul_f32_e32 v62, 0.5, v62
	v_add_f32_e32 v73, 1.0, v73
	v_mul_f32_e32 v73, v62, v73
	v_bfi_b32 v62, s37, v72, v71
	v_mul_f32_e32 v61, 0.5, v61
	v_add_f32_e32 v62, 1.0, v62
	v_mul_f32_e32 v62, v61, v62
	v_bfi_b32 v61, s37, v70, v69
	v_readlane_b32 s6, v252, 33
	v_mul_f32_e32 v60, 0.5, v60
	v_add_f32_e32 v61, 1.0, v61
	v_readlane_b32 s7, v252, 34
	v_mul_f32_e32 v69, v60, v61
	v_mul_f32_e32 v63, 0.5, v63
	v_lshl_add_u64 v[60:61], s[6:7], 0, v[66:67]
	v_bfi_b32 v66, s37, v76, v75
	v_add_f32_e32 v66, 1.0, v66
	v_mul_f32_e32 v63, v63, v66
	v_lshl_add_u64 v[60:61], v[182:183], 1, v[60:61]
	v_cvt_pk_bf16_f32 v62, v69, v62
	v_cvt_pk_bf16_f32 v63, v73, v63
	global_store_dwordx2 v[60:61], v[62:63], off offset:-2048

; DI void st_bf4(u16* p, float a, float b, float c, float d) { *(uint2*)p = make_uint2(pk2(a, b), pk2(c, d)); }
; DI float gelu_f(float x) { return 0.5f * x * (1.f + erff(x * 0.70710678118654752f)); }
;   template <int NT, int MT> DI void run(f32x4 (&acc)[NT][MT], int mb, int nb) const {
;     ...
;         } else if (n < 3072) {
;           st_bf4(uvbuf + (size_t)m * 2048 + (n - 1024), gelu_f(v[0]), gelu_f(v[1]), gelu_f(v[2]), gelu_f(v[3]));
.LBB0_1342:
	s_andn2_saveexec_b64 s[48:49], s[48:49]
	s_cbranch_execz .LBB0_1360
	v_mul_f32_e32 v69, 0x3f3504f3, v56
	v_and_b32_e32 v71, 0x7fffffff, v69
	v_fmamk_f32 v72, v71, 0x378e98ab, v222
	v_fmaak_f32 v72, v71, v72, 0x3b7cd369
	v_fmaak_f32 v72, v71, v72, 0xbcc618b2
	v_fmaak_f32 v72, v71, v72, 0x3dda74e4
	v_fmaak_f32 v72, v71, v72, 0x3f228afd
	v_fmaak_f32 v72, v71, v72, 0x3e03c728
	v_fma_f32 v72, v71, v72, v71
	v_mul_f32_e32 v72, 0xbfb8aa3b, v72
	v_exp_f32_e32 v72, v72
	v_mul_f32_e32 v73, v69, v69
	v_sub_f32_e32 v72, 1.0, v72
	v_fmamk_f32 v70, v73, 0xba1345e1, v200
	v_fmaak_f32 v70, v73, v70, 0xbcdac9b8
	v_fmaak_f32 v70, v73, v70, 0x3de703be
	v_fmaak_f32 v70, v73, v70, 0xbec09330
	v_fmaak_f32 v70, v73, v70, 0x3e0375d0
	v_fma_f32 v70, v71, v70, v71
	v_cmp_ngt_f32_e32 vcc, 1.0, v71
	s_nop 1
	v_cndmask_b32_e32 v70, v70, v72, vcc
	v_mul_f32_e32 v71, 0x3f3504f3, v57
	v_and_b32_e32 v73, 0x7fffffff, v71
	v_fmamk_f32 v74, v73, 0x378e98ab, v222
	v_fmaak_f32 v74, v73, v74, 0x3b7cd369
	v_fmaak_f32 v74, v73, v74, 0xbcc618b2
	v_fmaak_f32 v74, v73, v74, 0x3dda74e4
	v_fmaak_f32 v74, v73, v74, 0x3f228afd
	v_fmaak_f32 v74, v73, v74, 0x3e03c728
	v_fma_f32 v74, v73, v74, v73
	v_mul_f32_e32 v74, 0xbfb8aa3b, v74
	v_exp_f32_e32 v74, v74
	v_mul_f32_e32 v75, v71, v71
	v_sub_f32_e32 v74, 1.0, v74
	v_fmamk_f32 v72, v75, 0xba1345e1, v200
	v_fmaak_f32 v72, v75, v72, 0xbcdac9b8
	v_fmaak_f32 v72, v75, v72, 0x3de703be
	v_fmaak_f32 v72, v75, v72, 0xbec09330
	v_fmaak_f32 v72, v75, v72, 0x3e0375d0
	v_fma_f32 v72, v73, v72, v73
	v_cmp_ngt_f32_e32 vcc, 1.0, v73
	s_nop 1
	v_cndmask_b32_e32 v72, v72, v74, vcc
	v_mul_f32_e32 v73, 0x3f3504f3, v58
	v_and_b32_e32 v75, 0x7fffffff, v73
	v_fmamk_f32 v76, v75, 0x378e98ab, v222
	v_fmaak_f32 v76, v75, v76, 0x3b7cd369
	v_fmaak_f32 v76, v75, v76, 0xbcc618b2
	v_fmaak_f32 v76, v75, v76, 0x3dda74e4
	v_fmaak_f32 v76, v75, v76, 0x3f228afd
	v_fmaak_f32 v76, v75, v76, 0x3e03c728
	v_fma_f32 v76, v75, v76, v75
	v_mul_f32_e32 v76, 0xbfb8aa3b, v76
	v_exp_f32_e32 v76, v76
	v_mul_f32_e32 v77, v73, v73
	v_sub_f32_e32 v76, 1.0, v76
	v_fmamk_f32 v74, v77, 0xba1345e1, v200
	v_fmaak_f32 v74, v77, v74, 0xbcdac9b8
	v_fmaak_f32 v74, v77, v74, 0x3de703be
	v_fmaak_f32 v74, v77, v74, 0xbec09330
	v_fmaak_f32 v74, v77, v74, 0x3e0375d0
	v_fma_f32 v74, v75, v74, v75
	v_cmp_ngt_f32_e32 vcc, 1.0, v75
	s_nop 1
	v_cndmask_b32_e32 v74, v74, v76, vcc
	v_mul_f32_e32 v75, 0x3f3504f3, v59
	v_and_b32_e32 v77, 0x7fffffff, v75
	v_fmamk_f32 v78, v77, 0x378e98ab, v222
	v_fmaak_f32 v78, v77, v78, 0x3b7cd369
	v_fmaak_f32 v78, v77, v78, 0xbcc618b2
	v_fmaak_f32 v78, v77, v78, 0x3dda74e4
	v_fmaak_f32 v78, v77, v78, 0x3f228afd
	v_fmaak_f32 v78, v77, v78, 0x3e03c728
	v_fma_f32 v78, v77, v78, v77
	v_mul_f32_e32 v78, 0xbfb8aa3b, v78
	v_exp_f32_e32 v78, v78
	v_mul_f32_e32 v79, v75, v75
	v_sub_f32_e32 v78, 1.0, v78
	v_fmamk_f32 v76, v79, 0xba1345e1, v200
	v_fmaak_f32 v76, v79, v76, 0xbcdac9b8
	v_fmaak_f32 v76, v79, v76, 0x3de703be
	v_fmaak_f32 v76, v79, v76, 0xbec09330
	v_fmaak_f32 v76, v79, v76, 0x3e0375d0
	v_fma_f32 v76, v77, v76, v77
	v_cmp_ngt_f32_e32 vcc, 1.0, v77
	s_nop 1
	v_cndmask_b32_e32 v76, v76, v78, vcc
	v_bfi_b32 v73, s37, v74, v73
	v_mul_f32_e32 v58, 0.5, v58
	v_add_f32_e32 v73, 1.0, v73
	v_mul_f32_e32 v73, v58, v73
	v_bfi_b32 v58, s37, v72, v71
	v_mul_f32_e32 v57, 0.5, v57
	v_add_f32_e32 v58, 1.0, v58
	v_mul_f32_e32 v58, v57, v58
	v_bfi_b32 v57, s37, v70, v69
	v_readlane_b32 s6, v252, 33
	v_mul_f32_e32 v56, 0.5, v56
	v_add_f32_e32 v57, 1.0, v57
	v_readlane_b32 s7, v252, 34
	v_mul_f32_e32 v69, v56, v57
	v_mul_f32_e32 v59, 0.5, v59
	v_lshl_add_u64 v[56:57], s[6:7], 0, v[62:63]
	v_bfi_b32 v62, s37, v76, v75
	v_add_f32_e32 v62, 1.0, v62
	v_mul_f32_e32 v59, v59, v62
	v_lshl_add_u64 v[56:57], v[182:183], 1, v[56:57]
	v_cvt_pk_bf16_f32 v58, v69, v58
	v_cvt_pk_bf16_f32 v59, v73, v59
	global_store_dwordx2 v[56:57], v[58:59], off offset:-2048

; DI void st_bf4(u16* p, float a, float b, float c, float d) { *(uint2*)p = make_uint2(pk2(a, b), pk2(c, d)); }
; DI float gelu_f(float x) { return 0.5f * x * (1.f + erff(x * 0.70710678118654752f)); }
;   template <int NT, int MT> DI void run(f32x4 (&acc)[NT][MT], int mb, int nb) const {
;     ...
;         } else if (n < 3072) {
;           st_bf4(uvbuf + (size_t)m * 2048 + (n - 1024), gelu_f(v[0]), gelu_f(v[1]), gelu_f(v[2]), gelu_f(v[3]));
.LBB0_1372:
	s_andn2_saveexec_b64 s[48:49], s[48:49]
	s_cbranch_execz .LBB0_1390
	v_mul_f32_e32 v62, 0x3f3504f3, v52
	v_and_b32_e32 v69, 0x7fffffff, v62
	v_fmamk_f32 v70, v69, 0x378e98ab, v222
	v_fmaak_f32 v70, v69, v70, 0x3b7cd369
	v_fmaak_f32 v70, v69, v70, 0xbcc618b2
	v_fmaak_f32 v70, v69, v70, 0x3dda74e4
	v_fmaak_f32 v70, v69, v70, 0x3f228afd
	v_fmaak_f32 v70, v69, v70, 0x3e03c728
	v_fma_f32 v70, v69, v70, v69
	v_mul_f32_e32 v70, 0xbfb8aa3b, v70
	v_exp_f32_e32 v70, v70
	v_mul_f32_e32 v71, v62, v62
	v_sub_f32_e32 v70, 1.0, v70
	v_fmamk_f32 v63, v71, 0xba1345e1, v200
	v_fmaak_f32 v63, v71, v63, 0xbcdac9b8
	v_fmaak_f32 v63, v71, v63, 0x3de703be
	v_fmaak_f32 v63, v71, v63, 0xbec09330
	v_fmaak_f32 v63, v71, v63, 0x3e0375d0
	v_fma_f32 v63, v69, v63, v69
	v_cmp_ngt_f32_e32 vcc, 1.0, v69
	s_nop 1
	v_cndmask_b32_e32 v63, v63, v70, vcc
	v_mul_f32_e32 v69, 0x3f3504f3, v53
	v_and_b32_e32 v71, 0x7fffffff, v69
	v_fmamk_f32 v72, v71, 0x378e98ab, v222
	v_fmaak_f32 v72, v71, v72, 0x3b7cd369
	v_fmaak_f32 v72, v71, v72, 0xbcc618b2
	v_fmaak_f32 v72, v71, v72, 0x3dda74e4
	v_fmaak_f32 v72, v71, v72, 0x3f228afd
	v_fmaak_f32 v72, v71, v72, 0x3e03c728
	v_fma_f32 v72, v71, v72, v71
	v_mul_f32_e32 v72, 0xbfb8aa3b, v72
	v_exp_f32_e32 v72, v72
	v_mul_f32_e32 v73, v69, v69
	v_sub_f32_e32 v72, 1.0, v72
	v_fmamk_f32 v70, v73, 0xba1345e1, v200
	v_fmaak_f32 v70, v73, v70, 0xbcdac9b8
	v_fmaak_f32 v70, v73, v70, 0x3de703be
	v_fmaak_f32 v70, v73, v70, 0xbec09330
	v_fmaak_f32 v70, v73, v70, 0x3e0375d0
	v_fma_f32 v70, v71, v70, v71
	v_cmp_ngt_f32_e32 vcc, 1.0, v71
	s_nop 1
	v_cndmask_b32_e32 v70, v70, v72, vcc
	v_mul_f32_e32 v71, 0x3f3504f3, v54
	v_and_b32_e32 v73, 0x7fffffff, v71
	v_fmamk_f32 v74, v73, 0x378e98ab, v222
	v_fmaak_f32 v74, v73, v74, 0x3b7cd369
	v_fmaak_f32 v74, v73, v74, 0xbcc618b2
	v_fmaak_f32 v74, v73, v74, 0x3dda74e4
	v_fmaak_f32 v74, v73, v74, 0x3f228afd
	v_fmaak_f32 v74, v73, v74, 0x3e03c728
	v_fma_f32 v74, v73, v74, v73
	v_mul_f32_e32 v74, 0xbfb8aa3b, v74
	v_exp_f32_e32 v74, v74
	v_mul_f32_e32 v75, v71, v71
	v_sub_f32_e32 v74, 1.0, v74
	v_fmamk_f32 v72, v75, 0xba1345e1, v200
	v_fmaak_f32 v72, v75, v72, 0xbcdac9b8
	v_fmaak_f32 v72, v75, v72, 0x3de703be
	v_fmaak_f32 v72, v75, v72, 0xbec09330
	v_fmaak_f32 v72, v75, v72, 0x3e0375d0
	v_fma_f32 v72, v73, v72, v73
	v_cmp_ngt_f32_e32 vcc, 1.0, v73
	s_nop 1
	v_cndmask_b32_e32 v72, v72, v74, vcc
	v_mul_f32_e32 v73, 0x3f3504f3, v55
	v_and_b32_e32 v75, 0x7fffffff, v73
	v_fmamk_f32 v76, v75, 0x378e98ab, v222
	v_fmaak_f32 v76, v75, v76, 0x3b7cd369
	v_fmaak_f32 v76, v75, v76, 0xbcc618b2
	v_fmaak_f32 v76, v75, v76, 0x3dda74e4
	v_fmaak_f32 v76, v75, v76, 0x3f228afd
	v_fmaak_f32 v76, v75, v76, 0x3e03c728
	v_fma_f32 v76, v75, v76, v75
	v_mul_f32_e32 v76, 0xbfb8aa3b, v76
	v_exp_f32_e32 v76, v76
	v_mul_f32_e32 v77, v73, v73
	v_sub_f32_e32 v76, 1.0, v76
	v_fmamk_f32 v74, v77, 0xba1345e1, v200
	v_fmaak_f32 v74, v77, v74, 0xbcdac9b8
	v_fmaak_f32 v74, v77, v74, 0x3de703be
	v_fmaak_f32 v74, v77, v74, 0xbec09330
	v_fmaak_f32 v74, v77, v74, 0x3e0375d0
	v_fma_f32 v74, v75, v74, v75
	v_cmp_ngt_f32_e32 vcc, 1.0, v75
	s_nop 1
	v_cndmask_b32_e32 v74, v74, v76, vcc
	v_bfi_b32 v71, s37, v72, v71
	v_mul_f32_e32 v54, 0.5, v54
	v_add_f32_e32 v71, 1.0, v71
	v_mul_f32_e32 v71, v54, v71
	v_bfi_b32 v54, s37, v70, v69
	v_mul_f32_e32 v53, 0.5, v53
	v_add_f32_e32 v54, 1.0, v54
	v_mul_f32_e32 v54, v53, v54
	v_bfi_b32 v53, s37, v63, v62
	v_readlane_b32 s6, v252, 33
	v_mul_f32_e32 v52, 0.5, v52
	v_add_f32_e32 v53, 1.0, v53
	v_readlane_b32 s7, v252, 34
	v_mul_f32_e32 v62, v52, v53
	v_mul_f32_e32 v55, 0.5, v55
	v_lshl_add_u64 v[52:53], s[6:7], 0, v[58:59]
	v_bfi_b32 v58, s37, v74, v73
	v_add_f32_e32 v58, 1.0, v58
	v_mul_f32_e32 v55, v55, v58
	v_lshl_add_u64 v[52:53], v[182:183], 1, v[52:53]
	v_cvt_pk_bf16_f32 v54, v62, v54
	v_cvt_pk_bf16_f32 v55, v71, v55
	global_store_dwordx2 v[52:53], v[54:55], off offset:-2048

; DI void st_bf4(u16* p, float a, float b, float c, float d) { *(uint2*)p = make_uint2(pk2(a, b), pk2(c, d)); }
; DI float gelu_f(float x) { return 0.5f * x * (1.f + erff(x * 0.70710678118654752f)); }
;   template <int NT, int MT> DI void run(f32x4 (&acc)[NT][MT], int mb, int nb) const {
;     ...
;         } else if (n < 3072) {
;           st_bf4(uvbuf + (size_t)m * 2048 + (n - 1024), gelu_f(v[0]), gelu_f(v[1]), gelu_f(v[2]), gelu_f(v[3]));
.LBB0_1396:
	s_andn2_saveexec_b64 s[46:47], s[46:47]
	s_cbranch_execz .LBB0_1414
	v_mul_f32_e32 v58, 0x3f3504f3, v48
	v_and_b32_e32 v62, 0x7fffffff, v58
	v_fmamk_f32 v63, v62, 0x378e98ab, v222
	v_fmaak_f32 v63, v62, v63, 0x3b7cd369
	v_fmaak_f32 v63, v62, v63, 0xbcc618b2
	v_fmaak_f32 v63, v62, v63, 0x3dda74e4
	v_fmaak_f32 v63, v62, v63, 0x3f228afd
	v_fmaak_f32 v63, v62, v63, 0x3e03c728
	v_fma_f32 v63, v62, v63, v62
	v_mul_f32_e32 v63, 0xbfb8aa3b, v63
	v_exp_f32_e32 v63, v63
	v_mul_f32_e32 v69, v58, v58
	v_sub_f32_e32 v63, 1.0, v63
	v_fmamk_f32 v59, v69, 0xba1345e1, v200
	v_fmaak_f32 v59, v69, v59, 0xbcdac9b8
	v_fmaak_f32 v59, v69, v59, 0x3de703be
	v_fmaak_f32 v59, v69, v59, 0xbec09330
	v_fmaak_f32 v59, v69, v59, 0x3e0375d0
	v_fma_f32 v59, v62, v59, v62
	v_cmp_ngt_f32_e32 vcc, 1.0, v62
	s_nop 1
	v_cndmask_b32_e32 v59, v59, v63, vcc
	v_mul_f32_e32 v62, 0x3f3504f3, v49
	v_and_b32_e32 v69, 0x7fffffff, v62
	v_fmamk_f32 v70, v69, 0x378e98ab, v222
	v_fmaak_f32 v70, v69, v70, 0x3b7cd369
	v_fmaak_f32 v70, v69, v70, 0xbcc618b2
	v_fmaak_f32 v70, v69, v70, 0x3dda74e4
	v_fmaak_f32 v70, v69, v70, 0x3f228afd
	v_fmaak_f32 v70, v69, v70, 0x3e03c728
	v_fma_f32 v70, v69, v70, v69
	v_mul_f32_e32 v70, 0xbfb8aa3b, v70
	v_exp_f32_e32 v70, v70
	v_mul_f32_e32 v71, v62, v62
	v_sub_f32_e32 v70, 1.0, v70
	v_fmamk_f32 v63, v71, 0xba1345e1, v200
	v_fmaak_f32 v63, v71, v63, 0xbcdac9b8
	v_fmaak_f32 v63, v71, v63, 0x3de703be
	v_fmaak_f32 v63, v71, v63, 0xbec09330
	v_fmaak_f32 v63, v71, v63, 0x3e0375d0
	v_fma_f32 v63, v69, v63, v69
	v_cmp_ngt_f32_e32 vcc, 1.0, v69
	s_nop 1
	v_cndmask_b32_e32 v63, v63, v70, vcc
	v_mul_f32_e32 v69, 0x3f3504f3, v50
	v_and_b32_e32 v71, 0x7fffffff, v69
	v_fmamk_f32 v72, v71, 0x378e98ab, v222
	v_fmaak_f32 v72, v71, v72, 0x3b7cd369
	v_fmaak_f32 v72, v71, v72, 0xbcc618b2
	v_fmaak_f32 v72, v71, v72, 0x3dda74e4
	v_fmaak_f32 v72, v71, v72, 0x3f228afd
	v_fmaak_f32 v72, v71, v72, 0x3e03c728
	v_fma_f32 v72, v71, v72, v71
	v_mul_f32_e32 v72, 0xbfb8aa3b, v72
	v_exp_f32_e32 v72, v72
	v_mul_f32_e32 v73, v69, v69
	v_sub_f32_e32 v72, 1.0, v72
	v_fmamk_f32 v70, v73, 0xba1345e1, v200
	v_fmaak_f32 v70, v73, v70, 0xbcdac9b8
	v_fmaak_f32 v70, v73, v70, 0x3de703be
	v_fmaak_f32 v70, v73, v70, 0xbec09330
	v_fmaak_f32 v70, v73, v70, 0x3e0375d0
	v_fma_f32 v70, v71, v70, v71
	v_cmp_ngt_f32_e32 vcc, 1.0, v71
	s_nop 1
	v_cndmask_b32_e32 v70, v70, v72, vcc
	v_mul_f32_e32 v71, 0x3f3504f3, v51
	v_and_b32_e32 v73, 0x7fffffff, v71
	v_fmamk_f32 v74, v73, 0x378e98ab, v222
	v_fmaak_f32 v74, v73, v74, 0x3b7cd369
	v_fmaak_f32 v74, v73, v74, 0xbcc618b2
	v_fmaak_f32 v74, v73, v74, 0x3dda74e4
	v_fmaak_f32 v74, v73, v74, 0x3f228afd
	v_fmaak_f32 v74, v73, v74, 0x3e03c728
	v_fma_f32 v74, v73, v74, v73
	v_mul_f32_e32 v74, 0xbfb8aa3b, v74
	v_exp_f32_e32 v74, v74
	v_mul_f32_e32 v75, v71, v71
	v_sub_f32_e32 v74, 1.0, v74
	v_fmamk_f32 v72, v75, 0xba1345e1, v200
	v_fmaak_f32 v72, v75, v72, 0xbcdac9b8
	v_fmaak_f32 v72, v75, v72, 0x3de703be
	v_fmaak_f32 v72, v75, v72, 0xbec09330
	v_fmaak_f32 v72, v75, v72, 0x3e0375d0
	v_fma_f32 v72, v73, v72, v73
	v_cmp_ngt_f32_e32 vcc, 1.0, v73
	s_nop 1
	v_cndmask_b32_e32 v72, v72, v74, vcc
	v_bfi_b32 v69, s37, v70, v69
	v_mul_f32_e32 v50, 0.5, v50
	v_add_f32_e32 v69, 1.0, v69
	v_mul_f32_e32 v69, v50, v69
	v_bfi_b32 v50, s37, v63, v62
	v_mul_f32_e32 v49, 0.5, v49
	v_add_f32_e32 v50, 1.0, v50
	v_mul_f32_e32 v50, v49, v50
	v_bfi_b32 v49, s37, v59, v58
	v_readlane_b32 s6, v252, 33
	v_mul_f32_e32 v48, 0.5, v48
	v_add_f32_e32 v49, 1.0, v49
	v_readlane_b32 s7, v252, 34
	v_mul_f32_e32 v58, v48, v49
	v_mul_f32_e32 v51, 0.5, v51
	v_lshl_add_u64 v[48:49], s[6:7], 0, v[54:55]
	v_bfi_b32 v54, s37, v72, v71
	v_add_f32_e32 v54, 1.0, v54
	v_mul_f32_e32 v51, v51, v54
	v_lshl_add_u64 v[48:49], v[182:183], 1, v[48:49]
	v_cvt_pk_bf16_f32 v50, v58, v50
	v_cvt_pk_bf16_f32 v51, v69, v51
	global_store_dwordx2 v[48:49], v[50:51], off offset:-2048

; DI void st_bf4(u16* p, float a, float b, float c, float d) { *(uint2*)p = make_uint2(pk2(a, b), pk2(c, d)); }
; DI float gelu_f(float x) { return 0.5f * x * (1.f + erff(x * 0.70710678118654752f)); }
;   template <int NT, int MT> DI void run(f32x4 (&acc)[NT][MT], int mb, int nb) const {
;     ...
;         } else if (n < 3072) {
;           st_bf4(uvbuf + (size_t)m * 2048 + (n - 1024), gelu_f(v[0]), gelu_f(v[1]), gelu_f(v[2]), gelu_f(v[3]));
.LBB0_1426:
	s_andn2_saveexec_b64 s[48:49], s[48:49]
	s_cbranch_execz .LBB0_1444
	v_mul_f32_e32 v50, 0x3f3504f3, v44
	v_and_b32_e32 v54, 0x7fffffff, v50
	v_fmamk_f32 v55, v54, 0x378e98ab, v222
	v_fmaak_f32 v55, v54, v55, 0x3b7cd369
	v_fmaak_f32 v55, v54, v55, 0xbcc618b2
	v_fmaak_f32 v55, v54, v55, 0x3dda74e4
	v_fmaak_f32 v55, v54, v55, 0x3f228afd
	v_fmaak_f32 v55, v54, v55, 0x3e03c728
	v_fma_f32 v55, v54, v55, v54
	v_mul_f32_e32 v55, 0xbfb8aa3b, v55
	v_exp_f32_e32 v55, v55
	v_mul_f32_e32 v58, v50, v50
	v_sub_f32_e32 v55, 1.0, v55
	v_fmamk_f32 v51, v58, 0xba1345e1, v200
	v_fmaak_f32 v51, v58, v51, 0xbcdac9b8
	v_fmaak_f32 v51, v58, v51, 0x3de703be
	v_fmaak_f32 v51, v58, v51, 0xbec09330
	v_fmaak_f32 v51, v58, v51, 0x3e0375d0
	v_fma_f32 v51, v54, v51, v54
	v_cmp_ngt_f32_e32 vcc, 1.0, v54
	s_nop 1
	v_cndmask_b32_e32 v51, v51, v55, vcc
	v_mul_f32_e32 v54, 0x3f3504f3, v45
	v_and_b32_e32 v58, 0x7fffffff, v54
	v_fmamk_f32 v59, v58, 0x378e98ab, v222
	v_fmaak_f32 v59, v58, v59, 0x3b7cd369
	v_fmaak_f32 v59, v58, v59, 0xbcc618b2
	v_fmaak_f32 v59, v58, v59, 0x3dda74e4
	v_fmaak_f32 v59, v58, v59, 0x3f228afd
	v_fmaak_f32 v59, v58, v59, 0x3e03c728
	v_fma_f32 v59, v58, v59, v58
	v_mul_f32_e32 v59, 0xbfb8aa3b, v59
	v_exp_f32_e32 v59, v59
	v_mul_f32_e32 v62, v54, v54
	v_sub_f32_e32 v59, 1.0, v59
	v_fmamk_f32 v55, v62, 0xba1345e1, v200
	v_fmaak_f32 v55, v62, v55, 0xbcdac9b8
	v_fmaak_f32 v55, v62, v55, 0x3de703be
	v_fmaak_f32 v55, v62, v55, 0xbec09330
	v_fmaak_f32 v55, v62, v55, 0x3e0375d0
	v_fma_f32 v55, v58, v55, v58
	v_cmp_ngt_f32_e32 vcc, 1.0, v58
	s_nop 1
	v_cndmask_b32_e32 v55, v55, v59, vcc
	v_mul_f32_e32 v58, 0x3f3504f3, v46
	v_and_b32_e32 v62, 0x7fffffff, v58
	v_fmamk_f32 v63, v62, 0x378e98ab, v222
	v_fmaak_f32 v63, v62, v63, 0x3b7cd369
	v_fmaak_f32 v63, v62, v63, 0xbcc618b2
	v_fmaak_f32 v63, v62, v63, 0x3dda74e4
	v_fmaak_f32 v63, v62, v63, 0x3f228afd
	v_fmaak_f32 v63, v62, v63, 0x3e03c728
	v_fma_f32 v63, v62, v63, v62
	v_mul_f32_e32 v63, 0xbfb8aa3b, v63
	v_exp_f32_e32 v63, v63
	v_mul_f32_e32 v69, v58, v58
	v_sub_f32_e32 v63, 1.0, v63
	v_fmamk_f32 v59, v69, 0xba1345e1, v200
	v_fmaak_f32 v59, v69, v59, 0xbcdac9b8
	v_fmaak_f32 v59, v69, v59, 0x3de703be
	v_fmaak_f32 v59, v69, v59, 0xbec09330
	v_fmaak_f32 v59, v69, v59, 0x3e0375d0
	v_fma_f32 v59, v62, v59, v62
	v_cmp_ngt_f32_e32 vcc, 1.0, v62
	s_nop 1
	v_cndmask_b32_e32 v59, v59, v63, vcc
	v_mul_f32_e32 v62, 0x3f3504f3, v47
	v_and_b32_e32 v69, 0x7fffffff, v62
	v_fmamk_f32 v70, v69, 0x378e98ab, v222
	v_fmaak_f32 v70, v69, v70, 0x3b7cd369
	v_fmaak_f32 v70, v69, v70, 0xbcc618b2
	v_fmaak_f32 v70, v69, v70, 0x3dda74e4
	v_fmaak_f32 v70, v69, v70, 0x3f228afd
	v_fmaak_f32 v70, v69, v70, 0x3e03c728
	v_fma_f32 v70, v69, v70, v69
	v_mul_f32_e32 v70, 0xbfb8aa3b, v70
	v_exp_f32_e32 v70, v70
	v_mul_f32_e32 v71, v62, v62
	v_sub_f32_e32 v70, 1.0, v70
	v_fmamk_f32 v63, v71, 0xba1345e1, v200
	v_fmaak_f32 v63, v71, v63, 0xbcdac9b8
	v_fmaak_f32 v63, v71, v63, 0x3de703be
	v_fmaak_f32 v63, v71, v63, 0xbec09330
	v_fmaak_f32 v63, v71, v63, 0x3e0375d0
	v_fma_f32 v63, v69, v63, v69
	v_cmp_ngt_f32_e32 vcc, 1.0, v69
	s_nop 1
	v_cndmask_b32_e32 v63, v63, v70, vcc
	v_bfi_b32 v58, s37, v59, v58
	v_mul_f32_e32 v46, 0.5, v46
	v_add_f32_e32 v58, 1.0, v58
	v_mul_f32_e32 v58, v46, v58
	v_bfi_b32 v46, s37, v55, v54
	v_mul_f32_e32 v45, 0.5, v45
	v_add_f32_e32 v46, 1.0, v46
	v_mul_f32_e32 v46, v45, v46
	v_bfi_b32 v45, s37, v51, v50
	v_readlane_b32 s6, v252, 33
	v_mul_f32_e32 v44, 0.5, v44
	v_add_f32_e32 v45, 1.0, v45
	v_readlane_b32 s7, v252, 34
	v_mul_f32_e32 v50, v44, v45
	v_mul_f32_e32 v47, 0.5, v47
	v_lshl_add_u64 v[44:45], s[6:7], 0, v[48:49]
	v_bfi_b32 v48, s37, v63, v62
	v_add_f32_e32 v48, 1.0, v48
	v_mul_f32_e32 v47, v47, v48
	v_lshl_add_u64 v[44:45], v[182:183], 1, v[44:45]
	v_cvt_pk_bf16_f32 v46, v50, v46
	v_cvt_pk_bf16_f32 v47, v58, v47
	global_store_dwordx2 v[44:45], v[46:47], off offset:-2016

; DI void st_bf4(u16* p, float a, float b, float c, float d) { *(uint2*)p = make_uint2(pk2(a, b), pk2(c, d)); }
; DI float gelu_f(float x) { return 0.5f * x * (1.f + erff(x * 0.70710678118654752f)); }
;   template <int NT, int MT> DI void run(f32x4 (&acc)[NT][MT], int mb, int nb) const {
;     ...
;         } else if (n < 3072) {
;           st_bf4(uvbuf + (size_t)m * 2048 + (n - 1024), gelu_f(v[0]), gelu_f(v[1]), gelu_f(v[2]), gelu_f(v[3]));
.LBB0_1450:
	s_andn2_saveexec_b64 s[48:49], s[48:49]
	s_cbranch_execz .LBB0_1468
	v_mul_f32_e32 v46, 0x3f3504f3, v40
	v_and_b32_e32 v48, 0x7fffffff, v46
	v_fmamk_f32 v49, v48, 0x378e98ab, v222
	v_fmaak_f32 v49, v48, v49, 0x3b7cd369
	v_fmaak_f32 v49, v48, v49, 0xbcc618b2
	v_fmaak_f32 v49, v48, v49, 0x3dda74e4
	v_fmaak_f32 v49, v48, v49, 0x3f228afd
	v_fmaak_f32 v49, v48, v49, 0x3e03c728
	v_fma_f32 v49, v48, v49, v48
	v_mul_f32_e32 v49, 0xbfb8aa3b, v49
	v_exp_f32_e32 v49, v49
	v_mul_f32_e32 v50, v46, v46
	v_sub_f32_e32 v49, 1.0, v49
	v_fmamk_f32 v47, v50, 0xba1345e1, v200
	v_fmaak_f32 v47, v50, v47, 0xbcdac9b8
	v_fmaak_f32 v47, v50, v47, 0x3de703be
	v_fmaak_f32 v47, v50, v47, 0xbec09330
	v_fmaak_f32 v47, v50, v47, 0x3e0375d0
	v_fma_f32 v47, v48, v47, v48
	v_cmp_ngt_f32_e32 vcc, 1.0, v48
	s_nop 1
	v_cndmask_b32_e32 v47, v47, v49, vcc
	v_mul_f32_e32 v48, 0x3f3504f3, v41
	v_and_b32_e32 v50, 0x7fffffff, v48
	v_fmamk_f32 v51, v50, 0x378e98ab, v222
	v_fmaak_f32 v51, v50, v51, 0x3b7cd369
	v_fmaak_f32 v51, v50, v51, 0xbcc618b2
	v_fmaak_f32 v51, v50, v51, 0x3dda74e4
	v_fmaak_f32 v51, v50, v51, 0x3f228afd
	v_fmaak_f32 v51, v50, v51, 0x3e03c728
	v_fma_f32 v51, v50, v51, v50
	v_mul_f32_e32 v51, 0xbfb8aa3b, v51
	v_exp_f32_e32 v51, v51
	v_mul_f32_e32 v54, v48, v48
	v_sub_f32_e32 v51, 1.0, v51
	v_fmamk_f32 v49, v54, 0xba1345e1, v200
	v_fmaak_f32 v49, v54, v49, 0xbcdac9b8
	v_fmaak_f32 v49, v54, v49, 0x3de703be
	v_fmaak_f32 v49, v54, v49, 0xbec09330
	v_fmaak_f32 v49, v54, v49, 0x3e0375d0
	v_fma_f32 v49, v50, v49, v50
	v_cmp_ngt_f32_e32 vcc, 1.0, v50
	s_nop 1
	v_cndmask_b32_e32 v49, v49, v51, vcc
	v_mul_f32_e32 v50, 0x3f3504f3, v42
	v_and_b32_e32 v54, 0x7fffffff, v50
	v_fmamk_f32 v55, v54, 0x378e98ab, v222
	v_fmaak_f32 v55, v54, v55, 0x3b7cd369
	v_fmaak_f32 v55, v54, v55, 0xbcc618b2
	v_fmaak_f32 v55, v54, v55, 0x3dda74e4
	v_fmaak_f32 v55, v54, v55, 0x3f228afd
	v_fmaak_f32 v55, v54, v55, 0x3e03c728
	v_fma_f32 v55, v54, v55, v54
	v_mul_f32_e32 v55, 0xbfb8aa3b, v55
	v_exp_f32_e32 v55, v55
	v_mul_f32_e32 v58, v50, v50
	v_sub_f32_e32 v55, 1.0, v55
	v_fmamk_f32 v51, v58, 0xba1345e1, v200
	v_fmaak_f32 v51, v58, v51, 0xbcdac9b8
	v_fmaak_f32 v51, v58, v51, 0x3de703be
	v_fmaak_f32 v51, v58, v51, 0xbec09330
	v_fmaak_f32 v51, v58, v51, 0x3e0375d0
	v_fma_f32 v51, v54, v51, v54
	v_cmp_ngt_f32_e32 vcc, 1.0, v54
	s_nop 1
	v_cndmask_b32_e32 v51, v51, v55, vcc
	v_mul_f32_e32 v54, 0x3f3504f3, v43
	v_and_b32_e32 v58, 0x7fffffff, v54
	v_fmamk_f32 v59, v58, 0x378e98ab, v222
	v_fmaak_f32 v59, v58, v59, 0x3b7cd369
	v_fmaak_f32 v59, v58, v59, 0xbcc618b2
	v_fmaak_f32 v59, v58, v59, 0x3dda74e4
	v_fmaak_f32 v59, v58, v59, 0x3f228afd
	v_fmaak_f32 v59, v58, v59, 0x3e03c728
	v_fma_f32 v59, v58, v59, v58
	v_mul_f32_e32 v59, 0xbfb8aa3b, v59
	v_exp_f32_e32 v59, v59
	v_mul_f32_e32 v62, v54, v54
	v_sub_f32_e32 v59, 1.0, v59
	v_fmamk_f32 v55, v62, 0xba1345e1, v200
	v_fmaak_f32 v55, v62, v55, 0xbcdac9b8
	v_fmaak_f32 v55, v62, v55, 0x3de703be
	v_fmaak_f32 v55, v62, v55, 0xbec09330
	v_fmaak_f32 v55, v62, v55, 0x3e0375d0
	v_fma_f32 v55, v58, v55, v58
	v_cmp_ngt_f32_e32 vcc, 1.0, v58
	s_nop 1
	v_cndmask_b32_e32 v55, v55, v59, vcc
	v_bfi_b32 v50, s37, v51, v50
	v_mul_f32_e32 v42, 0.5, v42
	v_add_f32_e32 v50, 1.0, v50
	v_mul_f32_e32 v50, v42, v50
	v_bfi_b32 v42, s37, v49, v48
	v_mul_f32_e32 v41, 0.5, v41
	v_add_f32_e32 v42, 1.0, v42
	v_mul_f32_e32 v42, v41, v42
	v_bfi_b32 v41, s37, v47, v46
	v_readlane_b32 s6, v252, 33
	v_mul_f32_e32 v40, 0.5, v40
	v_add_f32_e32 v41, 1.0, v41
	v_readlane_b32 s7, v252, 34
	v_mul_f32_e32 v46, v40, v41
	v_mul_f32_e32 v43, 0.5, v43
	v_lshl_add_u64 v[40:41], s[6:7], 0, v[44:45]
	v_bfi_b32 v44, s37, v55, v54
	v_add_f32_e32 v44, 1.0, v44
	v_mul_f32_e32 v43, v43, v44
	v_lshl_add_u64 v[40:41], v[182:183], 1, v[40:41]
	v_cvt_pk_bf16_f32 v42, v46, v42
	v_cvt_pk_bf16_f32 v43, v50, v43
	global_store_dwordx2 v[40:41], v[42:43], off offset:-2016

; DI void st_bf4(u16* p, float a, float b, float c, float d) { *(uint2*)p = make_uint2(pk2(a, b), pk2(c, d)); }
; DI float gelu_f(float x) { return 0.5f * x * (1.f + erff(x * 0.70710678118654752f)); }
;   template <int NT, int MT> DI void run(f32x4 (&acc)[NT][MT], int mb, int nb) const {
;     ...
;         } else if (n < 3072) {
;           st_bf4(uvbuf + (size_t)m * 2048 + (n - 1024), gelu_f(v[0]), gelu_f(v[1]), gelu_f(v[2]), gelu_f(v[3]));
.LBB0_1480:
	s_andn2_saveexec_b64 s[48:49], s[48:49]
	s_cbranch_execz .LBB0_1498
	v_mul_f32_e32 v42, 0x3f3504f3, v36
	v_and_b32_e32 v44, 0x7fffffff, v42
	v_fmamk_f32 v45, v44, 0x378e98ab, v222
	v_fmaak_f32 v45, v44, v45, 0x3b7cd369
	v_fmaak_f32 v45, v44, v45, 0xbcc618b2
	v_fmaak_f32 v45, v44, v45, 0x3dda74e4
	v_fmaak_f32 v45, v44, v45, 0x3f228afd
	v_fmaak_f32 v45, v44, v45, 0x3e03c728
	v_fma_f32 v45, v44, v45, v44
	v_mul_f32_e32 v45, 0xbfb8aa3b, v45
	v_exp_f32_e32 v45, v45
	v_mul_f32_e32 v46, v42, v42
	v_sub_f32_e32 v45, 1.0, v45
	v_fmamk_f32 v43, v46, 0xba1345e1, v200
	v_fmaak_f32 v43, v46, v43, 0xbcdac9b8
	v_fmaak_f32 v43, v46, v43, 0x3de703be
	v_fmaak_f32 v43, v46, v43, 0xbec09330
	v_fmaak_f32 v43, v46, v43, 0x3e0375d0
	v_fma_f32 v43, v44, v43, v44
	v_cmp_ngt_f32_e32 vcc, 1.0, v44
	s_nop 1
	v_cndmask_b32_e32 v43, v43, v45, vcc
	v_mul_f32_e32 v44, 0x3f3504f3, v37
	v_and_b32_e32 v46, 0x7fffffff, v44
	v_fmamk_f32 v47, v46, 0x378e98ab, v222
	v_fmaak_f32 v47, v46, v47, 0x3b7cd369
	v_fmaak_f32 v47, v46, v47, 0xbcc618b2
	v_fmaak_f32 v47, v46, v47, 0x3dda74e4
	v_fmaak_f32 v47, v46, v47, 0x3f228afd
	v_fmaak_f32 v47, v46, v47, 0x3e03c728
	v_fma_f32 v47, v46, v47, v46
	v_mul_f32_e32 v47, 0xbfb8aa3b, v47
	v_exp_f32_e32 v47, v47
	v_mul_f32_e32 v48, v44, v44
	v_sub_f32_e32 v47, 1.0, v47
	v_fmamk_f32 v45, v48, 0xba1345e1, v200
	v_fmaak_f32 v45, v48, v45, 0xbcdac9b8
	v_fmaak_f32 v45, v48, v45, 0x3de703be
	v_fmaak_f32 v45, v48, v45, 0xbec09330
	v_fmaak_f32 v45, v48, v45, 0x3e0375d0
	v_fma_f32 v45, v46, v45, v46
	v_cmp_ngt_f32_e32 vcc, 1.0, v46
	s_nop 1
	v_cndmask_b32_e32 v45, v45, v47, vcc
	v_mul_f32_e32 v46, 0x3f3504f3, v38
	v_and_b32_e32 v48, 0x7fffffff, v46
	v_fmamk_f32 v49, v48, 0x378e98ab, v222
	v_fmaak_f32 v49, v48, v49, 0x3b7cd369
	v_fmaak_f32 v49, v48, v49, 0xbcc618b2
	v_fmaak_f32 v49, v48, v49, 0x3dda74e4
	v_fmaak_f32 v49, v48, v49, 0x3f228afd
	v_fmaak_f32 v49, v48, v49, 0x3e03c728
	v_fma_f32 v49, v48, v49, v48
	v_mul_f32_e32 v49, 0xbfb8aa3b, v49
	v_exp_f32_e32 v49, v49
	v_mul_f32_e32 v50, v46, v46
	v_sub_f32_e32 v49, 1.0, v49
	v_fmamk_f32 v47, v50, 0xba1345e1, v200
	v_fmaak_f32 v47, v50, v47, 0xbcdac9b8
	v_fmaak_f32 v47, v50, v47, 0x3de703be
	v_fmaak_f32 v47, v50, v47, 0xbec09330
	v_fmaak_f32 v47, v50, v47, 0x3e0375d0
	v_fma_f32 v47, v48, v47, v48
	v_cmp_ngt_f32_e32 vcc, 1.0, v48
	s_nop 1
	v_cndmask_b32_e32 v47, v47, v49, vcc
	v_mul_f32_e32 v48, 0x3f3504f3, v39
	v_and_b32_e32 v50, 0x7fffffff, v48
	v_fmamk_f32 v51, v50, 0x378e98ab, v222
	v_fmaak_f32 v51, v50, v51, 0x3b7cd369
	v_fmaak_f32 v51, v50, v51, 0xbcc618b2
	v_fmaak_f32 v51, v50, v51, 0x3dda74e4
	v_fmaak_f32 v51, v50, v51, 0x3f228afd
	v_fmaak_f32 v51, v50, v51, 0x3e03c728
	v_fma_f32 v51, v50, v51, v50
	v_mul_f32_e32 v51, 0xbfb8aa3b, v51
	v_exp_f32_e32 v51, v51
	v_mul_f32_e32 v54, v48, v48
	v_sub_f32_e32 v51, 1.0, v51
	v_fmamk_f32 v49, v54, 0xba1345e1, v200
	v_fmaak_f32 v49, v54, v49, 0xbcdac9b8
	v_fmaak_f32 v49, v54, v49, 0x3de703be
	v_fmaak_f32 v49, v54, v49, 0xbec09330
	v_fmaak_f32 v49, v54, v49, 0x3e0375d0
	v_fma_f32 v49, v50, v49, v50
	v_cmp_ngt_f32_e32 vcc, 1.0, v50
	s_nop 1
	v_cndmask_b32_e32 v49, v49, v51, vcc
	v_bfi_b32 v46, s37, v47, v46
	v_mul_f32_e32 v38, 0.5, v38
	v_add_f32_e32 v46, 1.0, v46
	v_mul_f32_e32 v46, v38, v46
	v_bfi_b32 v38, s37, v45, v44
	v_mul_f32_e32 v37, 0.5, v37
	v_add_f32_e32 v38, 1.0, v38
	v_mul_f32_e32 v38, v37, v38
	v_bfi_b32 v37, s37, v43, v42
	v_readlane_b32 s6, v252, 33
	v_mul_f32_e32 v36, 0.5, v36
	v_add_f32_e32 v37, 1.0, v37
	v_readlane_b32 s7, v252, 34
	v_mul_f32_e32 v42, v36, v37
	v_mul_f32_e32 v39, 0.5, v39
	v_lshl_add_u64 v[36:37], s[6:7], 0, v[40:41]
	v_bfi_b32 v40, s37, v49, v48
	v_add_f32_e32 v40, 1.0, v40
	v_mul_f32_e32 v39, v39, v40
	v_lshl_add_u64 v[36:37], v[182:183], 1, v[36:37]
	v_cvt_pk_bf16_f32 v38, v42, v38
	v_cvt_pk_bf16_f32 v39, v46, v39
	global_store_dwordx2 v[36:37], v[38:39], off offset:-2016

; DI void st_bf4(u16* p, float a, float b, float c, float d) { *(uint2*)p = make_uint2(pk2(a, b), pk2(c, d)); }
; DI float gelu_f(float x) { return 0.5f * x * (1.f + erff(x * 0.70710678118654752f)); }
;   template <int NT, int MT> DI void run(f32x4 (&acc)[NT][MT], int mb, int nb) const {
;     ...
;         } else if (n < 3072) {
;           st_bf4(uvbuf + (size_t)m * 2048 + (n - 1024), gelu_f(v[0]), gelu_f(v[1]), gelu_f(v[2]), gelu_f(v[3]));
.LBB0_1504:
	s_andn2_saveexec_b64 s[46:47], s[46:47]
	s_cbranch_execz .LBB0_1522
	v_mul_f32_e32 v38, 0x3f3504f3, v32
	v_and_b32_e32 v40, 0x7fffffff, v38
	v_fmamk_f32 v41, v40, 0x378e98ab, v222
	v_fmaak_f32 v41, v40, v41, 0x3b7cd369
	v_fmaak_f32 v41, v40, v41, 0xbcc618b2
	v_fmaak_f32 v41, v40, v41, 0x3dda74e4
	v_fmaak_f32 v41, v40, v41, 0x3f228afd
	v_fmaak_f32 v41, v40, v41, 0x3e03c728
	v_fma_f32 v41, v40, v41, v40
	v_mul_f32_e32 v41, 0xbfb8aa3b, v41
	v_exp_f32_e32 v41, v41
	v_mul_f32_e32 v42, v38, v38
	v_sub_f32_e32 v41, 1.0, v41
	v_fmamk_f32 v39, v42, 0xba1345e1, v200
	v_fmaak_f32 v39, v42, v39, 0xbcdac9b8
	v_fmaak_f32 v39, v42, v39, 0x3de703be
	v_fmaak_f32 v39, v42, v39, 0xbec09330
	v_fmaak_f32 v39, v42, v39, 0x3e0375d0
	v_fma_f32 v39, v40, v39, v40
	v_cmp_ngt_f32_e32 vcc, 1.0, v40
	s_nop 1
	v_cndmask_b32_e32 v39, v39, v41, vcc
	v_mul_f32_e32 v40, 0x3f3504f3, v33
	v_and_b32_e32 v42, 0x7fffffff, v40
	v_fmamk_f32 v43, v42, 0x378e98ab, v222
	v_fmaak_f32 v43, v42, v43, 0x3b7cd369
	v_fmaak_f32 v43, v42, v43, 0xbcc618b2
	v_fmaak_f32 v43, v42, v43, 0x3dda74e4
	v_fmaak_f32 v43, v42, v43, 0x3f228afd
	v_fmaak_f32 v43, v42, v43, 0x3e03c728
	v_fma_f32 v43, v42, v43, v42
	v_mul_f32_e32 v43, 0xbfb8aa3b, v43
	v_exp_f32_e32 v43, v43
	v_mul_f32_e32 v44, v40, v40
	v_sub_f32_e32 v43, 1.0, v43
	v_fmamk_f32 v41, v44, 0xba1345e1, v200
	v_fmaak_f32 v41, v44, v41, 0xbcdac9b8
	v_fmaak_f32 v41, v44, v41, 0x3de703be
	v_fmaak_f32 v41, v44, v41, 0xbec09330
	v_fmaak_f32 v41, v44, v41, 0x3e0375d0
	v_fma_f32 v41, v42, v41, v42
	v_cmp_ngt_f32_e32 vcc, 1.0, v42
	s_nop 1
	v_cndmask_b32_e32 v41, v41, v43, vcc
	v_mul_f32_e32 v42, 0x3f3504f3, v34
	v_and_b32_e32 v44, 0x7fffffff, v42
	v_fmamk_f32 v45, v44, 0x378e98ab, v222
	v_fmaak_f32 v45, v44, v45, 0x3b7cd369
	v_fmaak_f32 v45, v44, v45, 0xbcc618b2
	v_fmaak_f32 v45, v44, v45, 0x3dda74e4
	v_fmaak_f32 v45, v44, v45, 0x3f228afd
	v_fmaak_f32 v45, v44, v45, 0x3e03c728
	v_fma_f32 v45, v44, v45, v44
	v_mul_f32_e32 v45, 0xbfb8aa3b, v45
	v_exp_f32_e32 v45, v45
	v_mul_f32_e32 v46, v42, v42
	v_sub_f32_e32 v45, 1.0, v45
	v_fmamk_f32 v43, v46, 0xba1345e1, v200
	v_fmaak_f32 v43, v46, v43, 0xbcdac9b8
	v_fmaak_f32 v43, v46, v43, 0x3de703be
	v_fmaak_f32 v43, v46, v43, 0xbec09330
	v_fmaak_f32 v43, v46, v43, 0x3e0375d0
	v_fma_f32 v43, v44, v43, v44
	v_cmp_ngt_f32_e32 vcc, 1.0, v44
	s_nop 1
	v_cndmask_b32_e32 v43, v43, v45, vcc
	v_mul_f32_e32 v44, 0x3f3504f3, v35
	v_and_b32_e32 v46, 0x7fffffff, v44
	v_fmamk_f32 v47, v46, 0x378e98ab, v222
	v_fmaak_f32 v47, v46, v47, 0x3b7cd369
	v_fmaak_f32 v47, v46, v47, 0xbcc618b2
	v_fmaak_f32 v47, v46, v47, 0x3dda74e4
	v_fmaak_f32 v47, v46, v47, 0x3f228afd
	v_fmaak_f32 v47, v46, v47, 0x3e03c728
	v_fma_f32 v47, v46, v47, v46
	v_mul_f32_e32 v47, 0xbfb8aa3b, v47
	v_exp_f32_e32 v47, v47
	v_mul_f32_e32 v48, v44, v44
	v_sub_f32_e32 v47, 1.0, v47
	v_fmamk_f32 v45, v48, 0xba1345e1, v200
	v_fmaak_f32 v45, v48, v45, 0xbcdac9b8
	v_fmaak_f32 v45, v48, v45, 0x3de703be
	v_fmaak_f32 v45, v48, v45, 0xbec09330
	v_fmaak_f32 v45, v48, v45, 0x3e0375d0
	v_fma_f32 v45, v46, v45, v46
	v_cmp_ngt_f32_e32 vcc, 1.0, v46
	s_nop 1
	v_cndmask_b32_e32 v45, v45, v47, vcc
	v_bfi_b32 v42, s37, v43, v42
	v_mul_f32_e32 v34, 0.5, v34
	v_add_f32_e32 v42, 1.0, v42
	v_mul_f32_e32 v42, v34, v42
	v_bfi_b32 v34, s37, v41, v40
	v_mul_f32_e32 v33, 0.5, v33
	v_add_f32_e32 v34, 1.0, v34
	v_mul_f32_e32 v34, v33, v34
	v_bfi_b32 v33, s37, v39, v38
	v_readlane_b32 s6, v252, 33
	v_mul_f32_e32 v32, 0.5, v32
	v_add_f32_e32 v33, 1.0, v33
	v_readlane_b32 s7, v252, 34
	v_mul_f32_e32 v38, v32, v33
	v_mul_f32_e32 v35, 0.5, v35
	v_lshl_add_u64 v[32:33], s[6:7], 0, v[36:37]
	v_bfi_b32 v36, s37, v45, v44
	v_add_f32_e32 v36, 1.0, v36
	v_mul_f32_e32 v35, v35, v36
	v_lshl_add_u64 v[32:33], v[182:183], 1, v[32:33]
	v_cvt_pk_bf16_f32 v34, v38, v34
	v_cvt_pk_bf16_f32 v35, v42, v35
	global_store_dwordx2 v[32:33], v[34:35], off offset:-2016

; DI void st_bf4(u16* p, float a, float b, float c, float d) { *(uint2*)p = make_uint2(pk2(a, b), pk2(c, d)); }
; DI float gelu_f(float x) { return 0.5f * x * (1.f + erff(x * 0.70710678118654752f)); }
;   template <int NT, int MT> DI void run(f32x4 (&acc)[NT][MT], int mb, int nb) const {
;     ...
;         } else if (n < 3072) {
;           st_bf4(uvbuf + (size_t)m * 2048 + (n - 1024), gelu_f(v[0]), gelu_f(v[1]), gelu_f(v[2]), gelu_f(v[3]));
.LBB0_1534:
	s_andn2_saveexec_b64 s[48:49], s[48:49]
	s_cbranch_execz .LBB0_1552
	v_mul_f32_e32 v34, 0x3f3504f3, v28
	v_and_b32_e32 v36, 0x7fffffff, v34
	v_fmamk_f32 v37, v36, 0x378e98ab, v222
	v_fmaak_f32 v37, v36, v37, 0x3b7cd369
	v_fmaak_f32 v37, v36, v37, 0xbcc618b2
	v_fmaak_f32 v37, v36, v37, 0x3dda74e4
	v_fmaak_f32 v37, v36, v37, 0x3f228afd
	v_fmaak_f32 v37, v36, v37, 0x3e03c728
	v_fma_f32 v37, v36, v37, v36
	v_mul_f32_e32 v37, 0xbfb8aa3b, v37
	v_exp_f32_e32 v37, v37
	v_mul_f32_e32 v38, v34, v34
	v_sub_f32_e32 v37, 1.0, v37
	v_fmamk_f32 v35, v38, 0xba1345e1, v200
	v_fmaak_f32 v35, v38, v35, 0xbcdac9b8
	v_fmaak_f32 v35, v38, v35, 0x3de703be
	v_fmaak_f32 v35, v38, v35, 0xbec09330
	v_fmaak_f32 v35, v38, v35, 0x3e0375d0
	v_fma_f32 v35, v36, v35, v36
	v_cmp_ngt_f32_e32 vcc, 1.0, v36
	s_nop 1
	v_cndmask_b32_e32 v35, v35, v37, vcc
	v_mul_f32_e32 v36, 0x3f3504f3, v29
	v_and_b32_e32 v38, 0x7fffffff, v36
	v_fmamk_f32 v39, v38, 0x378e98ab, v222
	v_fmaak_f32 v39, v38, v39, 0x3b7cd369
	v_fmaak_f32 v39, v38, v39, 0xbcc618b2
	v_fmaak_f32 v39, v38, v39, 0x3dda74e4
	v_fmaak_f32 v39, v38, v39, 0x3f228afd
	v_fmaak_f32 v39, v38, v39, 0x3e03c728
	v_fma_f32 v39, v38, v39, v38
	v_mul_f32_e32 v39, 0xbfb8aa3b, v39
	v_exp_f32_e32 v39, v39
	v_mul_f32_e32 v40, v36, v36
	v_sub_f32_e32 v39, 1.0, v39
	v_fmamk_f32 v37, v40, 0xba1345e1, v200
	v_fmaak_f32 v37, v40, v37, 0xbcdac9b8
	v_fmaak_f32 v37, v40, v37, 0x3de703be
	v_fmaak_f32 v37, v40, v37, 0xbec09330
	v_fmaak_f32 v37, v40, v37, 0x3e0375d0
	v_fma_f32 v37, v38, v37, v38
	v_cmp_ngt_f32_e32 vcc, 1.0, v38
	s_nop 1
	v_cndmask_b32_e32 v37, v37, v39, vcc
	v_mul_f32_e32 v38, 0x3f3504f3, v30
	v_and_b32_e32 v40, 0x7fffffff, v38
	v_fmamk_f32 v41, v40, 0x378e98ab, v222
	v_fmaak_f32 v41, v40, v41, 0x3b7cd369
	v_fmaak_f32 v41, v40, v41, 0xbcc618b2
	v_fmaak_f32 v41, v40, v41, 0x3dda74e4
	v_fmaak_f32 v41, v40, v41, 0x3f228afd
	v_fmaak_f32 v41, v40, v41, 0x3e03c728
	v_fma_f32 v41, v40, v41, v40
	v_mul_f32_e32 v41, 0xbfb8aa3b, v41
	v_exp_f32_e32 v41, v41
	v_mul_f32_e32 v42, v38, v38
	v_sub_f32_e32 v41, 1.0, v41
	v_fmamk_f32 v39, v42, 0xba1345e1, v200
	v_fmaak_f32 v39, v42, v39, 0xbcdac9b8
	v_fmaak_f32 v39, v42, v39, 0x3de703be
	v_fmaak_f32 v39, v42, v39, 0xbec09330
	v_fmaak_f32 v39, v42, v39, 0x3e0375d0
	v_fma_f32 v39, v40, v39, v40
	v_cmp_ngt_f32_e32 vcc, 1.0, v40
	s_nop 1
	v_cndmask_b32_e32 v39, v39, v41, vcc
	v_mul_f32_e32 v40, 0x3f3504f3, v31
	v_and_b32_e32 v42, 0x7fffffff, v40
	v_fmamk_f32 v43, v42, 0x378e98ab, v222
	v_fmaak_f32 v43, v42, v43, 0x3b7cd369
	v_fmaak_f32 v43, v42, v43, 0xbcc618b2
	v_fmaak_f32 v43, v42, v43, 0x3dda74e4
	v_fmaak_f32 v43, v42, v43, 0x3f228afd
	v_fmaak_f32 v43, v42, v43, 0x3e03c728
	v_fma_f32 v43, v42, v43, v42
	v_mul_f32_e32 v43, 0xbfb8aa3b, v43
	v_exp_f32_e32 v43, v43
	v_mul_f32_e32 v44, v40, v40
	v_sub_f32_e32 v43, 1.0, v43
	v_fmamk_f32 v41, v44, 0xba1345e1, v200
	v_fmaak_f32 v41, v44, v41, 0xbcdac9b8
	v_fmaak_f32 v41, v44, v41, 0x3de703be
	v_fmaak_f32 v41, v44, v41, 0xbec09330
	v_fmaak_f32 v41, v44, v41, 0x3e0375d0
	v_fma_f32 v41, v42, v41, v42
	v_cmp_ngt_f32_e32 vcc, 1.0, v42
	s_nop 1
	v_cndmask_b32_e32 v41, v41, v43, vcc
	v_bfi_b32 v38, s37, v39, v38
	v_mul_f32_e32 v30, 0.5, v30
	v_add_f32_e32 v38, 1.0, v38
	v_mul_f32_e32 v38, v30, v38
	v_bfi_b32 v30, s37, v37, v36
	v_mul_f32_e32 v29, 0.5, v29
	v_add_f32_e32 v30, 1.0, v30
	v_mul_f32_e32 v30, v29, v30
	v_bfi_b32 v29, s37, v35, v34
	v_readlane_b32 s6, v252, 33
	v_mul_f32_e32 v28, 0.5, v28
	v_add_f32_e32 v29, 1.0, v29
	v_readlane_b32 s7, v252, 34
	v_mul_f32_e32 v34, v28, v29
	v_mul_f32_e32 v31, 0.5, v31
	v_lshl_add_u64 v[28:29], s[6:7], 0, v[32:33]
	v_bfi_b32 v32, s37, v41, v40
	v_add_f32_e32 v32, 1.0, v32
	v_mul_f32_e32 v31, v31, v32
	v_lshl_add_u64 v[28:29], v[182:183], 1, v[28:29]
	v_cvt_pk_bf16_f32 v30, v34, v30
	v_cvt_pk_bf16_f32 v31, v38, v31
	global_store_dwordx2 v[28:29], v[30:31], off offset:-1984

; DI void st_bf4(u16* p, float a, float b, float c, float d) { *(uint2*)p = make_uint2(pk2(a, b), pk2(c, d)); }
; DI float gelu_f(float x) { return 0.5f * x * (1.f + erff(x * 0.70710678118654752f)); }
;   template <int NT, int MT> DI void run(f32x4 (&acc)[NT][MT], int mb, int nb) const {
;     ...
;         } else if (n < 3072) {
;           st_bf4(uvbuf + (size_t)m * 2048 + (n - 1024), gelu_f(v[0]), gelu_f(v[1]), gelu_f(v[2]), gelu_f(v[3]));
.LBB0_1558:
	s_andn2_saveexec_b64 s[48:49], s[48:49]
	s_cbranch_execz .LBB0_1576
	v_mul_f32_e32 v30, 0x3f3504f3, v24
	v_and_b32_e32 v32, 0x7fffffff, v30
	v_fmamk_f32 v33, v32, 0x378e98ab, v222
	v_fmaak_f32 v33, v32, v33, 0x3b7cd369
	v_fmaak_f32 v33, v32, v33, 0xbcc618b2
	v_fmaak_f32 v33, v32, v33, 0x3dda74e4
	v_fmaak_f32 v33, v32, v33, 0x3f228afd
	v_fmaak_f32 v33, v32, v33, 0x3e03c728
	v_fma_f32 v33, v32, v33, v32
	v_mul_f32_e32 v33, 0xbfb8aa3b, v33
	v_exp_f32_e32 v33, v33
	v_mul_f32_e32 v34, v30, v30
	v_sub_f32_e32 v33, 1.0, v33
	v_fmamk_f32 v31, v34, 0xba1345e1, v200
	v_fmaak_f32 v31, v34, v31, 0xbcdac9b8
	v_fmaak_f32 v31, v34, v31, 0x3de703be
	v_fmaak_f32 v31, v34, v31, 0xbec09330
	v_fmaak_f32 v31, v34, v31, 0x3e0375d0
	v_fma_f32 v31, v32, v31, v32
	v_cmp_ngt_f32_e32 vcc, 1.0, v32
	s_nop 1
	v_cndmask_b32_e32 v31, v31, v33, vcc
	v_mul_f32_e32 v32, 0x3f3504f3, v25
	v_and_b32_e32 v34, 0x7fffffff, v32
	v_fmamk_f32 v35, v34, 0x378e98ab, v222
	v_fmaak_f32 v35, v34, v35, 0x3b7cd369
	v_fmaak_f32 v35, v34, v35, 0xbcc618b2
	v_fmaak_f32 v35, v34, v35, 0x3dda74e4
	v_fmaak_f32 v35, v34, v35, 0x3f228afd
	v_fmaak_f32 v35, v34, v35, 0x3e03c728
	v_fma_f32 v35, v34, v35, v34
	v_mul_f32_e32 v35, 0xbfb8aa3b, v35
	v_exp_f32_e32 v35, v35
	v_mul_f32_e32 v36, v32, v32
	v_sub_f32_e32 v35, 1.0, v35
	v_fmamk_f32 v33, v36, 0xba1345e1, v200
	v_fmaak_f32 v33, v36, v33, 0xbcdac9b8
	v_fmaak_f32 v33, v36, v33, 0x3de703be
	v_fmaak_f32 v33, v36, v33, 0xbec09330
	v_fmaak_f32 v33, v36, v33, 0x3e0375d0
	v_fma_f32 v33, v34, v33, v34
	v_cmp_ngt_f32_e32 vcc, 1.0, v34
	s_nop 1
	v_cndmask_b32_e32 v33, v33, v35, vcc
	v_mul_f32_e32 v34, 0x3f3504f3, v26
	v_and_b32_e32 v36, 0x7fffffff, v34
	v_fmamk_f32 v37, v36, 0x378e98ab, v222
	v_fmaak_f32 v37, v36, v37, 0x3b7cd369
	v_fmaak_f32 v37, v36, v37, 0xbcc618b2
	v_fmaak_f32 v37, v36, v37, 0x3dda74e4
	v_fmaak_f32 v37, v36, v37, 0x3f228afd
	v_fmaak_f32 v37, v36, v37, 0x3e03c728
	v_fma_f32 v37, v36, v37, v36
	v_mul_f32_e32 v37, 0xbfb8aa3b, v37
	v_exp_f32_e32 v37, v37
	v_mul_f32_e32 v38, v34, v34
	v_sub_f32_e32 v37, 1.0, v37
	v_fmamk_f32 v35, v38, 0xba1345e1, v200
	v_fmaak_f32 v35, v38, v35, 0xbcdac9b8
	v_fmaak_f32 v35, v38, v35, 0x3de703be
	v_fmaak_f32 v35, v38, v35, 0xbec09330
	v_fmaak_f32 v35, v38, v35, 0x3e0375d0
	v_fma_f32 v35, v36, v35, v36
	v_cmp_ngt_f32_e32 vcc, 1.0, v36
	s_nop 1
	v_cndmask_b32_e32 v35, v35, v37, vcc
	v_mul_f32_e32 v36, 0x3f3504f3, v27
	v_and_b32_e32 v38, 0x7fffffff, v36
	v_fmamk_f32 v39, v38, 0x378e98ab, v222
	v_fmaak_f32 v39, v38, v39, 0x3b7cd369
	v_fmaak_f32 v39, v38, v39, 0xbcc618b2
	v_fmaak_f32 v39, v38, v39, 0x3dda74e4
	v_fmaak_f32 v39, v38, v39, 0x3f228afd
	v_fmaak_f32 v39, v38, v39, 0x3e03c728
	v_fma_f32 v39, v38, v39, v38
	v_mul_f32_e32 v39, 0xbfb8aa3b, v39
	v_exp_f32_e32 v39, v39
	v_mul_f32_e32 v40, v36, v36
	v_sub_f32_e32 v39, 1.0, v39
	v_fmamk_f32 v37, v40, 0xba1345e1, v200
	v_fmaak_f32 v37, v40, v37, 0xbcdac9b8
	v_fmaak_f32 v37, v40, v37, 0x3de703be
	v_fmaak_f32 v37, v40, v37, 0xbec09330
	v_fmaak_f32 v37, v40, v37, 0x3e0375d0
	v_fma_f32 v37, v38, v37, v38
	v_cmp_ngt_f32_e32 vcc, 1.0, v38
	s_nop 1
	v_cndmask_b32_e32 v37, v37, v39, vcc
	v_bfi_b32 v34, s37, v35, v34
	v_mul_f32_e32 v26, 0.5, v26
	v_add_f32_e32 v34, 1.0, v34
	v_mul_f32_e32 v34, v26, v34
	v_bfi_b32 v26, s37, v33, v32
	v_mul_f32_e32 v25, 0.5, v25
	v_add_f32_e32 v26, 1.0, v26
	v_mul_f32_e32 v26, v25, v26
	v_bfi_b32 v25, s37, v31, v30
	v_readlane_b32 s6, v252, 33
	v_mul_f32_e32 v24, 0.5, v24
	v_add_f32_e32 v25, 1.0, v25
	v_readlane_b32 s7, v252, 34
	v_mul_f32_e32 v30, v24, v25
	v_mul_f32_e32 v27, 0.5, v27
	v_lshl_add_u64 v[24:25], s[6:7], 0, v[28:29]
	v_bfi_b32 v28, s37, v37, v36
	v_add_f32_e32 v28, 1.0, v28
	v_mul_f32_e32 v27, v27, v28
	v_lshl_add_u64 v[24:25], v[182:183], 1, v[24:25]
	v_cvt_pk_bf16_f32 v26, v30, v26
	v_cvt_pk_bf16_f32 v27, v34, v27
	global_store_dwordx2 v[24:25], v[26:27], off offset:-1984

; DI void st_bf4(u16* p, float a, float b, float c, float d) { *(uint2*)p = make_uint2(pk2(a, b), pk2(c, d)); }
; DI float gelu_f(float x) { return 0.5f * x * (1.f + erff(x * 0.70710678118654752f)); }
;   template <int NT, int MT> DI void run(f32x4 (&acc)[NT][MT], int mb, int nb) const {
;     ...
;         } else if (n < 3072) {
;           st_bf4(uvbuf + (size_t)m * 2048 + (n - 1024), gelu_f(v[0]), gelu_f(v[1]), gelu_f(v[2]), gelu_f(v[3]));
.LBB0_1588:
	s_andn2_saveexec_b64 s[48:49], s[48:49]
	s_cbranch_execz .LBB0_1606
	v_mul_f32_e32 v26, 0x3f3504f3, v20
	v_and_b32_e32 v28, 0x7fffffff, v26
	v_fmamk_f32 v29, v28, 0x378e98ab, v222
	v_fmaak_f32 v29, v28, v29, 0x3b7cd369
	v_fmaak_f32 v29, v28, v29, 0xbcc618b2
	v_fmaak_f32 v29, v28, v29, 0x3dda74e4
	v_fmaak_f32 v29, v28, v29, 0x3f228afd
	v_fmaak_f32 v29, v28, v29, 0x3e03c728
	v_fma_f32 v29, v28, v29, v28
	v_mul_f32_e32 v29, 0xbfb8aa3b, v29
	v_exp_f32_e32 v29, v29
	v_mul_f32_e32 v30, v26, v26
	v_sub_f32_e32 v29, 1.0, v29
	v_fmamk_f32 v27, v30, 0xba1345e1, v200
	v_fmaak_f32 v27, v30, v27, 0xbcdac9b8
	v_fmaak_f32 v27, v30, v27, 0x3de703be
	v_fmaak_f32 v27, v30, v27, 0xbec09330
	v_fmaak_f32 v27, v30, v27, 0x3e0375d0
	v_fma_f32 v27, v28, v27, v28
	v_cmp_ngt_f32_e32 vcc, 1.0, v28
	s_nop 1
	v_cndmask_b32_e32 v27, v27, v29, vcc
	v_mul_f32_e32 v28, 0x3f3504f3, v21
	v_and_b32_e32 v30, 0x7fffffff, v28
	v_fmamk_f32 v31, v30, 0x378e98ab, v222
	v_fmaak_f32 v31, v30, v31, 0x3b7cd369
	v_fmaak_f32 v31, v30, v31, 0xbcc618b2
	v_fmaak_f32 v31, v30, v31, 0x3dda74e4
	v_fmaak_f32 v31, v30, v31, 0x3f228afd
	v_fmaak_f32 v31, v30, v31, 0x3e03c728
	v_fma_f32 v31, v30, v31, v30
	v_mul_f32_e32 v31, 0xbfb8aa3b, v31
	v_exp_f32_e32 v31, v31
	v_mul_f32_e32 v32, v28, v28
	v_sub_f32_e32 v31, 1.0, v31
	v_fmamk_f32 v29, v32, 0xba1345e1, v200
	v_fmaak_f32 v29, v32, v29, 0xbcdac9b8
	v_fmaak_f32 v29, v32, v29, 0x3de703be
	v_fmaak_f32 v29, v32, v29, 0xbec09330
	v_fmaak_f32 v29, v32, v29, 0x3e0375d0
	v_fma_f32 v29, v30, v29, v30
	v_cmp_ngt_f32_e32 vcc, 1.0, v30
	s_nop 1
	v_cndmask_b32_e32 v29, v29, v31, vcc
	v_mul_f32_e32 v30, 0x3f3504f3, v22
	v_and_b32_e32 v32, 0x7fffffff, v30
	v_fmamk_f32 v33, v32, 0x378e98ab, v222
	v_fmaak_f32 v33, v32, v33, 0x3b7cd369
	v_fmaak_f32 v33, v32, v33, 0xbcc618b2
	v_fmaak_f32 v33, v32, v33, 0x3dda74e4
	v_fmaak_f32 v33, v32, v33, 0x3f228afd
	v_fmaak_f32 v33, v32, v33, 0x3e03c728
	v_fma_f32 v33, v32, v33, v32
	v_mul_f32_e32 v33, 0xbfb8aa3b, v33
	v_exp_f32_e32 v33, v33
	v_mul_f32_e32 v34, v30, v30
	v_sub_f32_e32 v33, 1.0, v33
	v_fmamk_f32 v31, v34, 0xba1345e1, v200
	v_fmaak_f32 v31, v34, v31, 0xbcdac9b8
	v_fmaak_f32 v31, v34, v31, 0x3de703be
	v_fmaak_f32 v31, v34, v31, 0xbec09330
	v_fmaak_f32 v31, v34, v31, 0x3e0375d0
	v_fma_f32 v31, v32, v31, v32
	v_cmp_ngt_f32_e32 vcc, 1.0, v32
	s_nop 1
	v_cndmask_b32_e32 v31, v31, v33, vcc
	v_mul_f32_e32 v32, 0x3f3504f3, v23
	v_and_b32_e32 v34, 0x7fffffff, v32
	v_fmamk_f32 v35, v34, 0x378e98ab, v222
	v_fmaak_f32 v35, v34, v35, 0x3b7cd369
	v_fmaak_f32 v35, v34, v35, 0xbcc618b2
	v_fmaak_f32 v35, v34, v35, 0x3dda74e4
	v_fmaak_f32 v35, v34, v35, 0x3f228afd
	v_fmaak_f32 v35, v34, v35, 0x3e03c728
	v_fma_f32 v35, v34, v35, v34
	v_mul_f32_e32 v35, 0xbfb8aa3b, v35
	v_exp_f32_e32 v35, v35
	v_mul_f32_e32 v36, v32, v32
	v_sub_f32_e32 v35, 1.0, v35
	v_fmamk_f32 v33, v36, 0xba1345e1, v200
	v_fmaak_f32 v33, v36, v33, 0xbcdac9b8
	v_fmaak_f32 v33, v36, v33, 0x3de703be
	v_fmaak_f32 v33, v36, v33, 0xbec09330
	v_fmaak_f32 v33, v36, v33, 0x3e0375d0
	v_fma_f32 v33, v34, v33, v34
	v_cmp_ngt_f32_e32 vcc, 1.0, v34
	s_nop 1
	v_cndmask_b32_e32 v33, v33, v35, vcc
	v_bfi_b32 v30, s37, v31, v30
	v_mul_f32_e32 v22, 0.5, v22
	v_add_f32_e32 v30, 1.0, v30
	v_mul_f32_e32 v30, v22, v30
	v_bfi_b32 v22, s37, v29, v28
	v_mul_f32_e32 v21, 0.5, v21
	v_add_f32_e32 v22, 1.0, v22
	v_mul_f32_e32 v22, v21, v22
	v_bfi_b32 v21, s37, v27, v26
	v_readlane_b32 s6, v252, 33
	v_mul_f32_e32 v20, 0.5, v20
	v_add_f32_e32 v21, 1.0, v21
	v_readlane_b32 s7, v252, 34
	v_mul_f32_e32 v26, v20, v21
	v_mul_f32_e32 v23, 0.5, v23
	v_lshl_add_u64 v[20:21], s[6:7], 0, v[24:25]
	v_bfi_b32 v24, s37, v33, v32
	v_add_f32_e32 v24, 1.0, v24
	v_mul_f32_e32 v23, v23, v24
	v_lshl_add_u64 v[20:21], v[182:183], 1, v[20:21]
	v_cvt_pk_bf16_f32 v22, v26, v22
	v_cvt_pk_bf16_f32 v23, v30, v23
	global_store_dwordx2 v[20:21], v[22:23], off offset:-1984

; DI void st_bf4(u16* p, float a, float b, float c, float d) { *(uint2*)p = make_uint2(pk2(a, b), pk2(c, d)); }
; DI float gelu_f(float x) { return 0.5f * x * (1.f + erff(x * 0.70710678118654752f)); }
;   template <int NT, int MT> DI void run(f32x4 (&acc)[NT][MT], int mb, int nb) const {
;     ...
;         } else if (n < 3072) {
;           st_bf4(uvbuf + (size_t)m * 2048 + (n - 1024), gelu_f(v[0]), gelu_f(v[1]), gelu_f(v[2]), gelu_f(v[3]));
.LBB0_1612:
	s_andn2_saveexec_b64 s[46:47], s[46:47]
	s_cbranch_execz .LBB0_1630
	v_mul_f32_e32 v22, 0x3f3504f3, v16
	v_and_b32_e32 v24, 0x7fffffff, v22
	v_fmamk_f32 v25, v24, 0x378e98ab, v222
	v_fmaak_f32 v25, v24, v25, 0x3b7cd369
	v_fmaak_f32 v25, v24, v25, 0xbcc618b2
	v_fmaak_f32 v25, v24, v25, 0x3dda74e4
	v_fmaak_f32 v25, v24, v25, 0x3f228afd
	v_fmaak_f32 v25, v24, v25, 0x3e03c728
	v_fma_f32 v25, v24, v25, v24
	v_mul_f32_e32 v25, 0xbfb8aa3b, v25
	v_exp_f32_e32 v25, v25
	v_mul_f32_e32 v26, v22, v22
	v_sub_f32_e32 v25, 1.0, v25
	v_fmamk_f32 v23, v26, 0xba1345e1, v200
	v_fmaak_f32 v23, v26, v23, 0xbcdac9b8
	v_fmaak_f32 v23, v26, v23, 0x3de703be
	v_fmaak_f32 v23, v26, v23, 0xbec09330
	v_fmaak_f32 v23, v26, v23, 0x3e0375d0
	v_fma_f32 v23, v24, v23, v24
	v_cmp_ngt_f32_e32 vcc, 1.0, v24
	s_nop 1
	v_cndmask_b32_e32 v23, v23, v25, vcc
	v_mul_f32_e32 v24, 0x3f3504f3, v17
	v_and_b32_e32 v26, 0x7fffffff, v24
	v_fmamk_f32 v27, v26, 0x378e98ab, v222
	v_fmaak_f32 v27, v26, v27, 0x3b7cd369
	v_fmaak_f32 v27, v26, v27, 0xbcc618b2
	v_fmaak_f32 v27, v26, v27, 0x3dda74e4
	v_fmaak_f32 v27, v26, v27, 0x3f228afd
	v_fmaak_f32 v27, v26, v27, 0x3e03c728
	v_fma_f32 v27, v26, v27, v26
	v_mul_f32_e32 v27, 0xbfb8aa3b, v27
	v_exp_f32_e32 v27, v27
	v_mul_f32_e32 v28, v24, v24
	v_sub_f32_e32 v27, 1.0, v27
	v_fmamk_f32 v25, v28, 0xba1345e1, v200
	v_fmaak_f32 v25, v28, v25, 0xbcdac9b8
	v_fmaak_f32 v25, v28, v25, 0x3de703be
	v_fmaak_f32 v25, v28, v25, 0xbec09330
	v_fmaak_f32 v25, v28, v25, 0x3e0375d0
	v_fma_f32 v25, v26, v25, v26
	v_cmp_ngt_f32_e32 vcc, 1.0, v26
	s_nop 1
	v_cndmask_b32_e32 v25, v25, v27, vcc
	v_mul_f32_e32 v26, 0x3f3504f3, v18
	v_and_b32_e32 v28, 0x7fffffff, v26
	v_fmamk_f32 v29, v28, 0x378e98ab, v222
	v_fmaak_f32 v29, v28, v29, 0x3b7cd369
	v_fmaak_f32 v29, v28, v29, 0xbcc618b2
	v_fmaak_f32 v29, v28, v29, 0x3dda74e4
	v_fmaak_f32 v29, v28, v29, 0x3f228afd
	v_fmaak_f32 v29, v28, v29, 0x3e03c728
	v_fma_f32 v29, v28, v29, v28
	v_mul_f32_e32 v29, 0xbfb8aa3b, v29
	v_exp_f32_e32 v29, v29
	v_mul_f32_e32 v30, v26, v26
	v_sub_f32_e32 v29, 1.0, v29
	v_fmamk_f32 v27, v30, 0xba1345e1, v200
	v_fmaak_f32 v27, v30, v27, 0xbcdac9b8
	v_fmaak_f32 v27, v30, v27, 0x3de703be
	v_fmaak_f32 v27, v30, v27, 0xbec09330
	v_fmaak_f32 v27, v30, v27, 0x3e0375d0
	v_fma_f32 v27, v28, v27, v28
	v_cmp_ngt_f32_e32 vcc, 1.0, v28
	s_nop 1
	v_cndmask_b32_e32 v27, v27, v29, vcc
	v_mul_f32_e32 v28, 0x3f3504f3, v19
	v_and_b32_e32 v30, 0x7fffffff, v28
	v_fmamk_f32 v31, v30, 0x378e98ab, v222
	v_fmaak_f32 v31, v30, v31, 0x3b7cd369
	v_fmaak_f32 v31, v30, v31, 0xbcc618b2
	v_fmaak_f32 v31, v30, v31, 0x3dda74e4
	v_fmaak_f32 v31, v30, v31, 0x3f228afd
	v_fmaak_f32 v31, v30, v31, 0x3e03c728
	v_fma_f32 v31, v30, v31, v30
	v_mul_f32_e32 v31, 0xbfb8aa3b, v31
	v_exp_f32_e32 v31, v31
	v_mul_f32_e32 v32, v28, v28
	v_sub_f32_e32 v31, 1.0, v31
	v_fmamk_f32 v29, v32, 0xba1345e1, v200
	v_fmaak_f32 v29, v32, v29, 0xbcdac9b8
	v_fmaak_f32 v29, v32, v29, 0x3de703be
	v_fmaak_f32 v29, v32, v29, 0xbec09330
	v_fmaak_f32 v29, v32, v29, 0x3e0375d0
	v_fma_f32 v29, v30, v29, v30
	v_cmp_ngt_f32_e32 vcc, 1.0, v30
	s_nop 1
	v_cndmask_b32_e32 v29, v29, v31, vcc
	v_bfi_b32 v26, s37, v27, v26
	v_mul_f32_e32 v18, 0.5, v18
	v_add_f32_e32 v26, 1.0, v26
	v_mul_f32_e32 v26, v18, v26
	v_bfi_b32 v18, s37, v25, v24
	v_mul_f32_e32 v17, 0.5, v17
	v_add_f32_e32 v18, 1.0, v18
	v_mul_f32_e32 v18, v17, v18
	v_bfi_b32 v17, s37, v23, v22
	v_readlane_b32 s6, v252, 33
	v_mul_f32_e32 v16, 0.5, v16
	v_add_f32_e32 v17, 1.0, v17
	v_readlane_b32 s7, v252, 34
	v_mul_f32_e32 v22, v16, v17
	v_mul_f32_e32 v19, 0.5, v19
	v_lshl_add_u64 v[16:17], s[6:7], 0, v[20:21]
	v_bfi_b32 v20, s37, v29, v28
	v_add_f32_e32 v20, 1.0, v20
	v_mul_f32_e32 v19, v19, v20
	v_lshl_add_u64 v[16:17], v[182:183], 1, v[16:17]
	v_cvt_pk_bf16_f32 v18, v22, v18
	v_cvt_pk_bf16_f32 v19, v26, v19
	global_store_dwordx2 v[16:17], v[18:19], off offset:-1984

; DI void st_bf4(u16* p, float a, float b, float c, float d) { *(uint2*)p = make_uint2(pk2(a, b), pk2(c, d)); }
; DI float gelu_f(float x) { return 0.5f * x * (1.f + erff(x * 0.70710678118654752f)); }
;   template <int NT, int MT> DI void run(f32x4 (&acc)[NT][MT], int mb, int nb) const {
;     ...
;         } else if (n < 3072) {
;           st_bf4(uvbuf + (size_t)m * 2048 + (n - 1024), gelu_f(v[0]), gelu_f(v[1]), gelu_f(v[2]), gelu_f(v[3]));
.LBB0_1642:
	s_andn2_saveexec_b64 s[48:49], s[48:49]
	s_cbranch_execz .LBB0_1660
	v_mul_f32_e32 v18, 0x3f3504f3, v12
	v_and_b32_e32 v20, 0x7fffffff, v18
	v_fmamk_f32 v21, v20, 0x378e98ab, v222
	v_fmaak_f32 v21, v20, v21, 0x3b7cd369
	v_fmaak_f32 v21, v20, v21, 0xbcc618b2
	v_fmaak_f32 v21, v20, v21, 0x3dda74e4
	v_fmaak_f32 v21, v20, v21, 0x3f228afd
	v_fmaak_f32 v21, v20, v21, 0x3e03c728
	v_fma_f32 v21, v20, v21, v20
	v_mul_f32_e32 v21, 0xbfb8aa3b, v21
	v_exp_f32_e32 v21, v21
	v_mul_f32_e32 v22, v18, v18
	v_sub_f32_e32 v21, 1.0, v21
	v_fmamk_f32 v19, v22, 0xba1345e1, v200
	v_fmaak_f32 v19, v22, v19, 0xbcdac9b8
	v_fmaak_f32 v19, v22, v19, 0x3de703be
	v_fmaak_f32 v19, v22, v19, 0xbec09330
	v_fmaak_f32 v19, v22, v19, 0x3e0375d0
	v_fma_f32 v19, v20, v19, v20
	v_cmp_ngt_f32_e32 vcc, 1.0, v20
	s_nop 1
	v_cndmask_b32_e32 v19, v19, v21, vcc
	v_mul_f32_e32 v20, 0x3f3504f3, v13
	v_and_b32_e32 v22, 0x7fffffff, v20
	v_fmamk_f32 v23, v22, 0x378e98ab, v222
	v_fmaak_f32 v23, v22, v23, 0x3b7cd369
	v_fmaak_f32 v23, v22, v23, 0xbcc618b2
	v_fmaak_f32 v23, v22, v23, 0x3dda74e4
	v_fmaak_f32 v23, v22, v23, 0x3f228afd
	v_fmaak_f32 v23, v22, v23, 0x3e03c728
	v_fma_f32 v23, v22, v23, v22
	v_mul_f32_e32 v23, 0xbfb8aa3b, v23
	v_exp_f32_e32 v23, v23
	v_mul_f32_e32 v24, v20, v20
	v_sub_f32_e32 v23, 1.0, v23
	v_fmamk_f32 v21, v24, 0xba1345e1, v200
	v_fmaak_f32 v21, v24, v21, 0xbcdac9b8
	v_fmaak_f32 v21, v24, v21, 0x3de703be
	v_fmaak_f32 v21, v24, v21, 0xbec09330
	v_fmaak_f32 v21, v24, v21, 0x3e0375d0
	v_fma_f32 v21, v22, v21, v22
	v_cmp_ngt_f32_e32 vcc, 1.0, v22
	s_nop 1
	v_cndmask_b32_e32 v21, v21, v23, vcc
	v_mul_f32_e32 v22, 0x3f3504f3, v14
	v_and_b32_e32 v24, 0x7fffffff, v22
	v_fmamk_f32 v25, v24, 0x378e98ab, v222
	v_fmaak_f32 v25, v24, v25, 0x3b7cd369
	v_fmaak_f32 v25, v24, v25, 0xbcc618b2
	v_fmaak_f32 v25, v24, v25, 0x3dda74e4
	v_fmaak_f32 v25, v24, v25, 0x3f228afd
	v_fmaak_f32 v25, v24, v25, 0x3e03c728
	v_fma_f32 v25, v24, v25, v24
	v_mul_f32_e32 v25, 0xbfb8aa3b, v25
	v_exp_f32_e32 v25, v25
	v_mul_f32_e32 v26, v22, v22
	v_sub_f32_e32 v25, 1.0, v25
	v_fmamk_f32 v23, v26, 0xba1345e1, v200
	v_fmaak_f32 v23, v26, v23, 0xbcdac9b8
	v_fmaak_f32 v23, v26, v23, 0x3de703be
	v_fmaak_f32 v23, v26, v23, 0xbec09330
	v_fmaak_f32 v23, v26, v23, 0x3e0375d0
	v_fma_f32 v23, v24, v23, v24
	v_cmp_ngt_f32_e32 vcc, 1.0, v24
	s_nop 1
	v_cndmask_b32_e32 v23, v23, v25, vcc
	v_mul_f32_e32 v24, 0x3f3504f3, v15
	v_and_b32_e32 v26, 0x7fffffff, v24
	v_fmamk_f32 v27, v26, 0x378e98ab, v222
	v_fmaak_f32 v27, v26, v27, 0x3b7cd369
	v_fmaak_f32 v27, v26, v27, 0xbcc618b2
	v_fmaak_f32 v27, v26, v27, 0x3dda74e4
	v_fmaak_f32 v27, v26, v27, 0x3f228afd
	v_fmaak_f32 v27, v26, v27, 0x3e03c728
	v_fma_f32 v27, v26, v27, v26
	v_mul_f32_e32 v27, 0xbfb8aa3b, v27
	v_exp_f32_e32 v27, v27
	v_mul_f32_e32 v28, v24, v24
	v_sub_f32_e32 v27, 1.0, v27
	v_fmamk_f32 v25, v28, 0xba1345e1, v200
	v_fmaak_f32 v25, v28, v25, 0xbcdac9b8
	v_fmaak_f32 v25, v28, v25, 0x3de703be
	v_fmaak_f32 v25, v28, v25, 0xbec09330
	v_fmaak_f32 v25, v28, v25, 0x3e0375d0
	v_fma_f32 v25, v26, v25, v26
	v_cmp_ngt_f32_e32 vcc, 1.0, v26
	s_nop 1
	v_cndmask_b32_e32 v25, v25, v27, vcc
	v_bfi_b32 v22, s37, v23, v22
	v_mul_f32_e32 v14, 0.5, v14
	v_add_f32_e32 v22, 1.0, v22
	v_mul_f32_e32 v22, v14, v22
	v_bfi_b32 v14, s37, v21, v20
	v_mul_f32_e32 v13, 0.5, v13
	v_add_f32_e32 v14, 1.0, v14
	v_mul_f32_e32 v14, v13, v14
	v_bfi_b32 v13, s37, v19, v18
	v_readlane_b32 s6, v252, 33
	v_mul_f32_e32 v12, 0.5, v12
	v_add_f32_e32 v13, 1.0, v13
	v_readlane_b32 s7, v252, 34
	v_mul_f32_e32 v18, v12, v13
	v_mul_f32_e32 v15, 0.5, v15
	v_lshl_add_u64 v[12:13], s[6:7], 0, v[16:17]
	v_bfi_b32 v16, s37, v25, v24
	v_add_f32_e32 v16, 1.0, v16
	v_mul_f32_e32 v15, v15, v16
	v_lshl_add_u64 v[12:13], v[182:183], 1, v[12:13]
	v_cvt_pk_bf16_f32 v14, v18, v14
	v_cvt_pk_bf16_f32 v15, v22, v15
	global_store_dwordx2 v[12:13], v[14:15], off offset:-1952

; DI void st_bf4(u16* p, float a, float b, float c, float d) { *(uint2*)p = make_uint2(pk2(a, b), pk2(c, d)); }
; DI float gelu_f(float x) { return 0.5f * x * (1.f + erff(x * 0.70710678118654752f)); }
;   template <int NT, int MT> DI void run(f32x4 (&acc)[NT][MT], int mb, int nb) const {
;     ...
;         } else if (n < 3072) {
;           st_bf4(uvbuf + (size_t)m * 2048 + (n - 1024), gelu_f(v[0]), gelu_f(v[1]), gelu_f(v[2]), gelu_f(v[3]));
.LBB0_1666:
	s_andn2_saveexec_b64 s[48:49], s[48:49]
	s_cbranch_execz .LBB0_1684
	v_mul_f32_e32 v14, 0x3f3504f3, v8
	v_and_b32_e32 v16, 0x7fffffff, v14
	v_fmamk_f32 v17, v16, 0x378e98ab, v222
	v_fmaak_f32 v17, v16, v17, 0x3b7cd369
	v_fmaak_f32 v17, v16, v17, 0xbcc618b2
	v_fmaak_f32 v17, v16, v17, 0x3dda74e4
	v_fmaak_f32 v17, v16, v17, 0x3f228afd
	v_fmaak_f32 v17, v16, v17, 0x3e03c728
	v_fma_f32 v17, v16, v17, v16
	v_mul_f32_e32 v17, 0xbfb8aa3b, v17
	v_exp_f32_e32 v17, v17
	v_mul_f32_e32 v18, v14, v14
	v_sub_f32_e32 v17, 1.0, v17
	v_fmamk_f32 v15, v18, 0xba1345e1, v200
	v_fmaak_f32 v15, v18, v15, 0xbcdac9b8
	v_fmaak_f32 v15, v18, v15, 0x3de703be
	v_fmaak_f32 v15, v18, v15, 0xbec09330
	v_fmaak_f32 v15, v18, v15, 0x3e0375d0
	v_fma_f32 v15, v16, v15, v16
	v_cmp_ngt_f32_e32 vcc, 1.0, v16
	s_nop 1
	v_cndmask_b32_e32 v15, v15, v17, vcc
	v_mul_f32_e32 v16, 0x3f3504f3, v9
	v_and_b32_e32 v18, 0x7fffffff, v16
	v_fmamk_f32 v19, v18, 0x378e98ab, v222
	v_fmaak_f32 v19, v18, v19, 0x3b7cd369
	v_fmaak_f32 v19, v18, v19, 0xbcc618b2
	v_fmaak_f32 v19, v18, v19, 0x3dda74e4
	v_fmaak_f32 v19, v18, v19, 0x3f228afd
	v_fmaak_f32 v19, v18, v19, 0x3e03c728
	v_fma_f32 v19, v18, v19, v18
	v_mul_f32_e32 v19, 0xbfb8aa3b, v19
	v_exp_f32_e32 v19, v19
	v_mul_f32_e32 v20, v16, v16
	v_sub_f32_e32 v19, 1.0, v19
	v_fmamk_f32 v17, v20, 0xba1345e1, v200
	v_fmaak_f32 v17, v20, v17, 0xbcdac9b8
	v_fmaak_f32 v17, v20, v17, 0x3de703be
	v_fmaak_f32 v17, v20, v17, 0xbec09330
	v_fmaak_f32 v17, v20, v17, 0x3e0375d0
	v_fma_f32 v17, v18, v17, v18
	v_cmp_ngt_f32_e32 vcc, 1.0, v18
	s_nop 1
	v_cndmask_b32_e32 v17, v17, v19, vcc
	v_mul_f32_e32 v18, 0x3f3504f3, v10
	v_and_b32_e32 v20, 0x7fffffff, v18
	v_fmamk_f32 v21, v20, 0x378e98ab, v222
	v_fmaak_f32 v21, v20, v21, 0x3b7cd369
	v_fmaak_f32 v21, v20, v21, 0xbcc618b2
	v_fmaak_f32 v21, v20, v21, 0x3dda74e4
	v_fmaak_f32 v21, v20, v21, 0x3f228afd
	v_fmaak_f32 v21, v20, v21, 0x3e03c728
	v_fma_f32 v21, v20, v21, v20
	v_mul_f32_e32 v21, 0xbfb8aa3b, v21
	v_exp_f32_e32 v21, v21
	v_mul_f32_e32 v22, v18, v18
	v_sub_f32_e32 v21, 1.0, v21
	v_fmamk_f32 v19, v22, 0xba1345e1, v200
	v_fmaak_f32 v19, v22, v19, 0xbcdac9b8
	v_fmaak_f32 v19, v22, v19, 0x3de703be
	v_fmaak_f32 v19, v22, v19, 0xbec09330
	v_fmaak_f32 v19, v22, v19, 0x3e0375d0
	v_fma_f32 v19, v20, v19, v20
	v_cmp_ngt_f32_e32 vcc, 1.0, v20
	s_nop 1
	v_cndmask_b32_e32 v19, v19, v21, vcc
	v_mul_f32_e32 v20, 0x3f3504f3, v11
	v_and_b32_e32 v22, 0x7fffffff, v20
	v_fmamk_f32 v23, v22, 0x378e98ab, v222
	v_fmaak_f32 v23, v22, v23, 0x3b7cd369
	v_fmaak_f32 v23, v22, v23, 0xbcc618b2
	v_fmaak_f32 v23, v22, v23, 0x3dda74e4
	v_fmaak_f32 v23, v22, v23, 0x3f228afd
	v_fmaak_f32 v23, v22, v23, 0x3e03c728
	v_fma_f32 v23, v22, v23, v22
	v_mul_f32_e32 v23, 0xbfb8aa3b, v23
	v_exp_f32_e32 v23, v23
	v_mul_f32_e32 v24, v20, v20
	v_sub_f32_e32 v23, 1.0, v23
	v_fmamk_f32 v21, v24, 0xba1345e1, v200
	v_fmaak_f32 v21, v24, v21, 0xbcdac9b8
	v_fmaak_f32 v21, v24, v21, 0x3de703be
	v_fmaak_f32 v21, v24, v21, 0xbec09330
	v_fmaak_f32 v21, v24, v21, 0x3e0375d0
	v_fma_f32 v21, v22, v21, v22
	v_cmp_ngt_f32_e32 vcc, 1.0, v22
	s_nop 1
	v_cndmask_b32_e32 v21, v21, v23, vcc
	v_bfi_b32 v18, s37, v19, v18
	v_mul_f32_e32 v10, 0.5, v10
	v_add_f32_e32 v18, 1.0, v18
	v_mul_f32_e32 v18, v10, v18
	v_bfi_b32 v10, s37, v17, v16
	v_mul_f32_e32 v9, 0.5, v9
	v_add_f32_e32 v10, 1.0, v10
	v_mul_f32_e32 v10, v9, v10
	v_bfi_b32 v9, s37, v15, v14
	v_readlane_b32 s6, v252, 33
	v_mul_f32_e32 v8, 0.5, v8
	v_add_f32_e32 v9, 1.0, v9
	v_readlane_b32 s7, v252, 34
	v_mul_f32_e32 v14, v8, v9
	v_mul_f32_e32 v11, 0.5, v11
	v_lshl_add_u64 v[8:9], s[6:7], 0, v[12:13]
	v_bfi_b32 v12, s37, v21, v20
	v_add_f32_e32 v12, 1.0, v12
	v_mul_f32_e32 v11, v11, v12
	v_lshl_add_u64 v[8:9], v[182:183], 1, v[8:9]
	v_cvt_pk_bf16_f32 v10, v14, v10
	v_cvt_pk_bf16_f32 v11, v18, v11
	global_store_dwordx2 v[8:9], v[10:11], off offset:-1952

; DI void st_bf4(u16* p, float a, float b, float c, float d) { *(uint2*)p = make_uint2(pk2(a, b), pk2(c, d)); }
; DI float gelu_f(float x) { return 0.5f * x * (1.f + erff(x * 0.70710678118654752f)); }
;   template <int NT, int MT> DI void run(f32x4 (&acc)[NT][MT], int mb, int nb) const {
;     ...
;         } else if (n < 3072) {
;           st_bf4(uvbuf + (size_t)m * 2048 + (n - 1024), gelu_f(v[0]), gelu_f(v[1]), gelu_f(v[2]), gelu_f(v[3]));
.LBB0_1696:
	s_andn2_saveexec_b64 s[48:49], s[48:49]
	s_cbranch_execz .LBB0_1714
	v_mul_f32_e32 v10, 0x3f3504f3, v4
	v_and_b32_e32 v12, 0x7fffffff, v10
	v_fmamk_f32 v13, v12, 0x378e98ab, v222
	v_fmaak_f32 v13, v12, v13, 0x3b7cd369
	v_fmaak_f32 v13, v12, v13, 0xbcc618b2
	v_fmaak_f32 v13, v12, v13, 0x3dda74e4
	v_fmaak_f32 v13, v12, v13, 0x3f228afd
	v_fmaak_f32 v13, v12, v13, 0x3e03c728
	v_fma_f32 v13, v12, v13, v12
	v_mul_f32_e32 v13, 0xbfb8aa3b, v13
	v_exp_f32_e32 v13, v13
	v_mul_f32_e32 v14, v10, v10
	v_sub_f32_e32 v13, 1.0, v13
	v_fmamk_f32 v11, v14, 0xba1345e1, v200
	v_fmaak_f32 v11, v14, v11, 0xbcdac9b8
	v_fmaak_f32 v11, v14, v11, 0x3de703be
	v_fmaak_f32 v11, v14, v11, 0xbec09330
	v_fmaak_f32 v11, v14, v11, 0x3e0375d0
	v_fma_f32 v11, v12, v11, v12
	v_cmp_ngt_f32_e32 vcc, 1.0, v12
	s_nop 1
	v_cndmask_b32_e32 v11, v11, v13, vcc
	v_mul_f32_e32 v12, 0x3f3504f3, v5
	v_and_b32_e32 v14, 0x7fffffff, v12
	v_fmamk_f32 v15, v14, 0x378e98ab, v222
	v_fmaak_f32 v15, v14, v15, 0x3b7cd369
	v_fmaak_f32 v15, v14, v15, 0xbcc618b2
	v_fmaak_f32 v15, v14, v15, 0x3dda74e4
	v_fmaak_f32 v15, v14, v15, 0x3f228afd
	v_fmaak_f32 v15, v14, v15, 0x3e03c728
	v_fma_f32 v15, v14, v15, v14
	v_mul_f32_e32 v15, 0xbfb8aa3b, v15
	v_exp_f32_e32 v15, v15
	v_mul_f32_e32 v16, v12, v12
	v_sub_f32_e32 v15, 1.0, v15
	v_fmamk_f32 v13, v16, 0xba1345e1, v200
	v_fmaak_f32 v13, v16, v13, 0xbcdac9b8
	v_fmaak_f32 v13, v16, v13, 0x3de703be
	v_fmaak_f32 v13, v16, v13, 0xbec09330
	v_fmaak_f32 v13, v16, v13, 0x3e0375d0
	v_fma_f32 v13, v14, v13, v14
	v_cmp_ngt_f32_e32 vcc, 1.0, v14
	s_nop 1
	v_cndmask_b32_e32 v13, v13, v15, vcc
	v_mul_f32_e32 v14, 0x3f3504f3, v6
	v_and_b32_e32 v16, 0x7fffffff, v14
	v_fmamk_f32 v17, v16, 0x378e98ab, v222
	v_fmaak_f32 v17, v16, v17, 0x3b7cd369
	v_fmaak_f32 v17, v16, v17, 0xbcc618b2
	v_fmaak_f32 v17, v16, v17, 0x3dda74e4
	v_fmaak_f32 v17, v16, v17, 0x3f228afd
	v_fmaak_f32 v17, v16, v17, 0x3e03c728
	v_fma_f32 v17, v16, v17, v16
	v_mul_f32_e32 v17, 0xbfb8aa3b, v17
	v_exp_f32_e32 v17, v17
	v_mul_f32_e32 v18, v14, v14
	v_sub_f32_e32 v17, 1.0, v17
	v_fmamk_f32 v15, v18, 0xba1345e1, v200
	v_fmaak_f32 v15, v18, v15, 0xbcdac9b8
	v_fmaak_f32 v15, v18, v15, 0x3de703be
	v_fmaak_f32 v15, v18, v15, 0xbec09330
	v_fmaak_f32 v15, v18, v15, 0x3e0375d0
	v_fma_f32 v15, v16, v15, v16
	v_cmp_ngt_f32_e32 vcc, 1.0, v16
	s_nop 1
	v_cndmask_b32_e32 v15, v15, v17, vcc
	v_mul_f32_e32 v16, 0x3f3504f3, v7
	v_and_b32_e32 v18, 0x7fffffff, v16
	v_fmamk_f32 v19, v18, 0x378e98ab, v222
	v_fmaak_f32 v19, v18, v19, 0x3b7cd369
	v_fmaak_f32 v19, v18, v19, 0xbcc618b2
	v_fmaak_f32 v19, v18, v19, 0x3dda74e4
	v_fmaak_f32 v19, v18, v19, 0x3f228afd
	v_fmaak_f32 v19, v18, v19, 0x3e03c728
	v_fma_f32 v19, v18, v19, v18
	v_mul_f32_e32 v19, 0xbfb8aa3b, v19
	v_exp_f32_e32 v19, v19
	v_mul_f32_e32 v20, v16, v16
	v_sub_f32_e32 v19, 1.0, v19
	v_fmamk_f32 v17, v20, 0xba1345e1, v200
	v_fmaak_f32 v17, v20, v17, 0xbcdac9b8
	v_fmaak_f32 v17, v20, v17, 0x3de703be
	v_fmaak_f32 v17, v20, v17, 0xbec09330
	v_fmaak_f32 v17, v20, v17, 0x3e0375d0
	v_fma_f32 v17, v18, v17, v18
	v_cmp_ngt_f32_e32 vcc, 1.0, v18
	s_nop 1
	v_cndmask_b32_e32 v17, v17, v19, vcc
	v_bfi_b32 v14, s37, v15, v14
	v_mul_f32_e32 v6, 0.5, v6
	v_add_f32_e32 v14, 1.0, v14
	v_mul_f32_e32 v14, v6, v14
	v_bfi_b32 v6, s37, v13, v12
	v_mul_f32_e32 v5, 0.5, v5
	v_add_f32_e32 v6, 1.0, v6
	v_mul_f32_e32 v6, v5, v6
	v_bfi_b32 v5, s37, v11, v10
	v_readlane_b32 s6, v252, 33
	v_mul_f32_e32 v4, 0.5, v4
	v_add_f32_e32 v5, 1.0, v5
	v_readlane_b32 s7, v252, 34
	v_mul_f32_e32 v10, v4, v5
	v_mul_f32_e32 v7, 0.5, v7
	v_lshl_add_u64 v[4:5], s[6:7], 0, v[8:9]
	v_bfi_b32 v8, s37, v17, v16
	v_add_f32_e32 v8, 1.0, v8
	v_mul_f32_e32 v7, v7, v8
	v_lshl_add_u64 v[4:5], v[182:183], 1, v[4:5]
	v_cvt_pk_bf16_f32 v6, v10, v6
	v_cvt_pk_bf16_f32 v7, v14, v7
	global_store_dwordx2 v[4:5], v[6:7], off offset:-1952

; DI void st_bf4(u16* p, float a, float b, float c, float d) { *(uint2*)p = make_uint2(pk2(a, b), pk2(c, d)); }
; DI float gelu_f(float x) { return 0.5f * x * (1.f + erff(x * 0.70710678118654752f)); }
;   template <int NT, int MT> DI void run(f32x4 (&acc)[NT][MT], int mb, int nb) const {
;     ...
;         } else if (n < 3072) {
;           st_bf4(uvbuf + (size_t)m * 2048 + (n - 1024), gelu_f(v[0]), gelu_f(v[1]), gelu_f(v[2]), gelu_f(v[3]));
.LBB0_1720:
	s_andn2_saveexec_b64 s[38:39], s[38:39]
	s_cbranch_execz .LBB0_1738
	v_mul_f32_e32 v6, 0x3f3504f3, v0
	v_and_b32_e32 v8, 0x7fffffff, v6
	v_fmamk_f32 v9, v8, 0x378e98ab, v222
	v_fmaak_f32 v9, v8, v9, 0x3b7cd369
	v_fmaak_f32 v9, v8, v9, 0xbcc618b2
	v_fmaak_f32 v9, v8, v9, 0x3dda74e4
	v_fmaak_f32 v9, v8, v9, 0x3f228afd
	v_fmaak_f32 v9, v8, v9, 0x3e03c728
	v_fma_f32 v9, v8, v9, v8
	v_mul_f32_e32 v9, 0xbfb8aa3b, v9
	v_exp_f32_e32 v9, v9
	v_mul_f32_e32 v10, v6, v6
	v_sub_f32_e32 v9, 1.0, v9
	v_fmamk_f32 v7, v10, 0xba1345e1, v200
	v_fmaak_f32 v7, v10, v7, 0xbcdac9b8
	v_fmaak_f32 v7, v10, v7, 0x3de703be
	v_fmaak_f32 v7, v10, v7, 0xbec09330
	v_fmaak_f32 v7, v10, v7, 0x3e0375d0
	v_fma_f32 v7, v8, v7, v8
	v_cmp_ngt_f32_e32 vcc, 1.0, v8
	s_nop 1
	v_cndmask_b32_e32 v7, v7, v9, vcc
	v_mul_f32_e32 v8, 0x3f3504f3, v1
	v_and_b32_e32 v10, 0x7fffffff, v8
	v_fmamk_f32 v11, v10, 0x378e98ab, v222
	v_fmaak_f32 v11, v10, v11, 0x3b7cd369
	v_fmaak_f32 v11, v10, v11, 0xbcc618b2
	v_fmaak_f32 v11, v10, v11, 0x3dda74e4
	v_fmaak_f32 v11, v10, v11, 0x3f228afd
	v_fmaak_f32 v11, v10, v11, 0x3e03c728
	v_fma_f32 v11, v10, v11, v10
	v_mul_f32_e32 v11, 0xbfb8aa3b, v11
	v_exp_f32_e32 v11, v11
	v_mul_f32_e32 v12, v8, v8
	v_sub_f32_e32 v11, 1.0, v11
	v_fmamk_f32 v9, v12, 0xba1345e1, v200
	v_fmaak_f32 v9, v12, v9, 0xbcdac9b8
	v_fmaak_f32 v9, v12, v9, 0x3de703be
	v_fmaak_f32 v9, v12, v9, 0xbec09330
	v_fmaak_f32 v9, v12, v9, 0x3e0375d0
	v_fma_f32 v9, v10, v9, v10
	v_cmp_ngt_f32_e32 vcc, 1.0, v10
	s_nop 1
	v_cndmask_b32_e32 v9, v9, v11, vcc
	v_mul_f32_e32 v10, 0x3f3504f3, v2
	v_and_b32_e32 v12, 0x7fffffff, v10
	v_fmamk_f32 v13, v12, 0x378e98ab, v222
	v_fmaak_f32 v13, v12, v13, 0x3b7cd369
	v_fmaak_f32 v13, v12, v13, 0xbcc618b2
	v_fmaak_f32 v13, v12, v13, 0x3dda74e4
	v_fmaak_f32 v13, v12, v13, 0x3f228afd
	v_fmaak_f32 v13, v12, v13, 0x3e03c728
	v_fma_f32 v13, v12, v13, v12
	v_mul_f32_e32 v13, 0xbfb8aa3b, v13
	v_exp_f32_e32 v13, v13
	v_mul_f32_e32 v14, v10, v10
	v_sub_f32_e32 v13, 1.0, v13
	v_fmamk_f32 v11, v14, 0xba1345e1, v200
	v_fmaak_f32 v11, v14, v11, 0xbcdac9b8
	v_fmaak_f32 v11, v14, v11, 0x3de703be
	v_fmaak_f32 v11, v14, v11, 0xbec09330
	v_fmaak_f32 v11, v14, v11, 0x3e0375d0
	v_fma_f32 v11, v12, v11, v12
	v_cmp_ngt_f32_e32 vcc, 1.0, v12
	s_nop 1
	v_cndmask_b32_e32 v11, v11, v13, vcc
	v_mul_f32_e32 v12, 0x3f3504f3, v3
	v_and_b32_e32 v14, 0x7fffffff, v12
	v_fmamk_f32 v15, v14, 0x378e98ab, v222
	v_fmaak_f32 v15, v14, v15, 0x3b7cd369
	v_fmaak_f32 v15, v14, v15, 0xbcc618b2
	v_fmaak_f32 v15, v14, v15, 0x3dda74e4
	v_fmaak_f32 v15, v14, v15, 0x3f228afd
	v_fmaak_f32 v15, v14, v15, 0x3e03c728
	v_fma_f32 v15, v14, v15, v14
	v_mul_f32_e32 v15, 0xbfb8aa3b, v15
	v_exp_f32_e32 v15, v15
	v_mul_f32_e32 v16, v12, v12
	v_sub_f32_e32 v15, 1.0, v15
	v_fmamk_f32 v13, v16, 0xba1345e1, v200
	v_fmaak_f32 v13, v16, v13, 0xbcdac9b8
	v_fmaak_f32 v13, v16, v13, 0x3de703be
	v_fmaak_f32 v13, v16, v13, 0xbec09330
	v_fmaak_f32 v13, v16, v13, 0x3e0375d0
	v_fma_f32 v13, v14, v13, v14
	v_cmp_ngt_f32_e32 vcc, 1.0, v14
	s_nop 1
	v_cndmask_b32_e32 v13, v13, v15, vcc
	v_bfi_b32 v10, s37, v11, v10
	v_mul_f32_e32 v2, 0.5, v2
	v_add_f32_e32 v10, 1.0, v10
	v_mul_f32_e32 v10, v2, v10
	v_bfi_b32 v2, s37, v9, v8
	v_mul_f32_e32 v1, 0.5, v1
	v_add_f32_e32 v2, 1.0, v2
	v_mul_f32_e32 v2, v1, v2
	v_bfi_b32 v1, s37, v7, v6
	v_readlane_b32 s6, v252, 33
	v_mul_f32_e32 v0, 0.5, v0
	v_add_f32_e32 v1, 1.0, v1
	v_readlane_b32 s7, v252, 34
	v_mul_f32_e32 v6, v0, v1
	v_mul_f32_e32 v3, 0.5, v3
	v_lshl_add_u64 v[0:1], s[6:7], 0, v[4:5]
	v_bfi_b32 v4, s37, v13, v12
	v_add_f32_e32 v4, 1.0, v4
	v_mul_f32_e32 v3, v3, v4
	v_lshl_add_u64 v[0:1], v[182:183], 1, v[0:1]
	v_cvt_pk_bf16_f32 v2, v6, v2
	v_cvt_pk_bf16_f32 v3, v10, v3
	global_store_dwordx2 v[0:1], v[2:3], off offset:-1952
